# U and V unit loops: LDS reads of the next unit's row offsets issued before the record DMA setup (latency hidden behind scalar work)
# baseline (speedup 1.0000x reference)
; __device__ __forceinline__ float bflo(unsigned u) { return __uint_as_float(u << 16); }
; __device__ __forceinline__ float bfhi(unsigned u) { return __uint_as_float(u & 0xffff0000u); }
; #define P5_LOAD(A, TAB, j0)                                                                \
;   _Pragma("unroll") for (int q = 0; q < 16; q++) {                                         \
;     A[q] = ((const uint4*)((TAB) + (size_t)widx[(j0) + q] * 1024))[lane];                  \
;   }
; __device__ __forceinline__ void phase5(const Params& p, char* smem, const bool store_x = true) {
;     ...
;     float2v h2[8];
;     {
;       const uint4 a = cur_ha;
;       const uint4 b2 = cur_hb;
;       h2[0] = float2v{bflo(a.x), bfhi(a.x)}; h2[1] = float2v{bflo(a.y), bfhi(a.y)}; h2[2] = float2v{bflo(a.z), bfhi(a.z)}; h2[3] = float2v{bflo(a.w), bfhi(a.w)};
;       h2[4] = float2v{bflo(b2.x), bfhi(b2.x)}; h2[5] = float2v{bflo(b2.y), bfhi(b2.y)}; h2[6] = float2v{bflo(b2.z), bfhi(b2.z)}; h2[7] = float2v{bflo(b2.w), bfhi(b2.w)};
; #pragma unroll
;       for (int i = 0; i < 8; i++) h2[i] = h2[i] * gf[i] * cur_rs;
;     }
;     uint4 A0[16], A1[16];
;     P5_LOAD(A0, EU, 0)
; #pragma unroll 1
;     for (int j0 = 0; j0 < 128; j0 += 32) {
;       P5_LOAD(A1, EU, j0 + 16)
;       P5_COMPUTE_U(A0, j0)
;       if (j0 + 32 < 128) { P5_LOAD(A0, EU, j0 + 32) } else { P5_LOAD(A0, EV, 0) }
;       P5_COMPUTE_U(A1, j0 + 16)
.Lp5u_loop:
	s_add_u32 s11, s16, 2
	s_and_b32 s11, s11, 7
	s_lshl_b32 s11, s11, 10
	v_add_u32_e32 v8, s11, v2
	ds_read_b128 v[10:13], v8 offset:0
	ds_read_b128 v[14:17], v8 offset:16
	ds_read_b128 v[18:21], v8 offset:32
	ds_read_b128 v[22:25], v8 offset:48
	s_add_u32 s10, s8, s25
	s_min_u32 s10, s10, s13
	s_lshl_b32 s18, s10, 10
	s_add_u32 s11, s16, 6
	s_and_b32 s11, s11, 7
	s_lshl_b32 s11, s11, 10
	s_add_u32 s11, s11, s17
	s_mov_b32 m0, s11
	v_lshl_add_u64 v[4:5], v[58:59], 0, s[18:19]
	global_load_lds_dwordx4 v[4:5], off
	s_add_u32 s10, s8, s21
	s_min_u32 s10, s10, s13
	s_lshl_b32 s11, s10, 11
	v_add_u32_e32 v6, s11, v7
	global_load_dwordx4 a[32:35], v6, s[36:37]
	global_load_dwordx4 a[36:39], v6, s[36:37] offset:16
	s_lshl_b32 s11, s10, 2
	v_mov_b32_e32 v6, s11
	global_load_dword a40, v6, s[38:39]
	s_waitcnt lgkmcnt(0)
	v_add_u32_e32 v10, v10, v1
	global_load_dwordx4 v[188:191], v10, s[2:3]
	v_add_u32_e32 v11, v11, v1
	global_load_dwordx4 v[192:195], v11, s[2:3]
	v_add_u32_e32 v12, v12, v1
	global_load_dwordx4 v[196:199], v12, s[2:3]
	v_add_u32_e32 v13, v13, v1
	global_load_dwordx4 v[200:203], v13, s[2:3]
	v_add_u32_e32 v14, v14, v1
	global_load_dwordx4 v[204:207], v14, s[2:3]
	v_add_u32_e32 v15, v15, v1
	global_load_dwordx4 v[208:211], v15, s[2:3]
	v_add_u32_e32 v16, v16, v1
	global_load_dwordx4 v[212:215], v16, s[2:3]
	v_add_u32_e32 v17, v17, v1
	global_load_dwordx4 v[216:219], v17, s[2:3]
	v_add_u32_e32 v18, v18, v1
	global_load_dwordx4 v[220:223], v18, s[2:3]
	v_add_u32_e32 v19, v19, v1
	global_load_dwordx4 v[224:227], v19, s[2:3]
	v_add_u32_e32 v20, v20, v1
	global_load_dwordx4 v[228:231], v20, s[2:3]
	v_add_u32_e32 v21, v21, v1
	global_load_dwordx4 v[232:235], v21, s[2:3]
	v_add_u32_e32 v22, v22, v1
	global_load_dwordx4 v[236:239], v22, s[2:3]
	v_add_u32_e32 v23, v23, v1
	global_load_dwordx4 v[240:243], v23, s[2:3]
	v_add_u32_e32 v24, v24, v1
	global_load_dwordx4 v[244:247], v24, s[2:3]
	v_add_u32_e32 v25, v25, v1
	global_load_dwordx4 v[248:251], v25, s[2:3]
	s_mov_b32 s12, s8
	s_waitcnt vmcnt(42)
	s_cmp_lt_u32 s12, 0x4200
	s_cbranch_scc0 .Lp5u_skip0
	v_accvgpr_read_b32 v56, a8
	v_fmamk_f32 v56, v56, 0x3a800000, v57
	v_mul_f32_e32 v9, 0x4b800000, v56
	v_cmp_gt_f32_e32 vcc, s33, v56
	s_nop 1
	v_cndmask_b32_e32 v56, v56, v9, vcc
	v_rsq_f32_e32 v56, v56
	s_nop 0
	v_mul_f32_e32 v9, 0x45800000, v56
	v_cndmask_b32_e32 v56, v56, v9, vcc
	v_accvgpr_read_b32 v9, a0
	v_accvgpr_read_b32 v54, a48
	v_accvgpr_read_b32 v55, a49
	v_lshlrev_b32_e32 v10, 16, v9
	v_and_b32_e32 v11, 0xffff0000, v9
	v_pk_mul_f32 v[10:11], v[10:11], v[54:55]
	v_accvgpr_read_b32 v9, a1
	v_accvgpr_read_b32 v54, a50
	v_accvgpr_read_b32 v55, a51
	v_lshlrev_b32_e32 v12, 16, v9
	v_and_b32_e32 v13, 0xffff0000, v9
	v_pk_mul_f32 v[12:13], v[12:13], v[54:55]
	v_accvgpr_read_b32 v9, a2
	v_accvgpr_read_b32 v54, a52
	v_accvgpr_read_b32 v55, a53
	v_lshlrev_b32_e32 v14, 16, v9
	v_and_b32_e32 v15, 0xffff0000, v9
	v_pk_mul_f32 v[14:15], v[14:15], v[54:55]
	v_accvgpr_read_b32 v9, a3
	v_accvgpr_read_b32 v54, a54
	v_accvgpr_read_b32 v55, a55
	v_lshlrev_b32_e32 v16, 16, v9
	v_and_b32_e32 v17, 0xffff0000, v9
	v_pk_mul_f32 v[16:17], v[16:17], v[54:55]
	v_accvgpr_read_b32 v9, a4
	v_accvgpr_read_b32 v54, a56
	v_accvgpr_read_b32 v55, a57
	v_lshlrev_b32_e32 v18, 16, v9
	v_and_b32_e32 v19, 0xffff0000, v9
	v_pk_mul_f32 v[18:19], v[18:19], v[54:55]
	v_accvgpr_read_b32 v9, a5
	v_accvgpr_read_b32 v54, a58
	v_accvgpr_read_b32 v55, a59
	v_lshlrev_b32_e32 v20, 16, v9
	v_and_b32_e32 v21, 0xffff0000, v9
	v_pk_mul_f32 v[20:21], v[20:21], v[54:55]
	v_accvgpr_read_b32 v9, a6
	v_accvgpr_read_b32 v54, a60
	v_accvgpr_read_b32 v55, a61
	v_lshlrev_b32_e32 v22, 16, v9
	v_and_b32_e32 v23, 0xffff0000, v9
	v_pk_mul_f32 v[22:23], v[22:23], v[54:55]
	v_accvgpr_read_b32 v9, a7
	v_accvgpr_read_b32 v54, a62
	v_accvgpr_read_b32 v55, a63
	v_lshlrev_b32_e32 v24, 16, v9
	v_and_b32_e32 v25, 0xffff0000, v9
	v_pk_mul_f32 v[24:25], v[24:25], v[54:55]
	v_cvt_pk_f32_fp8_e32 v[42:43], v60
	v_cvt_pk_f32_fp8_sdwa v[44:45], v60 src0_sel:WORD_1
	v_cvt_pk_f32_fp8_e32 v[46:47], v64
	v_cvt_pk_f32_fp8_sdwa v[48:49], v64 src0_sel:WORD_1
	v_pk_mul_f32 v[50:51], v[42:43], v[10:11]
	v_pk_mul_f32 v[52:53], v[46:47], v[10:11]
	v_pk_fma_f32 v[50:51], v[44:45], v[12:13], v[50:51]
	v_pk_fma_f32 v[52:53], v[48:49], v[12:13], v[52:53]
	v_cvt_pk_f32_fp8_e32 v[42:43], v61
	v_cvt_pk_f32_fp8_sdwa v[44:45], v61 src0_sel:WORD_1
	v_cvt_pk_f32_fp8_e32 v[46:47], v65
	v_cvt_pk_f32_fp8_sdwa v[48:49], v65 src0_sel:WORD_1
	v_pk_fma_f32 v[50:51], v[42:43], v[14:15], v[50:51]
	v_pk_fma_f32 v[52:53], v[46:47], v[14:15], v[52:53]
	v_pk_fma_f32 v[50:51], v[44:45], v[16:17], v[50:51]
	v_pk_fma_f32 v[52:53], v[48:49], v[16:17], v[52:53]
	v_cvt_pk_f32_fp8_e32 v[42:43], v62
	v_cvt_pk_f32_fp8_sdwa v[44:45], v62 src0_sel:WORD_1
	v_cvt_pk_f32_fp8_e32 v[46:47], v66
	v_cvt_pk_f32_fp8_sdwa v[48:49], v66 src0_sel:WORD_1
	v_pk_fma_f32 v[50:51], v[42:43], v[18:19], v[50:51]
	v_pk_fma_f32 v[52:53], v[46:47], v[18:19], v[52:53]
	v_pk_fma_f32 v[50:51], v[44:45], v[20:21], v[50:51]
	v_pk_fma_f32 v[52:53], v[48:49], v[20:21], v[52:53]
	v_cvt_pk_f32_fp8_e32 v[42:43], v63
	v_cvt_pk_f32_fp8_sdwa v[44:45], v63 src0_sel:WORD_1
	v_cvt_pk_f32_fp8_e32 v[46:47], v67
	v_cvt_pk_f32_fp8_sdwa v[48:49], v67 src0_sel:WORD_1
	v_pk_fma_f32 v[50:51], v[42:43], v[22:23], v[50:51]
	v_pk_fma_f32 v[52:53], v[46:47], v[22:23], v[52:53]
	v_pk_fma_f32 v[50:51], v[44:45], v[24:25], v[50:51]
	v_pk_fma_f32 v[52:53], v[48:49], v[24:25], v[52:53]
	v_add_f32_e32 v26, v50, v51
	v_add_f32_e32 v27, v52, v53
	v_cvt_pk_f32_fp8_e32 v[42:43], v68
	v_cvt_pk_f32_fp8_sdwa v[44:45], v68 src0_sel:WORD_1
	v_cvt_pk_f32_fp8_e32 v[46:47], v72
	v_cvt_pk_f32_fp8_sdwa v[48:49], v72 src0_sel:WORD_1
	v_pk_mul_f32 v[50:51], v[42:43], v[10:11]
	v_pk_mul_f32 v[52:53], v[46:47], v[10:11]
	v_pk_fma_f32 v[50:51], v[44:45], v[12:13], v[50:51]
	v_pk_fma_f32 v[52:53], v[48:49], v[12:13], v[52:53]
	v_cvt_pk_f32_fp8_e32 v[42:43], v69
	v_cvt_pk_f32_fp8_sdwa v[44:45], v69 src0_sel:WORD_1
	v_cvt_pk_f32_fp8_e32 v[46:47], v73
	v_cvt_pk_f32_fp8_sdwa v[48:49], v73 src0_sel:WORD_1
	v_pk_fma_f32 v[50:51], v[42:43], v[14:15], v[50:51]
	v_pk_fma_f32 v[52:53], v[46:47], v[14:15], v[52:53]
	v_pk_fma_f32 v[50:51], v[44:45], v[16:17], v[50:51]
	v_pk_fma_f32 v[52:53], v[48:49], v[16:17], v[52:53]
	v_cvt_pk_f32_fp8_e32 v[42:43], v70
	v_cvt_pk_f32_fp8_sdwa v[44:45], v70 src0_sel:WORD_1
	v_cvt_pk_f32_fp8_e32 v[46:47], v74
	v_cvt_pk_f32_fp8_sdwa v[48:49], v74 src0_sel:WORD_1
	v_pk_fma_f32 v[50:51], v[42:43], v[18:19], v[50:51]
	v_pk_fma_f32 v[52:53], v[46:47], v[18:19], v[52:53]
	v_pk_fma_f32 v[50:51], v[44:45], v[20:21], v[50:51]
	v_pk_fma_f32 v[52:53], v[48:49], v[20:21], v[52:53]
	v_cvt_pk_f32_fp8_e32 v[42:43], v71
	v_cvt_pk_f32_fp8_sdwa v[44:45], v71 src0_sel:WORD_1
	v_cvt_pk_f32_fp8_e32 v[46:47], v75
	v_cvt_pk_f32_fp8_sdwa v[48:49], v75 src0_sel:WORD_1
	v_pk_fma_f32 v[50:51], v[42:43], v[22:23], v[50:51]
	v_pk_fma_f32 v[52:53], v[46:47], v[22:23], v[52:53]
	v_pk_fma_f32 v[50:51], v[44:45], v[24:25], v[50:51]
	v_pk_fma_f32 v[52:53], v[48:49], v[24:25], v[52:53]
	v_add_f32_e32 v28, v50, v51
	v_add_f32_e32 v29, v52, v53
	v_cvt_pk_f32_fp8_e32 v[42:43], v76
	v_cvt_pk_f32_fp8_sdwa v[44:45], v76 src0_sel:WORD_1
	v_cvt_pk_f32_fp8_e32 v[46:47], v80
	v_cvt_pk_f32_fp8_sdwa v[48:49], v80 src0_sel:WORD_1
	v_pk_mul_f32 v[50:51], v[42:43], v[10:11]
	v_pk_mul_f32 v[52:53], v[46:47], v[10:11]
	v_pk_fma_f32 v[50:51], v[44:45], v[12:13], v[50:51]
	v_pk_fma_f32 v[52:53], v[48:49], v[12:13], v[52:53]
	v_cvt_pk_f32_fp8_e32 v[42:43], v77
	v_cvt_pk_f32_fp8_sdwa v[44:45], v77 src0_sel:WORD_1
	v_cvt_pk_f32_fp8_e32 v[46:47], v81
	v_cvt_pk_f32_fp8_sdwa v[48:49], v81 src0_sel:WORD_1
	v_pk_fma_f32 v[50:51], v[42:43], v[14:15], v[50:51]
	v_pk_fma_f32 v[52:53], v[46:47], v[14:15], v[52:53]
	v_pk_fma_f32 v[50:51], v[44:45], v[16:17], v[50:51]
	v_pk_fma_f32 v[52:53], v[48:49], v[16:17], v[52:53]
	v_cvt_pk_f32_fp8_e32 v[42:43], v78
	v_cvt_pk_f32_fp8_sdwa v[44:45], v78 src0_sel:WORD_1
	v_cvt_pk_f32_fp8_e32 v[46:47], v82
	v_cvt_pk_f32_fp8_sdwa v[48:49], v82 src0_sel:WORD_1
	v_pk_fma_f32 v[50:51], v[42:43], v[18:19], v[50:51]
	v_pk_fma_f32 v[52:53], v[46:47], v[18:19], v[52:53]
	v_pk_fma_f32 v[50:51], v[44:45], v[20:21], v[50:51]
	v_pk_fma_f32 v[52:53], v[48:49], v[20:21], v[52:53]
	v_cvt_pk_f32_fp8_e32 v[42:43], v79
	v_cvt_pk_f32_fp8_sdwa v[44:45], v79 src0_sel:WORD_1
	v_cvt_pk_f32_fp8_e32 v[46:47], v83
	v_cvt_pk_f32_fp8_sdwa v[48:49], v83 src0_sel:WORD_1
	v_pk_fma_f32 v[50:51], v[42:43], v[22:23], v[50:51]
	v_pk_fma_f32 v[52:53], v[46:47], v[22:23], v[52:53]
	v_pk_fma_f32 v[50:51], v[44:45], v[24:25], v[50:51]
	v_pk_fma_f32 v[52:53], v[48:49], v[24:25], v[52:53]
	v_add_f32_e32 v30, v50, v51
	v_add_f32_e32 v31, v52, v53
	v_cvt_pk_f32_fp8_e32 v[42:43], v84
	v_cvt_pk_f32_fp8_sdwa v[44:45], v84 src0_sel:WORD_1
	v_cvt_pk_f32_fp8_e32 v[46:47], v88
	v_cvt_pk_f32_fp8_sdwa v[48:49], v88 src0_sel:WORD_1
	v_pk_mul_f32 v[50:51], v[42:43], v[10:11]
	v_pk_mul_f32 v[52:53], v[46:47], v[10:11]
	v_pk_fma_f32 v[50:51], v[44:45], v[12:13], v[50:51]
	v_pk_fma_f32 v[52:53], v[48:49], v[12:13], v[52:53]
	v_cvt_pk_f32_fp8_e32 v[42:43], v85
	v_cvt_pk_f32_fp8_sdwa v[44:45], v85 src0_sel:WORD_1
	v_cvt_pk_f32_fp8_e32 v[46:47], v89
	v_cvt_pk_f32_fp8_sdwa v[48:49], v89 src0_sel:WORD_1
	v_pk_fma_f32 v[50:51], v[42:43], v[14:15], v[50:51]
	v_pk_fma_f32 v[52:53], v[46:47], v[14:15], v[52:53]
	v_pk_fma_f32 v[50:51], v[44:45], v[16:17], v[50:51]
	v_pk_fma_f32 v[52:53], v[48:49], v[16:17], v[52:53]
	v_cvt_pk_f32_fp8_e32 v[42:43], v86
	v_cvt_pk_f32_fp8_sdwa v[44:45], v86 src0_sel:WORD_1
	v_cvt_pk_f32_fp8_e32 v[46:47], v90
	v_cvt_pk_f32_fp8_sdwa v[48:49], v90 src0_sel:WORD_1
	v_pk_fma_f32 v[50:51], v[42:43], v[18:19], v[50:51]
	v_pk_fma_f32 v[52:53], v[46:47], v[18:19], v[52:53]
	v_pk_fma_f32 v[50:51], v[44:45], v[20:21], v[50:51]
	v_pk_fma_f32 v[52:53], v[48:49], v[20:21], v[52:53]
	v_cvt_pk_f32_fp8_e32 v[42:43], v87
	v_cvt_pk_f32_fp8_sdwa v[44:45], v87 src0_sel:WORD_1
	v_cvt_pk_f32_fp8_e32 v[46:47], v91
	v_cvt_pk_f32_fp8_sdwa v[48:49], v91 src0_sel:WORD_1
	v_pk_fma_f32 v[50:51], v[42:43], v[22:23], v[50:51]
	v_pk_fma_f32 v[52:53], v[46:47], v[22:23], v[52:53]
	v_pk_fma_f32 v[50:51], v[44:45], v[24:25], v[50:51]
	v_pk_fma_f32 v[52:53], v[48:49], v[24:25], v[52:53]
	v_add_f32_e32 v32, v50, v51
	v_add_f32_e32 v33, v52, v53
	v_cvt_pk_f32_fp8_e32 v[42:43], v92
	v_cvt_pk_f32_fp8_sdwa v[44:45], v92 src0_sel:WORD_1
	v_cvt_pk_f32_fp8_e32 v[46:47], v96
	v_cvt_pk_f32_fp8_sdwa v[48:49], v96 src0_sel:WORD_1
	v_pk_mul_f32 v[50:51], v[42:43], v[10:11]
	v_pk_mul_f32 v[52:53], v[46:47], v[10:11]
	v_pk_fma_f32 v[50:51], v[44:45], v[12:13], v[50:51]
	v_pk_fma_f32 v[52:53], v[48:49], v[12:13], v[52:53]
	v_cvt_pk_f32_fp8_e32 v[42:43], v93
	v_cvt_pk_f32_fp8_sdwa v[44:45], v93 src0_sel:WORD_1
	v_cvt_pk_f32_fp8_e32 v[46:47], v97
	v_cvt_pk_f32_fp8_sdwa v[48:49], v97 src0_sel:WORD_1
	v_pk_fma_f32 v[50:51], v[42:43], v[14:15], v[50:51]
	v_pk_fma_f32 v[52:53], v[46:47], v[14:15], v[52:53]
	v_pk_fma_f32 v[50:51], v[44:45], v[16:17], v[50:51]
	v_pk_fma_f32 v[52:53], v[48:49], v[16:17], v[52:53]
	v_cvt_pk_f32_fp8_e32 v[42:43], v94
	v_cvt_pk_f32_fp8_sdwa v[44:45], v94 src0_sel:WORD_1
	v_cvt_pk_f32_fp8_e32 v[46:47], v98
	v_cvt_pk_f32_fp8_sdwa v[48:49], v98 src0_sel:WORD_1
	v_pk_fma_f32 v[50:51], v[42:43], v[18:19], v[50:51]
	v_pk_fma_f32 v[52:53], v[46:47], v[18:19], v[52:53]
	v_pk_fma_f32 v[50:51], v[44:45], v[20:21], v[50:51]
	v_pk_fma_f32 v[52:53], v[48:49], v[20:21], v[52:53]
	v_cvt_pk_f32_fp8_e32 v[42:43], v95
	v_cvt_pk_f32_fp8_sdwa v[44:45], v95 src0_sel:WORD_1
	v_cvt_pk_f32_fp8_e32 v[46:47], v99
	v_cvt_pk_f32_fp8_sdwa v[48:49], v99 src0_sel:WORD_1
	v_pk_fma_f32 v[50:51], v[42:43], v[22:23], v[50:51]
	v_pk_fma_f32 v[52:53], v[46:47], v[22:23], v[52:53]
	v_pk_fma_f32 v[50:51], v[44:45], v[24:25], v[50:51]
	v_pk_fma_f32 v[52:53], v[48:49], v[24:25], v[52:53]
	v_add_f32_e32 v34, v50, v51
	v_add_f32_e32 v35, v52, v53
	v_cvt_pk_f32_fp8_e32 v[42:43], v100
	v_cvt_pk_f32_fp8_sdwa v[44:45], v100 src0_sel:WORD_1
	v_cvt_pk_f32_fp8_e32 v[46:47], v104
	v_cvt_pk_f32_fp8_sdwa v[48:49], v104 src0_sel:WORD_1
	v_pk_mul_f32 v[50:51], v[42:43], v[10:11]
	v_pk_mul_f32 v[52:53], v[46:47], v[10:11]
	v_pk_fma_f32 v[50:51], v[44:45], v[12:13], v[50:51]
	v_pk_fma_f32 v[52:53], v[48:49], v[12:13], v[52:53]
	v_cvt_pk_f32_fp8_e32 v[42:43], v101
	v_cvt_pk_f32_fp8_sdwa v[44:45], v101 src0_sel:WORD_1
	v_cvt_pk_f32_fp8_e32 v[46:47], v105
	v_cvt_pk_f32_fp8_sdwa v[48:49], v105 src0_sel:WORD_1
	v_pk_fma_f32 v[50:51], v[42:43], v[14:15], v[50:51]
	v_pk_fma_f32 v[52:53], v[46:47], v[14:15], v[52:53]
	v_pk_fma_f32 v[50:51], v[44:45], v[16:17], v[50:51]
	v_pk_fma_f32 v[52:53], v[48:49], v[16:17], v[52:53]
	v_cvt_pk_f32_fp8_e32 v[42:43], v102
	v_cvt_pk_f32_fp8_sdwa v[44:45], v102 src0_sel:WORD_1
	v_cvt_pk_f32_fp8_e32 v[46:47], v106
	v_cvt_pk_f32_fp8_sdwa v[48:49], v106 src0_sel:WORD_1
	v_pk_fma_f32 v[50:51], v[42:43], v[18:19], v[50:51]
	v_pk_fma_f32 v[52:53], v[46:47], v[18:19], v[52:53]
	v_pk_fma_f32 v[50:51], v[44:45], v[20:21], v[50:51]
	v_pk_fma_f32 v[52:53], v[48:49], v[20:21], v[52:53]
	v_cvt_pk_f32_fp8_e32 v[42:43], v103
	v_cvt_pk_f32_fp8_sdwa v[44:45], v103 src0_sel:WORD_1
	v_cvt_pk_f32_fp8_e32 v[46:47], v107
	v_cvt_pk_f32_fp8_sdwa v[48:49], v107 src0_sel:WORD_1
	v_pk_fma_f32 v[50:51], v[42:43], v[22:23], v[50:51]
	v_pk_fma_f32 v[52:53], v[46:47], v[22:23], v[52:53]
	v_pk_fma_f32 v[50:51], v[44:45], v[24:25], v[50:51]
	v_pk_fma_f32 v[52:53], v[48:49], v[24:25], v[52:53]
	v_add_f32_e32 v36, v50, v51
	v_add_f32_e32 v37, v52, v53
	v_cvt_pk_f32_fp8_e32 v[42:43], v108
	v_cvt_pk_f32_fp8_sdwa v[44:45], v108 src0_sel:WORD_1
	v_cvt_pk_f32_fp8_e32 v[46:47], v112
	v_cvt_pk_f32_fp8_sdwa v[48:49], v112 src0_sel:WORD_1
	v_pk_mul_f32 v[50:51], v[42:43], v[10:11]
	v_pk_mul_f32 v[52:53], v[46:47], v[10:11]
	v_pk_fma_f32 v[50:51], v[44:45], v[12:13], v[50:51]
	v_pk_fma_f32 v[52:53], v[48:49], v[12:13], v[52:53]
	v_cvt_pk_f32_fp8_e32 v[42:43], v109
	v_cvt_pk_f32_fp8_sdwa v[44:45], v109 src0_sel:WORD_1
	v_cvt_pk_f32_fp8_e32 v[46:47], v113
	v_cvt_pk_f32_fp8_sdwa v[48:49], v113 src0_sel:WORD_1
	v_pk_fma_f32 v[50:51], v[42:43], v[14:15], v[50:51]
	v_pk_fma_f32 v[52:53], v[46:47], v[14:15], v[52:53]
	v_pk_fma_f32 v[50:51], v[44:45], v[16:17], v[50:51]
	v_pk_fma_f32 v[52:53], v[48:49], v[16:17], v[52:53]
	v_cvt_pk_f32_fp8_e32 v[42:43], v110
	v_cvt_pk_f32_fp8_sdwa v[44:45], v110 src0_sel:WORD_1
	v_cvt_pk_f32_fp8_e32 v[46:47], v114
	v_cvt_pk_f32_fp8_sdwa v[48:49], v114 src0_sel:WORD_1
	v_pk_fma_f32 v[50:51], v[42:43], v[18:19], v[50:51]
	v_pk_fma_f32 v[52:53], v[46:47], v[18:19], v[52:53]
	v_pk_fma_f32 v[50:51], v[44:45], v[20:21], v[50:51]
	v_pk_fma_f32 v[52:53], v[48:49], v[20:21], v[52:53]
	v_cvt_pk_f32_fp8_e32 v[42:43], v111
	v_cvt_pk_f32_fp8_sdwa v[44:45], v111 src0_sel:WORD_1
	v_cvt_pk_f32_fp8_e32 v[46:47], v115
	v_cvt_pk_f32_fp8_sdwa v[48:49], v115 src0_sel:WORD_1
	v_pk_fma_f32 v[50:51], v[42:43], v[22:23], v[50:51]
	v_pk_fma_f32 v[52:53], v[46:47], v[22:23], v[52:53]
	v_pk_fma_f32 v[50:51], v[44:45], v[24:25], v[50:51]
	v_pk_fma_f32 v[52:53], v[48:49], v[24:25], v[52:53]
	v_add_f32_e32 v38, v50, v51
	v_add_f32_e32 v39, v52, v53
	v_cvt_pk_f32_fp8_e32 v[42:43], v116
	v_cvt_pk_f32_fp8_sdwa v[44:45], v116 src0_sel:WORD_1
	v_cvt_pk_f32_fp8_e32 v[46:47], v120
	v_cvt_pk_f32_fp8_sdwa v[48:49], v120 src0_sel:WORD_1
	v_pk_mul_f32 v[50:51], v[42:43], v[10:11]
	v_pk_mul_f32 v[52:53], v[46:47], v[10:11]
	v_pk_fma_f32 v[50:51], v[44:45], v[12:13], v[50:51]
	v_pk_fma_f32 v[52:53], v[48:49], v[12:13], v[52:53]
	v_cvt_pk_f32_fp8_e32 v[42:43], v117
	v_cvt_pk_f32_fp8_sdwa v[44:45], v117 src0_sel:WORD_1
	v_cvt_pk_f32_fp8_e32 v[46:47], v121
	v_cvt_pk_f32_fp8_sdwa v[48:49], v121 src0_sel:WORD_1
	v_pk_fma_f32 v[50:51], v[42:43], v[14:15], v[50:51]
	v_pk_fma_f32 v[52:53], v[46:47], v[14:15], v[52:53]
	v_pk_fma_f32 v[50:51], v[44:45], v[16:17], v[50:51]
	v_pk_fma_f32 v[52:53], v[48:49], v[16:17], v[52:53]
	v_cvt_pk_f32_fp8_e32 v[42:43], v118
	v_cvt_pk_f32_fp8_sdwa v[44:45], v118 src0_sel:WORD_1
	v_cvt_pk_f32_fp8_e32 v[46:47], v122
	v_cvt_pk_f32_fp8_sdwa v[48:49], v122 src0_sel:WORD_1
	v_pk_fma_f32 v[50:51], v[42:43], v[18:19], v[50:51]
	v_pk_fma_f32 v[52:53], v[46:47], v[18:19], v[52:53]
	v_pk_fma_f32 v[50:51], v[44:45], v[20:21], v[50:51]
	v_pk_fma_f32 v[52:53], v[48:49], v[20:21], v[52:53]
	v_cvt_pk_f32_fp8_e32 v[42:43], v119
	v_cvt_pk_f32_fp8_sdwa v[44:45], v119 src0_sel:WORD_1
	v_cvt_pk_f32_fp8_e32 v[46:47], v123
	v_cvt_pk_f32_fp8_sdwa v[48:49], v123 src0_sel:WORD_1
	v_pk_fma_f32 v[50:51], v[42:43], v[22:23], v[50:51]
	v_pk_fma_f32 v[52:53], v[46:47], v[22:23], v[52:53]
	v_pk_fma_f32 v[50:51], v[44:45], v[24:25], v[50:51]
	v_pk_fma_f32 v[52:53], v[48:49], v[24:25], v[52:53]
	v_add_f32_e32 v40, v50, v51
	v_add_f32_e32 v41, v52, v53
	s_lshl_b32 s11, s12, 12
	v_add_u32_e32 v6, s11, v3
	v_add_f32_dpp v42, v26, v26 row_half_mirror row_mask:0xf bank_mask:0xf
	v_add_f32_dpp v43, v34, v34 row_half_mirror row_mask:0xf bank_mask:0xf
; #define P5_LOAD(A, TAB, j0)                                                                \
;   _Pragma("unroll") for (int q = 0; q < 16; q++) {                                         \
;     A[q] = ((const uint4*)((TAB) + (size_t)widx[(j0) + q] * 1024))[lane];                  \
;   }
; __device__ __forceinline__ void phase5(const Params& p, char* smem, const bool store_x = true) {
;     ...
;     uint4 A0[16], A1[16];
;     P5_LOAD(A0, EU, 0)
; #pragma unroll 1
;     for (int j0 = 0; j0 < 128; j0 += 32) {
;       P5_LOAD(A1, EU, j0 + 16)
;       P5_COMPUTE_U(A0, j0)
;       if (j0 + 32 < 128) { P5_LOAD(A0, EU, j0 + 32) } else { P5_LOAD(A0, EV, 0) }
	v_cndmask_b32_e64 v26, v42, v43, s[14:15]
	v_add_f32_dpp v44, v27, v27 row_half_mirror row_mask:0xf bank_mask:0xf
	v_add_f32_dpp v45, v35, v35 row_half_mirror row_mask:0xf bank_mask:0xf
	v_cndmask_b32_e64 v27, v44, v45, s[14:15]
	v_add_f32_dpp v42, v28, v28 row_half_mirror row_mask:0xf bank_mask:0xf
	v_add_f32_dpp v43, v36, v36 row_half_mirror row_mask:0xf bank_mask:0xf
	v_cndmask_b32_e64 v28, v42, v43, s[14:15]
	v_add_f32_dpp v44, v29, v29 row_half_mirror row_mask:0xf bank_mask:0xf
	v_add_f32_dpp v45, v37, v37 row_half_mirror row_mask:0xf bank_mask:0xf
	v_cndmask_b32_e64 v29, v44, v45, s[14:15]
	v_add_f32_dpp v42, v30, v30 row_half_mirror row_mask:0xf bank_mask:0xf
	v_add_f32_dpp v43, v38, v38 row_half_mirror row_mask:0xf bank_mask:0xf
	v_cndmask_b32_e64 v30, v42, v43, s[14:15]
	v_add_f32_dpp v44, v31, v31 row_half_mirror row_mask:0xf bank_mask:0xf
	v_add_f32_dpp v45, v39, v39 row_half_mirror row_mask:0xf bank_mask:0xf
	v_cndmask_b32_e64 v31, v44, v45, s[14:15]
	v_add_f32_dpp v42, v32, v32 row_half_mirror row_mask:0xf bank_mask:0xf
	v_add_f32_dpp v43, v40, v40 row_half_mirror row_mask:0xf bank_mask:0xf
	v_cndmask_b32_e64 v32, v42, v43, s[14:15]
	v_add_f32_dpp v44, v33, v33 row_half_mirror row_mask:0xf bank_mask:0xf
	v_add_f32_dpp v45, v41, v41 row_half_mirror row_mask:0xf bank_mask:0xf
	v_cndmask_b32_e64 v33, v44, v45, s[14:15]
	s_nop 1
	v_add_f32_dpp v42, v26, v26 quad_perm:[2,3,0,1] row_mask:0xf bank_mask:0xf
	v_add_f32_dpp v43, v30, v30 quad_perm:[2,3,0,1] row_mask:0xf bank_mask:0xf
	v_cndmask_b32_e64 v26, v42, v43, s[40:41]
	v_add_f32_dpp v44, v27, v27 quad_perm:[2,3,0,1] row_mask:0xf bank_mask:0xf
	v_add_f32_dpp v45, v31, v31 quad_perm:[2,3,0,1] row_mask:0xf bank_mask:0xf
	v_cndmask_b32_e64 v27, v44, v45, s[40:41]
	v_add_f32_dpp v42, v28, v28 quad_perm:[2,3,0,1] row_mask:0xf bank_mask:0xf
	v_add_f32_dpp v43, v32, v32 quad_perm:[2,3,0,1] row_mask:0xf bank_mask:0xf
	v_cndmask_b32_e64 v28, v42, v43, s[40:41]
	v_add_f32_dpp v44, v29, v29 quad_perm:[2,3,0,1] row_mask:0xf bank_mask:0xf
	v_add_f32_dpp v45, v33, v33 quad_perm:[2,3,0,1] row_mask:0xf bank_mask:0xf
	v_cndmask_b32_e64 v29, v44, v45, s[40:41]
	s_nop 1
	v_add_f32_dpp v42, v26, v26 quad_perm:[1,0,3,2] row_mask:0xf bank_mask:0xf
	v_add_f32_dpp v43, v28, v28 quad_perm:[1,0,3,2] row_mask:0xf bank_mask:0xf
	v_cndmask_b32_e64 v26, v42, v43, s[42:43]
	v_add_f32_dpp v44, v27, v27 quad_perm:[1,0,3,2] row_mask:0xf bank_mask:0xf
	v_add_f32_dpp v45, v29, v29 quad_perm:[1,0,3,2] row_mask:0xf bank_mask:0xf
	v_cndmask_b32_e64 v27, v44, v45, s[42:43]
	s_nop 1
	v_mul_f32_e32 v26, v26, v56
	v_mul_f32_e32 v27, v27, v56
	global_store_dwordx2 v6, v[26:27], s[6:7]
.Lp5u_skip0:
	s_add_u32 s11, s16, 3
	s_and_b32 s11, s11, 7
	s_lshl_b32 s11, s11, 10
	v_add_u32_e32 v8, s11, v2
	ds_read_b128 v[10:13], v8 offset:0
	ds_read_b128 v[14:17], v8 offset:16
	ds_read_b128 v[18:21], v8 offset:32
	ds_read_b128 v[22:25], v8 offset:48
	s_add_u32 s10, s8, s26
	s_min_u32 s10, s10, s13
	s_lshl_b32 s18, s10, 10
	s_add_u32 s11, s16, 7
	s_and_b32 s11, s11, 7
	s_lshl_b32 s11, s11, 10
	s_add_u32 s11, s11, s17
	s_mov_b32 m0, s11
	v_lshl_add_u64 v[4:5], v[58:59], 0, s[18:19]
	global_load_lds_dwordx4 v[4:5], off
	s_add_u32 s10, s8, s22
	s_min_u32 s10, s10, s13
	s_lshl_b32 s11, s10, 11
	v_add_u32_e32 v6, s11, v7
	global_load_dwordx4 a[0:3], v6, s[36:37]
	global_load_dwordx4 a[4:7], v6, s[36:37] offset:16
	s_lshl_b32 s11, s10, 2
	v_mov_b32_e32 v6, s11
	global_load_dword a8, v6, s[38:39]
	s_waitcnt lgkmcnt(0)
	v_add_u32_e32 v10, v10, v1
	global_load_dwordx4 v[60:63], v10, s[2:3]
	v_add_u32_e32 v11, v11, v1
	global_load_dwordx4 v[64:67], v11, s[2:3]
	v_add_u32_e32 v12, v12, v1
	global_load_dwordx4 v[68:71], v12, s[2:3]
	v_add_u32_e32 v13, v13, v1
	global_load_dwordx4 v[72:75], v13, s[2:3]
	v_add_u32_e32 v14, v14, v1
	global_load_dwordx4 v[76:79], v14, s[2:3]
	v_add_u32_e32 v15, v15, v1
	global_load_dwordx4 v[80:83], v15, s[2:3]
	v_add_u32_e32 v16, v16, v1
	global_load_dwordx4 v[84:87], v16, s[2:3]
	v_add_u32_e32 v17, v17, v1
	global_load_dwordx4 v[88:91], v17, s[2:3]
	v_add_u32_e32 v18, v18, v1
	global_load_dwordx4 v[92:95], v18, s[2:3]
	v_add_u32_e32 v19, v19, v1
	global_load_dwordx4 v[96:99], v19, s[2:3]
	v_add_u32_e32 v20, v20, v1
	global_load_dwordx4 v[100:103], v20, s[2:3]
	v_add_u32_e32 v21, v21, v1
	global_load_dwordx4 v[104:107], v21, s[2:3]
	v_add_u32_e32 v22, v22, v1
	global_load_dwordx4 v[108:111], v22, s[2:3]
	v_add_u32_e32 v23, v23, v1
	global_load_dwordx4 v[112:115], v23, s[2:3]
	v_add_u32_e32 v24, v24, v1
	global_load_dwordx4 v[116:119], v24, s[2:3]
	v_add_u32_e32 v25, v25, v1
	global_load_dwordx4 v[120:123], v25, s[2:3]
	s_add_u32 s12, s8, s20
	s_waitcnt vmcnt(42)
	s_cmp_lt_u32 s12, 0x4200
	s_cbranch_scc0 .Lp5u_skip1
; __device__ __forceinline__ float bflo(unsigned u) { return __uint_as_float(u << 16); }
; __device__ __forceinline__ float bfhi(unsigned u) { return __uint_as_float(u & 0xffff0000u); }
; __device__ __forceinline__ void phase5(const Params& p, char* smem, const bool store_x = true) {
;     ...
;     float2v h2[8];
;     {
;       const uint4 a = cur_ha;
;       const uint4 b2 = cur_hb;
;       h2[0] = float2v{bflo(a.x), bfhi(a.x)}; h2[1] = float2v{bflo(a.y), bfhi(a.y)}; h2[2] = float2v{bflo(a.z), bfhi(a.z)}; h2[3] = float2v{bflo(a.w), bfhi(a.w)};
;       h2[4] = float2v{bflo(b2.x), bfhi(b2.x)}; h2[5] = float2v{bflo(b2.y), bfhi(b2.y)}; h2[6] = float2v{bflo(b2.z), bfhi(b2.z)}; h2[7] = float2v{bflo(b2.w), bfhi(b2.w)};
; #pragma unroll
;       for (int i = 0; i < 8; i++) h2[i] = h2[i] * gf[i] * cur_rs;
;     }
	v_accvgpr_read_b32 v56, a24
	v_fmamk_f32 v56, v56, 0x3a800000, v57
	v_mul_f32_e32 v9, 0x4b800000, v56
	v_cmp_gt_f32_e32 vcc, s33, v56
	s_nop 1
	v_cndmask_b32_e32 v56, v56, v9, vcc
	v_rsq_f32_e32 v56, v56
	s_nop 0
	v_mul_f32_e32 v9, 0x45800000, v56
	v_cndmask_b32_e32 v56, v56, v9, vcc
	v_accvgpr_read_b32 v9, a16
	v_accvgpr_read_b32 v54, a48
	v_accvgpr_read_b32 v55, a49
	v_lshlrev_b32_e32 v10, 16, v9
	v_and_b32_e32 v11, 0xffff0000, v9
	v_pk_mul_f32 v[10:11], v[10:11], v[54:55]
	v_accvgpr_read_b32 v9, a17
	v_accvgpr_read_b32 v54, a50
	v_accvgpr_read_b32 v55, a51
	v_lshlrev_b32_e32 v12, 16, v9
	v_and_b32_e32 v13, 0xffff0000, v9
	v_pk_mul_f32 v[12:13], v[12:13], v[54:55]
	v_accvgpr_read_b32 v9, a18
	v_accvgpr_read_b32 v54, a52
	v_accvgpr_read_b32 v55, a53
	v_lshlrev_b32_e32 v14, 16, v9
	v_and_b32_e32 v15, 0xffff0000, v9
	v_pk_mul_f32 v[14:15], v[14:15], v[54:55]
	v_accvgpr_read_b32 v9, a19
	v_accvgpr_read_b32 v54, a54
	v_accvgpr_read_b32 v55, a55
	v_lshlrev_b32_e32 v16, 16, v9
	v_and_b32_e32 v17, 0xffff0000, v9
	v_pk_mul_f32 v[16:17], v[16:17], v[54:55]
	v_accvgpr_read_b32 v9, a20
	v_accvgpr_read_b32 v54, a56
	v_accvgpr_read_b32 v55, a57
	v_lshlrev_b32_e32 v18, 16, v9
	v_and_b32_e32 v19, 0xffff0000, v9
	v_pk_mul_f32 v[18:19], v[18:19], v[54:55]
	v_accvgpr_read_b32 v9, a21
	v_accvgpr_read_b32 v54, a58
	v_accvgpr_read_b32 v55, a59
	v_lshlrev_b32_e32 v20, 16, v9
	v_and_b32_e32 v21, 0xffff0000, v9
	v_pk_mul_f32 v[20:21], v[20:21], v[54:55]
	v_accvgpr_read_b32 v9, a22
	v_accvgpr_read_b32 v54, a60
	v_accvgpr_read_b32 v55, a61
	v_lshlrev_b32_e32 v22, 16, v9
	v_and_b32_e32 v23, 0xffff0000, v9
	v_pk_mul_f32 v[22:23], v[22:23], v[54:55]
	v_accvgpr_read_b32 v9, a23
	v_accvgpr_read_b32 v54, a62
	v_accvgpr_read_b32 v55, a63
	v_lshlrev_b32_e32 v24, 16, v9
	v_and_b32_e32 v25, 0xffff0000, v9
	v_pk_mul_f32 v[24:25], v[24:25], v[54:55]
	v_cvt_pk_f32_fp8_e32 v[42:43], v124
	v_cvt_pk_f32_fp8_sdwa v[44:45], v124 src0_sel:WORD_1
	v_cvt_pk_f32_fp8_e32 v[46:47], v128
	v_cvt_pk_f32_fp8_sdwa v[48:49], v128 src0_sel:WORD_1
	v_pk_mul_f32 v[50:51], v[42:43], v[10:11]
	v_pk_mul_f32 v[52:53], v[46:47], v[10:11]
	v_pk_fma_f32 v[50:51], v[44:45], v[12:13], v[50:51]
	v_pk_fma_f32 v[52:53], v[48:49], v[12:13], v[52:53]
	v_cvt_pk_f32_fp8_e32 v[42:43], v125
	v_cvt_pk_f32_fp8_sdwa v[44:45], v125 src0_sel:WORD_1
	v_cvt_pk_f32_fp8_e32 v[46:47], v129
	v_cvt_pk_f32_fp8_sdwa v[48:49], v129 src0_sel:WORD_1
	v_pk_fma_f32 v[50:51], v[42:43], v[14:15], v[50:51]
	v_pk_fma_f32 v[52:53], v[46:47], v[14:15], v[52:53]
	v_pk_fma_f32 v[50:51], v[44:45], v[16:17], v[50:51]
	v_pk_fma_f32 v[52:53], v[48:49], v[16:17], v[52:53]
	v_cvt_pk_f32_fp8_e32 v[42:43], v126
	v_cvt_pk_f32_fp8_sdwa v[44:45], v126 src0_sel:WORD_1
	v_cvt_pk_f32_fp8_e32 v[46:47], v130
	v_cvt_pk_f32_fp8_sdwa v[48:49], v130 src0_sel:WORD_1
	v_pk_fma_f32 v[50:51], v[42:43], v[18:19], v[50:51]
	v_pk_fma_f32 v[52:53], v[46:47], v[18:19], v[52:53]
	v_pk_fma_f32 v[50:51], v[44:45], v[20:21], v[50:51]
	v_pk_fma_f32 v[52:53], v[48:49], v[20:21], v[52:53]
	v_cvt_pk_f32_fp8_e32 v[42:43], v127
	v_cvt_pk_f32_fp8_sdwa v[44:45], v127 src0_sel:WORD_1
	v_cvt_pk_f32_fp8_e32 v[46:47], v131
	v_cvt_pk_f32_fp8_sdwa v[48:49], v131 src0_sel:WORD_1
	v_pk_fma_f32 v[50:51], v[42:43], v[22:23], v[50:51]
	v_pk_fma_f32 v[52:53], v[46:47], v[22:23], v[52:53]
	v_pk_fma_f32 v[50:51], v[44:45], v[24:25], v[50:51]
	v_pk_fma_f32 v[52:53], v[48:49], v[24:25], v[52:53]
	v_add_f32_e32 v26, v50, v51
	v_add_f32_e32 v27, v52, v53
	v_cvt_pk_f32_fp8_e32 v[42:43], v132
	v_cvt_pk_f32_fp8_sdwa v[44:45], v132 src0_sel:WORD_1
	v_cvt_pk_f32_fp8_e32 v[46:47], v136
	v_cvt_pk_f32_fp8_sdwa v[48:49], v136 src0_sel:WORD_1
	v_pk_mul_f32 v[50:51], v[42:43], v[10:11]
	v_pk_mul_f32 v[52:53], v[46:47], v[10:11]
	v_pk_fma_f32 v[50:51], v[44:45], v[12:13], v[50:51]
	v_pk_fma_f32 v[52:53], v[48:49], v[12:13], v[52:53]
	v_cvt_pk_f32_fp8_e32 v[42:43], v133
	v_cvt_pk_f32_fp8_sdwa v[44:45], v133 src0_sel:WORD_1
	v_cvt_pk_f32_fp8_e32 v[46:47], v137
	v_cvt_pk_f32_fp8_sdwa v[48:49], v137 src0_sel:WORD_1
	v_pk_fma_f32 v[50:51], v[42:43], v[14:15], v[50:51]
	v_pk_fma_f32 v[52:53], v[46:47], v[14:15], v[52:53]
	v_pk_fma_f32 v[50:51], v[44:45], v[16:17], v[50:51]
	v_pk_fma_f32 v[52:53], v[48:49], v[16:17], v[52:53]
	v_cvt_pk_f32_fp8_e32 v[42:43], v134
	v_cvt_pk_f32_fp8_sdwa v[44:45], v134 src0_sel:WORD_1
	v_cvt_pk_f32_fp8_e32 v[46:47], v138
	v_cvt_pk_f32_fp8_sdwa v[48:49], v138 src0_sel:WORD_1
	v_pk_fma_f32 v[50:51], v[42:43], v[18:19], v[50:51]
	v_pk_fma_f32 v[52:53], v[46:47], v[18:19], v[52:53]
	v_pk_fma_f32 v[50:51], v[44:45], v[20:21], v[50:51]
	v_pk_fma_f32 v[52:53], v[48:49], v[20:21], v[52:53]
	v_cvt_pk_f32_fp8_e32 v[42:43], v135
	v_cvt_pk_f32_fp8_sdwa v[44:45], v135 src0_sel:WORD_1
	v_cvt_pk_f32_fp8_e32 v[46:47], v139
	v_cvt_pk_f32_fp8_sdwa v[48:49], v139 src0_sel:WORD_1
	v_pk_fma_f32 v[50:51], v[42:43], v[22:23], v[50:51]
	v_pk_fma_f32 v[52:53], v[46:47], v[22:23], v[52:53]
	v_pk_fma_f32 v[50:51], v[44:45], v[24:25], v[50:51]
	v_pk_fma_f32 v[52:53], v[48:49], v[24:25], v[52:53]
	v_add_f32_e32 v28, v50, v51
	v_add_f32_e32 v29, v52, v53
	v_cvt_pk_f32_fp8_e32 v[42:43], v140
	v_cvt_pk_f32_fp8_sdwa v[44:45], v140 src0_sel:WORD_1
	v_cvt_pk_f32_fp8_e32 v[46:47], v144
	v_cvt_pk_f32_fp8_sdwa v[48:49], v144 src0_sel:WORD_1
	v_pk_mul_f32 v[50:51], v[42:43], v[10:11]
	v_pk_mul_f32 v[52:53], v[46:47], v[10:11]
	v_pk_fma_f32 v[50:51], v[44:45], v[12:13], v[50:51]
	v_pk_fma_f32 v[52:53], v[48:49], v[12:13], v[52:53]
	v_cvt_pk_f32_fp8_e32 v[42:43], v141
	v_cvt_pk_f32_fp8_sdwa v[44:45], v141 src0_sel:WORD_1
	v_cvt_pk_f32_fp8_e32 v[46:47], v145
	v_cvt_pk_f32_fp8_sdwa v[48:49], v145 src0_sel:WORD_1
	v_pk_fma_f32 v[50:51], v[42:43], v[14:15], v[50:51]
	v_pk_fma_f32 v[52:53], v[46:47], v[14:15], v[52:53]
	v_pk_fma_f32 v[50:51], v[44:45], v[16:17], v[50:51]
	v_pk_fma_f32 v[52:53], v[48:49], v[16:17], v[52:53]
	v_cvt_pk_f32_fp8_e32 v[42:43], v142
	v_cvt_pk_f32_fp8_sdwa v[44:45], v142 src0_sel:WORD_1
	v_cvt_pk_f32_fp8_e32 v[46:47], v146
	v_cvt_pk_f32_fp8_sdwa v[48:49], v146 src0_sel:WORD_1
	v_pk_fma_f32 v[50:51], v[42:43], v[18:19], v[50:51]
	v_pk_fma_f32 v[52:53], v[46:47], v[18:19], v[52:53]
	v_pk_fma_f32 v[50:51], v[44:45], v[20:21], v[50:51]
	v_pk_fma_f32 v[52:53], v[48:49], v[20:21], v[52:53]
	v_cvt_pk_f32_fp8_e32 v[42:43], v143
	v_cvt_pk_f32_fp8_sdwa v[44:45], v143 src0_sel:WORD_1
	v_cvt_pk_f32_fp8_e32 v[46:47], v147
	v_cvt_pk_f32_fp8_sdwa v[48:49], v147 src0_sel:WORD_1
	v_pk_fma_f32 v[50:51], v[42:43], v[22:23], v[50:51]
	v_pk_fma_f32 v[52:53], v[46:47], v[22:23], v[52:53]
	v_pk_fma_f32 v[50:51], v[44:45], v[24:25], v[50:51]
	v_pk_fma_f32 v[52:53], v[48:49], v[24:25], v[52:53]
	v_add_f32_e32 v30, v50, v51
	v_add_f32_e32 v31, v52, v53
	v_cvt_pk_f32_fp8_e32 v[42:43], v148
	v_cvt_pk_f32_fp8_sdwa v[44:45], v148 src0_sel:WORD_1
	v_cvt_pk_f32_fp8_e32 v[46:47], v152
	v_cvt_pk_f32_fp8_sdwa v[48:49], v152 src0_sel:WORD_1
	v_pk_mul_f32 v[50:51], v[42:43], v[10:11]
	v_pk_mul_f32 v[52:53], v[46:47], v[10:11]
	v_pk_fma_f32 v[50:51], v[44:45], v[12:13], v[50:51]
	v_pk_fma_f32 v[52:53], v[48:49], v[12:13], v[52:53]
	v_cvt_pk_f32_fp8_e32 v[42:43], v149
	v_cvt_pk_f32_fp8_sdwa v[44:45], v149 src0_sel:WORD_1
	v_cvt_pk_f32_fp8_e32 v[46:47], v153
	v_cvt_pk_f32_fp8_sdwa v[48:49], v153 src0_sel:WORD_1
	v_pk_fma_f32 v[50:51], v[42:43], v[14:15], v[50:51]
	v_pk_fma_f32 v[52:53], v[46:47], v[14:15], v[52:53]
	v_pk_fma_f32 v[50:51], v[44:45], v[16:17], v[50:51]
	v_pk_fma_f32 v[52:53], v[48:49], v[16:17], v[52:53]
	v_cvt_pk_f32_fp8_e32 v[42:43], v150
	v_cvt_pk_f32_fp8_sdwa v[44:45], v150 src0_sel:WORD_1
	v_cvt_pk_f32_fp8_e32 v[46:47], v154
	v_cvt_pk_f32_fp8_sdwa v[48:49], v154 src0_sel:WORD_1
	v_pk_fma_f32 v[50:51], v[42:43], v[18:19], v[50:51]
	v_pk_fma_f32 v[52:53], v[46:47], v[18:19], v[52:53]
	v_pk_fma_f32 v[50:51], v[44:45], v[20:21], v[50:51]
	v_pk_fma_f32 v[52:53], v[48:49], v[20:21], v[52:53]
	v_cvt_pk_f32_fp8_e32 v[42:43], v151
	v_cvt_pk_f32_fp8_sdwa v[44:45], v151 src0_sel:WORD_1
	v_cvt_pk_f32_fp8_e32 v[46:47], v155
	v_cvt_pk_f32_fp8_sdwa v[48:49], v155 src0_sel:WORD_1
	v_pk_fma_f32 v[50:51], v[42:43], v[22:23], v[50:51]
	v_pk_fma_f32 v[52:53], v[46:47], v[22:23], v[52:53]
	v_pk_fma_f32 v[50:51], v[44:45], v[24:25], v[50:51]
	v_pk_fma_f32 v[52:53], v[48:49], v[24:25], v[52:53]
	v_add_f32_e32 v32, v50, v51
	v_add_f32_e32 v33, v52, v53
	v_cvt_pk_f32_fp8_e32 v[42:43], v156
	v_cvt_pk_f32_fp8_sdwa v[44:45], v156 src0_sel:WORD_1
	v_cvt_pk_f32_fp8_e32 v[46:47], v160
	v_cvt_pk_f32_fp8_sdwa v[48:49], v160 src0_sel:WORD_1
	v_pk_mul_f32 v[50:51], v[42:43], v[10:11]
	v_pk_mul_f32 v[52:53], v[46:47], v[10:11]
	v_pk_fma_f32 v[50:51], v[44:45], v[12:13], v[50:51]
	v_pk_fma_f32 v[52:53], v[48:49], v[12:13], v[52:53]
	v_cvt_pk_f32_fp8_e32 v[42:43], v157
	v_cvt_pk_f32_fp8_sdwa v[44:45], v157 src0_sel:WORD_1
	v_cvt_pk_f32_fp8_e32 v[46:47], v161
	v_cvt_pk_f32_fp8_sdwa v[48:49], v161 src0_sel:WORD_1
	v_pk_fma_f32 v[50:51], v[42:43], v[14:15], v[50:51]
	v_pk_fma_f32 v[52:53], v[46:47], v[14:15], v[52:53]
	v_pk_fma_f32 v[50:51], v[44:45], v[16:17], v[50:51]
	v_pk_fma_f32 v[52:53], v[48:49], v[16:17], v[52:53]
	v_cvt_pk_f32_fp8_e32 v[42:43], v158
	v_cvt_pk_f32_fp8_sdwa v[44:45], v158 src0_sel:WORD_1
	v_cvt_pk_f32_fp8_e32 v[46:47], v162
	v_cvt_pk_f32_fp8_sdwa v[48:49], v162 src0_sel:WORD_1
	v_pk_fma_f32 v[50:51], v[42:43], v[18:19], v[50:51]
	v_pk_fma_f32 v[52:53], v[46:47], v[18:19], v[52:53]
	v_pk_fma_f32 v[50:51], v[44:45], v[20:21], v[50:51]
	v_pk_fma_f32 v[52:53], v[48:49], v[20:21], v[52:53]
	v_cvt_pk_f32_fp8_e32 v[42:43], v159
	v_cvt_pk_f32_fp8_sdwa v[44:45], v159 src0_sel:WORD_1
	v_cvt_pk_f32_fp8_e32 v[46:47], v163
	v_cvt_pk_f32_fp8_sdwa v[48:49], v163 src0_sel:WORD_1
	v_pk_fma_f32 v[50:51], v[42:43], v[22:23], v[50:51]
	v_pk_fma_f32 v[52:53], v[46:47], v[22:23], v[52:53]
	v_pk_fma_f32 v[50:51], v[44:45], v[24:25], v[50:51]
	v_pk_fma_f32 v[52:53], v[48:49], v[24:25], v[52:53]
	v_add_f32_e32 v34, v50, v51
	v_add_f32_e32 v35, v52, v53
	v_cvt_pk_f32_fp8_e32 v[42:43], v164
	v_cvt_pk_f32_fp8_sdwa v[44:45], v164 src0_sel:WORD_1
	v_cvt_pk_f32_fp8_e32 v[46:47], v168
	v_cvt_pk_f32_fp8_sdwa v[48:49], v168 src0_sel:WORD_1
	v_pk_mul_f32 v[50:51], v[42:43], v[10:11]
	v_pk_mul_f32 v[52:53], v[46:47], v[10:11]
	v_pk_fma_f32 v[50:51], v[44:45], v[12:13], v[50:51]
	v_pk_fma_f32 v[52:53], v[48:49], v[12:13], v[52:53]
	v_cvt_pk_f32_fp8_e32 v[42:43], v165
	v_cvt_pk_f32_fp8_sdwa v[44:45], v165 src0_sel:WORD_1
	v_cvt_pk_f32_fp8_e32 v[46:47], v169
	v_cvt_pk_f32_fp8_sdwa v[48:49], v169 src0_sel:WORD_1
	v_pk_fma_f32 v[50:51], v[42:43], v[14:15], v[50:51]
	v_pk_fma_f32 v[52:53], v[46:47], v[14:15], v[52:53]
	v_pk_fma_f32 v[50:51], v[44:45], v[16:17], v[50:51]
	v_pk_fma_f32 v[52:53], v[48:49], v[16:17], v[52:53]
	v_cvt_pk_f32_fp8_e32 v[42:43], v166
	v_cvt_pk_f32_fp8_sdwa v[44:45], v166 src0_sel:WORD_1
	v_cvt_pk_f32_fp8_e32 v[46:47], v170
	v_cvt_pk_f32_fp8_sdwa v[48:49], v170 src0_sel:WORD_1
	v_pk_fma_f32 v[50:51], v[42:43], v[18:19], v[50:51]
	v_pk_fma_f32 v[52:53], v[46:47], v[18:19], v[52:53]
	v_pk_fma_f32 v[50:51], v[44:45], v[20:21], v[50:51]
	v_pk_fma_f32 v[52:53], v[48:49], v[20:21], v[52:53]
	v_cvt_pk_f32_fp8_e32 v[42:43], v167
	v_cvt_pk_f32_fp8_sdwa v[44:45], v167 src0_sel:WORD_1
	v_cvt_pk_f32_fp8_e32 v[46:47], v171
	v_cvt_pk_f32_fp8_sdwa v[48:49], v171 src0_sel:WORD_1
	v_pk_fma_f32 v[50:51], v[42:43], v[22:23], v[50:51]
	v_pk_fma_f32 v[52:53], v[46:47], v[22:23], v[52:53]
	v_pk_fma_f32 v[50:51], v[44:45], v[24:25], v[50:51]
	v_pk_fma_f32 v[52:53], v[48:49], v[24:25], v[52:53]
	v_add_f32_e32 v36, v50, v51
	v_add_f32_e32 v37, v52, v53
	v_cvt_pk_f32_fp8_e32 v[42:43], v172
	v_cvt_pk_f32_fp8_sdwa v[44:45], v172 src0_sel:WORD_1
	v_cvt_pk_f32_fp8_e32 v[46:47], v176
	v_cvt_pk_f32_fp8_sdwa v[48:49], v176 src0_sel:WORD_1
	v_pk_mul_f32 v[50:51], v[42:43], v[10:11]
	v_pk_mul_f32 v[52:53], v[46:47], v[10:11]
	v_pk_fma_f32 v[50:51], v[44:45], v[12:13], v[50:51]
	v_pk_fma_f32 v[52:53], v[48:49], v[12:13], v[52:53]
	v_cvt_pk_f32_fp8_e32 v[42:43], v173
	v_cvt_pk_f32_fp8_sdwa v[44:45], v173 src0_sel:WORD_1
	v_cvt_pk_f32_fp8_e32 v[46:47], v177
	v_cvt_pk_f32_fp8_sdwa v[48:49], v177 src0_sel:WORD_1
	v_pk_fma_f32 v[50:51], v[42:43], v[14:15], v[50:51]
	v_pk_fma_f32 v[52:53], v[46:47], v[14:15], v[52:53]
	v_pk_fma_f32 v[50:51], v[44:45], v[16:17], v[50:51]
	v_pk_fma_f32 v[52:53], v[48:49], v[16:17], v[52:53]
	v_cvt_pk_f32_fp8_e32 v[42:43], v174
	v_cvt_pk_f32_fp8_sdwa v[44:45], v174 src0_sel:WORD_1
	v_cvt_pk_f32_fp8_e32 v[46:47], v178
	v_cvt_pk_f32_fp8_sdwa v[48:49], v178 src0_sel:WORD_1
	v_pk_fma_f32 v[50:51], v[42:43], v[18:19], v[50:51]
	v_pk_fma_f32 v[52:53], v[46:47], v[18:19], v[52:53]
	v_pk_fma_f32 v[50:51], v[44:45], v[20:21], v[50:51]
	v_pk_fma_f32 v[52:53], v[48:49], v[20:21], v[52:53]
	v_cvt_pk_f32_fp8_e32 v[42:43], v175
	v_cvt_pk_f32_fp8_sdwa v[44:45], v175 src0_sel:WORD_1
	v_cvt_pk_f32_fp8_e32 v[46:47], v179
	v_cvt_pk_f32_fp8_sdwa v[48:49], v179 src0_sel:WORD_1
	v_pk_fma_f32 v[50:51], v[42:43], v[22:23], v[50:51]
	v_pk_fma_f32 v[52:53], v[46:47], v[22:23], v[52:53]
	v_pk_fma_f32 v[50:51], v[44:45], v[24:25], v[50:51]
	v_pk_fma_f32 v[52:53], v[48:49], v[24:25], v[52:53]
	v_add_f32_e32 v38, v50, v51
	v_add_f32_e32 v39, v52, v53
	v_cvt_pk_f32_fp8_e32 v[42:43], v180
	v_cvt_pk_f32_fp8_sdwa v[44:45], v180 src0_sel:WORD_1
	v_cvt_pk_f32_fp8_e32 v[46:47], v184
	v_cvt_pk_f32_fp8_sdwa v[48:49], v184 src0_sel:WORD_1
	v_pk_mul_f32 v[50:51], v[42:43], v[10:11]
	v_pk_mul_f32 v[52:53], v[46:47], v[10:11]
	v_pk_fma_f32 v[50:51], v[44:45], v[12:13], v[50:51]
	v_pk_fma_f32 v[52:53], v[48:49], v[12:13], v[52:53]
	v_cvt_pk_f32_fp8_e32 v[42:43], v181
	v_cvt_pk_f32_fp8_sdwa v[44:45], v181 src0_sel:WORD_1
	v_cvt_pk_f32_fp8_e32 v[46:47], v185
	v_cvt_pk_f32_fp8_sdwa v[48:49], v185 src0_sel:WORD_1
	v_pk_fma_f32 v[50:51], v[42:43], v[14:15], v[50:51]
	v_pk_fma_f32 v[52:53], v[46:47], v[14:15], v[52:53]
	v_pk_fma_f32 v[50:51], v[44:45], v[16:17], v[50:51]
	v_pk_fma_f32 v[52:53], v[48:49], v[16:17], v[52:53]
	v_cvt_pk_f32_fp8_e32 v[42:43], v182
	v_cvt_pk_f32_fp8_sdwa v[44:45], v182 src0_sel:WORD_1
	v_cvt_pk_f32_fp8_e32 v[46:47], v186
	v_cvt_pk_f32_fp8_sdwa v[48:49], v186 src0_sel:WORD_1
	v_pk_fma_f32 v[50:51], v[42:43], v[18:19], v[50:51]
	v_pk_fma_f32 v[52:53], v[46:47], v[18:19], v[52:53]
	v_pk_fma_f32 v[50:51], v[44:45], v[20:21], v[50:51]
	v_pk_fma_f32 v[52:53], v[48:49], v[20:21], v[52:53]
	v_cvt_pk_f32_fp8_e32 v[42:43], v183
	v_cvt_pk_f32_fp8_sdwa v[44:45], v183 src0_sel:WORD_1
	v_cvt_pk_f32_fp8_e32 v[46:47], v187
	v_cvt_pk_f32_fp8_sdwa v[48:49], v187 src0_sel:WORD_1
	v_pk_fma_f32 v[50:51], v[42:43], v[22:23], v[50:51]
	v_pk_fma_f32 v[52:53], v[46:47], v[22:23], v[52:53]
	v_pk_fma_f32 v[50:51], v[44:45], v[24:25], v[50:51]
	v_pk_fma_f32 v[52:53], v[48:49], v[24:25], v[52:53]
	v_add_f32_e32 v40, v50, v51
	v_add_f32_e32 v41, v52, v53
	s_lshl_b32 s11, s12, 12
	v_add_u32_e32 v6, s11, v3
	v_add_f32_dpp v42, v26, v26 row_half_mirror row_mask:0xf bank_mask:0xf
	v_add_f32_dpp v43, v34, v34 row_half_mirror row_mask:0xf bank_mask:0xf
	v_cndmask_b32_e64 v26, v42, v43, s[14:15]
	v_add_f32_dpp v44, v27, v27 row_half_mirror row_mask:0xf bank_mask:0xf
	v_add_f32_dpp v45, v35, v35 row_half_mirror row_mask:0xf bank_mask:0xf
	v_cndmask_b32_e64 v27, v44, v45, s[14:15]
	v_add_f32_dpp v42, v28, v28 row_half_mirror row_mask:0xf bank_mask:0xf
	v_add_f32_dpp v43, v36, v36 row_half_mirror row_mask:0xf bank_mask:0xf
	v_cndmask_b32_e64 v28, v42, v43, s[14:15]
	v_add_f32_dpp v44, v29, v29 row_half_mirror row_mask:0xf bank_mask:0xf
	v_add_f32_dpp v45, v37, v37 row_half_mirror row_mask:0xf bank_mask:0xf
	v_cndmask_b32_e64 v29, v44, v45, s[14:15]
	v_add_f32_dpp v42, v30, v30 row_half_mirror row_mask:0xf bank_mask:0xf
	v_add_f32_dpp v43, v38, v38 row_half_mirror row_mask:0xf bank_mask:0xf
	v_cndmask_b32_e64 v30, v42, v43, s[14:15]
	v_add_f32_dpp v44, v31, v31 row_half_mirror row_mask:0xf bank_mask:0xf
	v_add_f32_dpp v45, v39, v39 row_half_mirror row_mask:0xf bank_mask:0xf
	v_cndmask_b32_e64 v31, v44, v45, s[14:15]
	v_add_f32_dpp v42, v32, v32 row_half_mirror row_mask:0xf bank_mask:0xf
	v_add_f32_dpp v43, v40, v40 row_half_mirror row_mask:0xf bank_mask:0xf
	v_cndmask_b32_e64 v32, v42, v43, s[14:15]
	v_add_f32_dpp v44, v33, v33 row_half_mirror row_mask:0xf bank_mask:0xf
	v_add_f32_dpp v45, v41, v41 row_half_mirror row_mask:0xf bank_mask:0xf
	v_cndmask_b32_e64 v33, v44, v45, s[14:15]
	s_nop 1
	v_add_f32_dpp v42, v26, v26 quad_perm:[2,3,0,1] row_mask:0xf bank_mask:0xf
	v_add_f32_dpp v43, v30, v30 quad_perm:[2,3,0,1] row_mask:0xf bank_mask:0xf
	v_cndmask_b32_e64 v26, v42, v43, s[40:41]
	v_add_f32_dpp v44, v27, v27 quad_perm:[2,3,0,1] row_mask:0xf bank_mask:0xf
	v_add_f32_dpp v45, v31, v31 quad_perm:[2,3,0,1] row_mask:0xf bank_mask:0xf
	v_cndmask_b32_e64 v27, v44, v45, s[40:41]
	v_add_f32_dpp v42, v28, v28 quad_perm:[2,3,0,1] row_mask:0xf bank_mask:0xf
	v_add_f32_dpp v43, v32, v32 quad_perm:[2,3,0,1] row_mask:0xf bank_mask:0xf
	v_cndmask_b32_e64 v28, v42, v43, s[40:41]
	v_add_f32_dpp v44, v29, v29 quad_perm:[2,3,0,1] row_mask:0xf bank_mask:0xf
	v_add_f32_dpp v45, v33, v33 quad_perm:[2,3,0,1] row_mask:0xf bank_mask:0xf
	v_cndmask_b32_e64 v29, v44, v45, s[40:41]
	s_nop 1
	v_add_f32_dpp v42, v26, v26 quad_perm:[1,0,3,2] row_mask:0xf bank_mask:0xf
	v_add_f32_dpp v43, v28, v28 quad_perm:[1,0,3,2] row_mask:0xf bank_mask:0xf
	v_cndmask_b32_e64 v26, v42, v43, s[42:43]
	v_add_f32_dpp v44, v27, v27 quad_perm:[1,0,3,2] row_mask:0xf bank_mask:0xf
	v_add_f32_dpp v45, v29, v29 quad_perm:[1,0,3,2] row_mask:0xf bank_mask:0xf
	v_cndmask_b32_e64 v27, v44, v45, s[42:43]
	s_nop 1
	v_mul_f32_e32 v26, v26, v56
	v_mul_f32_e32 v27, v27, v56
	global_store_dwordx2 v6, v[26:27], s[6:7]
; #define P5_LOAD(A, TAB, j0)                                                                \
;   _Pragma("unroll") for (int q = 0; q < 16; q++) {                                         \
;     A[q] = ((const uint4*)((TAB) + (size_t)widx[(j0) + q] * 1024))[lane];                  \
;   }
; __device__ __forceinline__ void phase5(const Params& p, char* smem, const bool store_x = true) {
;     ...
;     uint4 A0[16], A1[16];
;     P5_LOAD(A0, EU, 0)
; #pragma unroll 1
;     for (int j0 = 0; j0 < 128; j0 += 32) {
;       P5_LOAD(A1, EU, j0 + 16)
;       P5_COMPUTE_U(A0, j0)
;       if (j0 + 32 < 128) { P5_LOAD(A0, EU, j0 + 32) } else { P5_LOAD(A0, EV, 0) }
;       P5_COMPUTE_U(A1, j0 + 16)
.Lp5u_skip1:
	s_add_u32 s11, s16, 4
	s_and_b32 s11, s11, 7
	s_lshl_b32 s11, s11, 10
	v_add_u32_e32 v8, s11, v2
	ds_read_b128 v[10:13], v8 offset:0
	ds_read_b128 v[14:17], v8 offset:16
	ds_read_b128 v[18:21], v8 offset:32
	ds_read_b128 v[22:25], v8 offset:48
	s_add_u32 s10, s8, s27
	s_min_u32 s10, s10, s13
	s_lshl_b32 s18, s10, 10
	s_add_u32 s11, s16, 8
	s_and_b32 s11, s11, 7
	s_lshl_b32 s11, s11, 10
	s_add_u32 s11, s11, s17
	s_mov_b32 m0, s11
	v_lshl_add_u64 v[4:5], v[58:59], 0, s[18:19]
	global_load_lds_dwordx4 v[4:5], off
	s_add_u32 s10, s8, s23
	s_min_u32 s10, s10, s13
	s_lshl_b32 s11, s10, 11
	v_add_u32_e32 v6, s11, v7
	global_load_dwordx4 a[16:19], v6, s[36:37]
	global_load_dwordx4 a[20:23], v6, s[36:37] offset:16
	s_lshl_b32 s11, s10, 2
	v_mov_b32_e32 v6, s11
	global_load_dword a24, v6, s[38:39]
	s_waitcnt lgkmcnt(0)
	v_add_u32_e32 v10, v10, v1
	global_load_dwordx4 v[124:127], v10, s[2:3]
	v_add_u32_e32 v11, v11, v1
	global_load_dwordx4 v[128:131], v11, s[2:3]
	v_add_u32_e32 v12, v12, v1
	global_load_dwordx4 v[132:135], v12, s[2:3]
	v_add_u32_e32 v13, v13, v1
	global_load_dwordx4 v[136:139], v13, s[2:3]
	v_add_u32_e32 v14, v14, v1
	global_load_dwordx4 v[140:143], v14, s[2:3]
	v_add_u32_e32 v15, v15, v1
	global_load_dwordx4 v[144:147], v15, s[2:3]
	v_add_u32_e32 v16, v16, v1
	global_load_dwordx4 v[148:151], v16, s[2:3]
	v_add_u32_e32 v17, v17, v1
	global_load_dwordx4 v[152:155], v17, s[2:3]
	v_add_u32_e32 v18, v18, v1
	global_load_dwordx4 v[156:159], v18, s[2:3]
	v_add_u32_e32 v19, v19, v1
	global_load_dwordx4 v[160:163], v19, s[2:3]
	v_add_u32_e32 v20, v20, v1
	global_load_dwordx4 v[164:167], v20, s[2:3]
	v_add_u32_e32 v21, v21, v1
	global_load_dwordx4 v[168:171], v21, s[2:3]
	v_add_u32_e32 v22, v22, v1
	global_load_dwordx4 v[172:175], v22, s[2:3]
	v_add_u32_e32 v23, v23, v1
	global_load_dwordx4 v[176:179], v23, s[2:3]
	v_add_u32_e32 v24, v24, v1
	global_load_dwordx4 v[180:183], v24, s[2:3]
	v_add_u32_e32 v25, v25, v1
	global_load_dwordx4 v[184:187], v25, s[2:3]
	s_add_u32 s12, s8, s21
	s_waitcnt vmcnt(42)
	s_cmp_lt_u32 s12, 0x4200
	s_cbranch_scc0 .Lp5u_skip2
	v_accvgpr_read_b32 v56, a40
	v_fmamk_f32 v56, v56, 0x3a800000, v57
	v_mul_f32_e32 v9, 0x4b800000, v56
	v_cmp_gt_f32_e32 vcc, s33, v56
	s_nop 1
	v_cndmask_b32_e32 v56, v56, v9, vcc
	v_rsq_f32_e32 v56, v56
	s_nop 0
	v_mul_f32_e32 v9, 0x45800000, v56
	v_cndmask_b32_e32 v56, v56, v9, vcc
	v_accvgpr_read_b32 v9, a32
	v_accvgpr_read_b32 v54, a48
	v_accvgpr_read_b32 v55, a49
	v_lshlrev_b32_e32 v10, 16, v9
	v_and_b32_e32 v11, 0xffff0000, v9
	v_pk_mul_f32 v[10:11], v[10:11], v[54:55]
	v_accvgpr_read_b32 v9, a33
	v_accvgpr_read_b32 v54, a50
	v_accvgpr_read_b32 v55, a51
	v_lshlrev_b32_e32 v12, 16, v9
	v_and_b32_e32 v13, 0xffff0000, v9
	v_pk_mul_f32 v[12:13], v[12:13], v[54:55]
	v_accvgpr_read_b32 v9, a34
	v_accvgpr_read_b32 v54, a52
	v_accvgpr_read_b32 v55, a53
	v_lshlrev_b32_e32 v14, 16, v9
	v_and_b32_e32 v15, 0xffff0000, v9
	v_pk_mul_f32 v[14:15], v[14:15], v[54:55]
	v_accvgpr_read_b32 v9, a35
	v_accvgpr_read_b32 v54, a54
	v_accvgpr_read_b32 v55, a55
	v_lshlrev_b32_e32 v16, 16, v9
	v_and_b32_e32 v17, 0xffff0000, v9
	v_pk_mul_f32 v[16:17], v[16:17], v[54:55]
	v_accvgpr_read_b32 v9, a36
	v_accvgpr_read_b32 v54, a56
	v_accvgpr_read_b32 v55, a57
	v_lshlrev_b32_e32 v18, 16, v9
	v_and_b32_e32 v19, 0xffff0000, v9
	v_pk_mul_f32 v[18:19], v[18:19], v[54:55]
	v_accvgpr_read_b32 v9, a37
	v_accvgpr_read_b32 v54, a58
	v_accvgpr_read_b32 v55, a59
	v_lshlrev_b32_e32 v20, 16, v9
	v_and_b32_e32 v21, 0xffff0000, v9
	v_pk_mul_f32 v[20:21], v[20:21], v[54:55]
	v_accvgpr_read_b32 v9, a38
	v_accvgpr_read_b32 v54, a60
	v_accvgpr_read_b32 v55, a61
	v_lshlrev_b32_e32 v22, 16, v9
	v_and_b32_e32 v23, 0xffff0000, v9
	v_pk_mul_f32 v[22:23], v[22:23], v[54:55]
	v_accvgpr_read_b32 v9, a39
	v_accvgpr_read_b32 v54, a62
	v_accvgpr_read_b32 v55, a63
	v_lshlrev_b32_e32 v24, 16, v9
	v_and_b32_e32 v25, 0xffff0000, v9
	v_pk_mul_f32 v[24:25], v[24:25], v[54:55]
	v_cvt_pk_f32_fp8_e32 v[42:43], v188
	v_cvt_pk_f32_fp8_sdwa v[44:45], v188 src0_sel:WORD_1
	v_cvt_pk_f32_fp8_e32 v[46:47], v192
	v_cvt_pk_f32_fp8_sdwa v[48:49], v192 src0_sel:WORD_1
	v_pk_mul_f32 v[50:51], v[42:43], v[10:11]
	v_pk_mul_f32 v[52:53], v[46:47], v[10:11]
	v_pk_fma_f32 v[50:51], v[44:45], v[12:13], v[50:51]
	v_pk_fma_f32 v[52:53], v[48:49], v[12:13], v[52:53]
	v_cvt_pk_f32_fp8_e32 v[42:43], v189
	v_cvt_pk_f32_fp8_sdwa v[44:45], v189 src0_sel:WORD_1
	v_cvt_pk_f32_fp8_e32 v[46:47], v193
	v_cvt_pk_f32_fp8_sdwa v[48:49], v193 src0_sel:WORD_1
	v_pk_fma_f32 v[50:51], v[42:43], v[14:15], v[50:51]
	v_pk_fma_f32 v[52:53], v[46:47], v[14:15], v[52:53]
	v_pk_fma_f32 v[50:51], v[44:45], v[16:17], v[50:51]
	v_pk_fma_f32 v[52:53], v[48:49], v[16:17], v[52:53]
	v_cvt_pk_f32_fp8_e32 v[42:43], v190
	v_cvt_pk_f32_fp8_sdwa v[44:45], v190 src0_sel:WORD_1
	v_cvt_pk_f32_fp8_e32 v[46:47], v194
	v_cvt_pk_f32_fp8_sdwa v[48:49], v194 src0_sel:WORD_1
	v_pk_fma_f32 v[50:51], v[42:43], v[18:19], v[50:51]
	v_pk_fma_f32 v[52:53], v[46:47], v[18:19], v[52:53]
	v_pk_fma_f32 v[50:51], v[44:45], v[20:21], v[50:51]
	v_pk_fma_f32 v[52:53], v[48:49], v[20:21], v[52:53]
	v_cvt_pk_f32_fp8_e32 v[42:43], v191
	v_cvt_pk_f32_fp8_sdwa v[44:45], v191 src0_sel:WORD_1
	v_cvt_pk_f32_fp8_e32 v[46:47], v195
	v_cvt_pk_f32_fp8_sdwa v[48:49], v195 src0_sel:WORD_1
	v_pk_fma_f32 v[50:51], v[42:43], v[22:23], v[50:51]
	v_pk_fma_f32 v[52:53], v[46:47], v[22:23], v[52:53]
	v_pk_fma_f32 v[50:51], v[44:45], v[24:25], v[50:51]
	v_pk_fma_f32 v[52:53], v[48:49], v[24:25], v[52:53]
	v_add_f32_e32 v26, v50, v51
	v_add_f32_e32 v27, v52, v53
	v_cvt_pk_f32_fp8_e32 v[42:43], v196
	v_cvt_pk_f32_fp8_sdwa v[44:45], v196 src0_sel:WORD_1
	v_cvt_pk_f32_fp8_e32 v[46:47], v200
	v_cvt_pk_f32_fp8_sdwa v[48:49], v200 src0_sel:WORD_1
	v_pk_mul_f32 v[50:51], v[42:43], v[10:11]
	v_pk_mul_f32 v[52:53], v[46:47], v[10:11]
	v_pk_fma_f32 v[50:51], v[44:45], v[12:13], v[50:51]
	v_pk_fma_f32 v[52:53], v[48:49], v[12:13], v[52:53]
	v_cvt_pk_f32_fp8_e32 v[42:43], v197
	v_cvt_pk_f32_fp8_sdwa v[44:45], v197 src0_sel:WORD_1
	v_cvt_pk_f32_fp8_e32 v[46:47], v201
	v_cvt_pk_f32_fp8_sdwa v[48:49], v201 src0_sel:WORD_1
	v_pk_fma_f32 v[50:51], v[42:43], v[14:15], v[50:51]
	v_pk_fma_f32 v[52:53], v[46:47], v[14:15], v[52:53]
	v_pk_fma_f32 v[50:51], v[44:45], v[16:17], v[50:51]
	v_pk_fma_f32 v[52:53], v[48:49], v[16:17], v[52:53]
	v_cvt_pk_f32_fp8_e32 v[42:43], v198
	v_cvt_pk_f32_fp8_sdwa v[44:45], v198 src0_sel:WORD_1
	v_cvt_pk_f32_fp8_e32 v[46:47], v202
	v_cvt_pk_f32_fp8_sdwa v[48:49], v202 src0_sel:WORD_1
	v_pk_fma_f32 v[50:51], v[42:43], v[18:19], v[50:51]
	v_pk_fma_f32 v[52:53], v[46:47], v[18:19], v[52:53]
	v_pk_fma_f32 v[50:51], v[44:45], v[20:21], v[50:51]
	v_pk_fma_f32 v[52:53], v[48:49], v[20:21], v[52:53]
	v_cvt_pk_f32_fp8_e32 v[42:43], v199
	v_cvt_pk_f32_fp8_sdwa v[44:45], v199 src0_sel:WORD_1
	v_cvt_pk_f32_fp8_e32 v[46:47], v203
	v_cvt_pk_f32_fp8_sdwa v[48:49], v203 src0_sel:WORD_1
	v_pk_fma_f32 v[50:51], v[42:43], v[22:23], v[50:51]
	v_pk_fma_f32 v[52:53], v[46:47], v[22:23], v[52:53]
	v_pk_fma_f32 v[50:51], v[44:45], v[24:25], v[50:51]
	v_pk_fma_f32 v[52:53], v[48:49], v[24:25], v[52:53]
	v_add_f32_e32 v28, v50, v51
	v_add_f32_e32 v29, v52, v53
	v_cvt_pk_f32_fp8_e32 v[42:43], v204
	v_cvt_pk_f32_fp8_sdwa v[44:45], v204 src0_sel:WORD_1
	v_cvt_pk_f32_fp8_e32 v[46:47], v208
	v_cvt_pk_f32_fp8_sdwa v[48:49], v208 src0_sel:WORD_1
	v_pk_mul_f32 v[50:51], v[42:43], v[10:11]
	v_pk_mul_f32 v[52:53], v[46:47], v[10:11]
	v_pk_fma_f32 v[50:51], v[44:45], v[12:13], v[50:51]
	v_pk_fma_f32 v[52:53], v[48:49], v[12:13], v[52:53]
	v_cvt_pk_f32_fp8_e32 v[42:43], v205
	v_cvt_pk_f32_fp8_sdwa v[44:45], v205 src0_sel:WORD_1
	v_cvt_pk_f32_fp8_e32 v[46:47], v209
	v_cvt_pk_f32_fp8_sdwa v[48:49], v209 src0_sel:WORD_1
	v_pk_fma_f32 v[50:51], v[42:43], v[14:15], v[50:51]
	v_pk_fma_f32 v[52:53], v[46:47], v[14:15], v[52:53]
	v_pk_fma_f32 v[50:51], v[44:45], v[16:17], v[50:51]
	v_pk_fma_f32 v[52:53], v[48:49], v[16:17], v[52:53]
	v_cvt_pk_f32_fp8_e32 v[42:43], v206
	v_cvt_pk_f32_fp8_sdwa v[44:45], v206 src0_sel:WORD_1
	v_cvt_pk_f32_fp8_e32 v[46:47], v210
	v_cvt_pk_f32_fp8_sdwa v[48:49], v210 src0_sel:WORD_1
	v_pk_fma_f32 v[50:51], v[42:43], v[18:19], v[50:51]
	v_pk_fma_f32 v[52:53], v[46:47], v[18:19], v[52:53]
	v_pk_fma_f32 v[50:51], v[44:45], v[20:21], v[50:51]
	v_pk_fma_f32 v[52:53], v[48:49], v[20:21], v[52:53]
	v_cvt_pk_f32_fp8_e32 v[42:43], v207
	v_cvt_pk_f32_fp8_sdwa v[44:45], v207 src0_sel:WORD_1
	v_cvt_pk_f32_fp8_e32 v[46:47], v211
	v_cvt_pk_f32_fp8_sdwa v[48:49], v211 src0_sel:WORD_1
	v_pk_fma_f32 v[50:51], v[42:43], v[22:23], v[50:51]
	v_pk_fma_f32 v[52:53], v[46:47], v[22:23], v[52:53]
	v_pk_fma_f32 v[50:51], v[44:45], v[24:25], v[50:51]
	v_pk_fma_f32 v[52:53], v[48:49], v[24:25], v[52:53]
	v_add_f32_e32 v30, v50, v51
	v_add_f32_e32 v31, v52, v53
	v_cvt_pk_f32_fp8_e32 v[42:43], v212
	v_cvt_pk_f32_fp8_sdwa v[44:45], v212 src0_sel:WORD_1
	v_cvt_pk_f32_fp8_e32 v[46:47], v216
	v_cvt_pk_f32_fp8_sdwa v[48:49], v216 src0_sel:WORD_1
	v_pk_mul_f32 v[50:51], v[42:43], v[10:11]
	v_pk_mul_f32 v[52:53], v[46:47], v[10:11]
	v_pk_fma_f32 v[50:51], v[44:45], v[12:13], v[50:51]
	v_pk_fma_f32 v[52:53], v[48:49], v[12:13], v[52:53]
	v_cvt_pk_f32_fp8_e32 v[42:43], v213
	v_cvt_pk_f32_fp8_sdwa v[44:45], v213 src0_sel:WORD_1
	v_cvt_pk_f32_fp8_e32 v[46:47], v217
	v_cvt_pk_f32_fp8_sdwa v[48:49], v217 src0_sel:WORD_1
	v_pk_fma_f32 v[50:51], v[42:43], v[14:15], v[50:51]
	v_pk_fma_f32 v[52:53], v[46:47], v[14:15], v[52:53]
	v_pk_fma_f32 v[50:51], v[44:45], v[16:17], v[50:51]
	v_pk_fma_f32 v[52:53], v[48:49], v[16:17], v[52:53]
	v_cvt_pk_f32_fp8_e32 v[42:43], v214
	v_cvt_pk_f32_fp8_sdwa v[44:45], v214 src0_sel:WORD_1
	v_cvt_pk_f32_fp8_e32 v[46:47], v218
	v_cvt_pk_f32_fp8_sdwa v[48:49], v218 src0_sel:WORD_1
	v_pk_fma_f32 v[50:51], v[42:43], v[18:19], v[50:51]
	v_pk_fma_f32 v[52:53], v[46:47], v[18:19], v[52:53]
	v_pk_fma_f32 v[50:51], v[44:45], v[20:21], v[50:51]
	v_pk_fma_f32 v[52:53], v[48:49], v[20:21], v[52:53]
	v_cvt_pk_f32_fp8_e32 v[42:43], v215
	v_cvt_pk_f32_fp8_sdwa v[44:45], v215 src0_sel:WORD_1
	v_cvt_pk_f32_fp8_e32 v[46:47], v219
	v_cvt_pk_f32_fp8_sdwa v[48:49], v219 src0_sel:WORD_1
	v_pk_fma_f32 v[50:51], v[42:43], v[22:23], v[50:51]
	v_pk_fma_f32 v[52:53], v[46:47], v[22:23], v[52:53]
	v_pk_fma_f32 v[50:51], v[44:45], v[24:25], v[50:51]
	v_pk_fma_f32 v[52:53], v[48:49], v[24:25], v[52:53]
	v_add_f32_e32 v32, v50, v51
	v_add_f32_e32 v33, v52, v53
	v_cvt_pk_f32_fp8_e32 v[42:43], v220
	v_cvt_pk_f32_fp8_sdwa v[44:45], v220 src0_sel:WORD_1
	v_cvt_pk_f32_fp8_e32 v[46:47], v224
	v_cvt_pk_f32_fp8_sdwa v[48:49], v224 src0_sel:WORD_1
	v_pk_mul_f32 v[50:51], v[42:43], v[10:11]
	v_pk_mul_f32 v[52:53], v[46:47], v[10:11]
	v_pk_fma_f32 v[50:51], v[44:45], v[12:13], v[50:51]
	v_pk_fma_f32 v[52:53], v[48:49], v[12:13], v[52:53]
	v_cvt_pk_f32_fp8_e32 v[42:43], v221
	v_cvt_pk_f32_fp8_sdwa v[44:45], v221 src0_sel:WORD_1
	v_cvt_pk_f32_fp8_e32 v[46:47], v225
	v_cvt_pk_f32_fp8_sdwa v[48:49], v225 src0_sel:WORD_1
	v_pk_fma_f32 v[50:51], v[42:43], v[14:15], v[50:51]
	v_pk_fma_f32 v[52:53], v[46:47], v[14:15], v[52:53]
	v_pk_fma_f32 v[50:51], v[44:45], v[16:17], v[50:51]
	v_pk_fma_f32 v[52:53], v[48:49], v[16:17], v[52:53]
	v_cvt_pk_f32_fp8_e32 v[42:43], v222
	v_cvt_pk_f32_fp8_sdwa v[44:45], v222 src0_sel:WORD_1
	v_cvt_pk_f32_fp8_e32 v[46:47], v226
	v_cvt_pk_f32_fp8_sdwa v[48:49], v226 src0_sel:WORD_1
	v_pk_fma_f32 v[50:51], v[42:43], v[18:19], v[50:51]
	v_pk_fma_f32 v[52:53], v[46:47], v[18:19], v[52:53]
	v_pk_fma_f32 v[50:51], v[44:45], v[20:21], v[50:51]
	v_pk_fma_f32 v[52:53], v[48:49], v[20:21], v[52:53]
	v_cvt_pk_f32_fp8_e32 v[42:43], v223
	v_cvt_pk_f32_fp8_sdwa v[44:45], v223 src0_sel:WORD_1
	v_cvt_pk_f32_fp8_e32 v[46:47], v227
	v_cvt_pk_f32_fp8_sdwa v[48:49], v227 src0_sel:WORD_1
	v_pk_fma_f32 v[50:51], v[42:43], v[22:23], v[50:51]
	v_pk_fma_f32 v[52:53], v[46:47], v[22:23], v[52:53]
	v_pk_fma_f32 v[50:51], v[44:45], v[24:25], v[50:51]
	v_pk_fma_f32 v[52:53], v[48:49], v[24:25], v[52:53]
	v_add_f32_e32 v34, v50, v51
	v_add_f32_e32 v35, v52, v53
	v_cvt_pk_f32_fp8_e32 v[42:43], v228
	v_cvt_pk_f32_fp8_sdwa v[44:45], v228 src0_sel:WORD_1
	v_cvt_pk_f32_fp8_e32 v[46:47], v232
	v_cvt_pk_f32_fp8_sdwa v[48:49], v232 src0_sel:WORD_1
	v_pk_mul_f32 v[50:51], v[42:43], v[10:11]
	v_pk_mul_f32 v[52:53], v[46:47], v[10:11]
	v_pk_fma_f32 v[50:51], v[44:45], v[12:13], v[50:51]
	v_pk_fma_f32 v[52:53], v[48:49], v[12:13], v[52:53]
	v_cvt_pk_f32_fp8_e32 v[42:43], v229
	v_cvt_pk_f32_fp8_sdwa v[44:45], v229 src0_sel:WORD_1
	v_cvt_pk_f32_fp8_e32 v[46:47], v233
	v_cvt_pk_f32_fp8_sdwa v[48:49], v233 src0_sel:WORD_1
	v_pk_fma_f32 v[50:51], v[42:43], v[14:15], v[50:51]
	v_pk_fma_f32 v[52:53], v[46:47], v[14:15], v[52:53]
	v_pk_fma_f32 v[50:51], v[44:45], v[16:17], v[50:51]
	v_pk_fma_f32 v[52:53], v[48:49], v[16:17], v[52:53]
	v_cvt_pk_f32_fp8_e32 v[42:43], v230
	v_cvt_pk_f32_fp8_sdwa v[44:45], v230 src0_sel:WORD_1
	v_cvt_pk_f32_fp8_e32 v[46:47], v234
	v_cvt_pk_f32_fp8_sdwa v[48:49], v234 src0_sel:WORD_1
	v_pk_fma_f32 v[50:51], v[42:43], v[18:19], v[50:51]
	v_pk_fma_f32 v[52:53], v[46:47], v[18:19], v[52:53]
	v_pk_fma_f32 v[50:51], v[44:45], v[20:21], v[50:51]
	v_pk_fma_f32 v[52:53], v[48:49], v[20:21], v[52:53]
	v_cvt_pk_f32_fp8_e32 v[42:43], v231
	v_cvt_pk_f32_fp8_sdwa v[44:45], v231 src0_sel:WORD_1
	v_cvt_pk_f32_fp8_e32 v[46:47], v235
	v_cvt_pk_f32_fp8_sdwa v[48:49], v235 src0_sel:WORD_1
	v_pk_fma_f32 v[50:51], v[42:43], v[22:23], v[50:51]
	v_pk_fma_f32 v[52:53], v[46:47], v[22:23], v[52:53]
	v_pk_fma_f32 v[50:51], v[44:45], v[24:25], v[50:51]
	v_pk_fma_f32 v[52:53], v[48:49], v[24:25], v[52:53]
	v_add_f32_e32 v36, v50, v51
	v_add_f32_e32 v37, v52, v53
	v_cvt_pk_f32_fp8_e32 v[42:43], v236
	v_cvt_pk_f32_fp8_sdwa v[44:45], v236 src0_sel:WORD_1
	v_cvt_pk_f32_fp8_e32 v[46:47], v240
	v_cvt_pk_f32_fp8_sdwa v[48:49], v240 src0_sel:WORD_1
	v_pk_mul_f32 v[50:51], v[42:43], v[10:11]
	v_pk_mul_f32 v[52:53], v[46:47], v[10:11]
	v_pk_fma_f32 v[50:51], v[44:45], v[12:13], v[50:51]
	v_pk_fma_f32 v[52:53], v[48:49], v[12:13], v[52:53]
	v_cvt_pk_f32_fp8_e32 v[42:43], v237
	v_cvt_pk_f32_fp8_sdwa v[44:45], v237 src0_sel:WORD_1
	v_cvt_pk_f32_fp8_e32 v[46:47], v241
	v_cvt_pk_f32_fp8_sdwa v[48:49], v241 src0_sel:WORD_1
	v_pk_fma_f32 v[50:51], v[42:43], v[14:15], v[50:51]
	v_pk_fma_f32 v[52:53], v[46:47], v[14:15], v[52:53]
	v_pk_fma_f32 v[50:51], v[44:45], v[16:17], v[50:51]
	v_pk_fma_f32 v[52:53], v[48:49], v[16:17], v[52:53]
	v_cvt_pk_f32_fp8_e32 v[42:43], v238
	v_cvt_pk_f32_fp8_sdwa v[44:45], v238 src0_sel:WORD_1
	v_cvt_pk_f32_fp8_e32 v[46:47], v242
	v_cvt_pk_f32_fp8_sdwa v[48:49], v242 src0_sel:WORD_1
	v_pk_fma_f32 v[50:51], v[42:43], v[18:19], v[50:51]
	v_pk_fma_f32 v[52:53], v[46:47], v[18:19], v[52:53]
	v_pk_fma_f32 v[50:51], v[44:45], v[20:21], v[50:51]
	v_pk_fma_f32 v[52:53], v[48:49], v[20:21], v[52:53]
	v_cvt_pk_f32_fp8_e32 v[42:43], v239
	v_cvt_pk_f32_fp8_sdwa v[44:45], v239 src0_sel:WORD_1
	v_cvt_pk_f32_fp8_e32 v[46:47], v243
	v_cvt_pk_f32_fp8_sdwa v[48:49], v243 src0_sel:WORD_1
	v_pk_fma_f32 v[50:51], v[42:43], v[22:23], v[50:51]
	v_pk_fma_f32 v[52:53], v[46:47], v[22:23], v[52:53]
	v_pk_fma_f32 v[50:51], v[44:45], v[24:25], v[50:51]
	v_pk_fma_f32 v[52:53], v[48:49], v[24:25], v[52:53]
	v_add_f32_e32 v38, v50, v51
	v_add_f32_e32 v39, v52, v53
	v_cvt_pk_f32_fp8_e32 v[42:43], v244
	v_cvt_pk_f32_fp8_sdwa v[44:45], v244 src0_sel:WORD_1
	v_cvt_pk_f32_fp8_e32 v[46:47], v248
	v_cvt_pk_f32_fp8_sdwa v[48:49], v248 src0_sel:WORD_1
	v_pk_mul_f32 v[50:51], v[42:43], v[10:11]
	v_pk_mul_f32 v[52:53], v[46:47], v[10:11]
	v_pk_fma_f32 v[50:51], v[44:45], v[12:13], v[50:51]
	v_pk_fma_f32 v[52:53], v[48:49], v[12:13], v[52:53]
	v_cvt_pk_f32_fp8_e32 v[42:43], v245
	v_cvt_pk_f32_fp8_sdwa v[44:45], v245 src0_sel:WORD_1
	v_cvt_pk_f32_fp8_e32 v[46:47], v249
	v_cvt_pk_f32_fp8_sdwa v[48:49], v249 src0_sel:WORD_1
	v_pk_fma_f32 v[50:51], v[42:43], v[14:15], v[50:51]
	v_pk_fma_f32 v[52:53], v[46:47], v[14:15], v[52:53]
	v_pk_fma_f32 v[50:51], v[44:45], v[16:17], v[50:51]
	v_pk_fma_f32 v[52:53], v[48:49], v[16:17], v[52:53]
	v_cvt_pk_f32_fp8_e32 v[42:43], v246
	v_cvt_pk_f32_fp8_sdwa v[44:45], v246 src0_sel:WORD_1
	v_cvt_pk_f32_fp8_e32 v[46:47], v250
	v_cvt_pk_f32_fp8_sdwa v[48:49], v250 src0_sel:WORD_1
	v_pk_fma_f32 v[50:51], v[42:43], v[18:19], v[50:51]
	v_pk_fma_f32 v[52:53], v[46:47], v[18:19], v[52:53]
	v_pk_fma_f32 v[50:51], v[44:45], v[20:21], v[50:51]
	v_pk_fma_f32 v[52:53], v[48:49], v[20:21], v[52:53]
	v_cvt_pk_f32_fp8_e32 v[42:43], v247
	v_cvt_pk_f32_fp8_sdwa v[44:45], v247 src0_sel:WORD_1
	v_cvt_pk_f32_fp8_e32 v[46:47], v251
	v_cvt_pk_f32_fp8_sdwa v[48:49], v251 src0_sel:WORD_1
	v_pk_fma_f32 v[50:51], v[42:43], v[22:23], v[50:51]
	v_pk_fma_f32 v[52:53], v[46:47], v[22:23], v[52:53]
	v_pk_fma_f32 v[50:51], v[44:45], v[24:25], v[50:51]
	v_pk_fma_f32 v[52:53], v[48:49], v[24:25], v[52:53]
	v_add_f32_e32 v40, v50, v51
	v_add_f32_e32 v41, v52, v53
	s_lshl_b32 s11, s12, 12
	v_add_u32_e32 v6, s11, v3
	v_add_f32_dpp v42, v26, v26 row_half_mirror row_mask:0xf bank_mask:0xf
	v_add_f32_dpp v43, v34, v34 row_half_mirror row_mask:0xf bank_mask:0xf
	v_cndmask_b32_e64 v26, v42, v43, s[14:15]
	v_add_f32_dpp v44, v27, v27 row_half_mirror row_mask:0xf bank_mask:0xf
	v_add_f32_dpp v45, v35, v35 row_half_mirror row_mask:0xf bank_mask:0xf
	v_cndmask_b32_e64 v27, v44, v45, s[14:15]
	v_add_f32_dpp v42, v28, v28 row_half_mirror row_mask:0xf bank_mask:0xf
	v_add_f32_dpp v43, v36, v36 row_half_mirror row_mask:0xf bank_mask:0xf
	v_cndmask_b32_e64 v28, v42, v43, s[14:15]
	v_add_f32_dpp v44, v29, v29 row_half_mirror row_mask:0xf bank_mask:0xf
	v_add_f32_dpp v45, v37, v37 row_half_mirror row_mask:0xf bank_mask:0xf
	v_cndmask_b32_e64 v29, v44, v45, s[14:15]
	v_add_f32_dpp v42, v30, v30 row_half_mirror row_mask:0xf bank_mask:0xf
	v_add_f32_dpp v43, v38, v38 row_half_mirror row_mask:0xf bank_mask:0xf
	v_cndmask_b32_e64 v30, v42, v43, s[14:15]
	v_add_f32_dpp v44, v31, v31 row_half_mirror row_mask:0xf bank_mask:0xf
	v_add_f32_dpp v45, v39, v39 row_half_mirror row_mask:0xf bank_mask:0xf
	v_cndmask_b32_e64 v31, v44, v45, s[14:15]
	v_add_f32_dpp v42, v32, v32 row_half_mirror row_mask:0xf bank_mask:0xf
	v_add_f32_dpp v43, v40, v40 row_half_mirror row_mask:0xf bank_mask:0xf
	v_cndmask_b32_e64 v32, v42, v43, s[14:15]
	v_add_f32_dpp v44, v33, v33 row_half_mirror row_mask:0xf bank_mask:0xf
	v_add_f32_dpp v45, v41, v41 row_half_mirror row_mask:0xf bank_mask:0xf
	v_cndmask_b32_e64 v33, v44, v45, s[14:15]
	s_nop 1
	v_add_f32_dpp v42, v26, v26 quad_perm:[2,3,0,1] row_mask:0xf bank_mask:0xf
	v_add_f32_dpp v43, v30, v30 quad_perm:[2,3,0,1] row_mask:0xf bank_mask:0xf
	v_cndmask_b32_e64 v26, v42, v43, s[40:41]
	v_add_f32_dpp v44, v27, v27 quad_perm:[2,3,0,1] row_mask:0xf bank_mask:0xf
	v_add_f32_dpp v45, v31, v31 quad_perm:[2,3,0,1] row_mask:0xf bank_mask:0xf
	v_cndmask_b32_e64 v27, v44, v45, s[40:41]
	v_add_f32_dpp v42, v28, v28 quad_perm:[2,3,0,1] row_mask:0xf bank_mask:0xf
	v_add_f32_dpp v43, v32, v32 quad_perm:[2,3,0,1] row_mask:0xf bank_mask:0xf
	v_cndmask_b32_e64 v28, v42, v43, s[40:41]
	v_add_f32_dpp v44, v29, v29 quad_perm:[2,3,0,1] row_mask:0xf bank_mask:0xf
	v_add_f32_dpp v45, v33, v33 quad_perm:[2,3,0,1] row_mask:0xf bank_mask:0xf
	v_cndmask_b32_e64 v29, v44, v45, s[40:41]
	s_nop 1
	v_add_f32_dpp v42, v26, v26 quad_perm:[1,0,3,2] row_mask:0xf bank_mask:0xf
	v_add_f32_dpp v43, v28, v28 quad_perm:[1,0,3,2] row_mask:0xf bank_mask:0xf
	v_cndmask_b32_e64 v26, v42, v43, s[42:43]
	v_add_f32_dpp v44, v27, v27 quad_perm:[1,0,3,2] row_mask:0xf bank_mask:0xf
	v_add_f32_dpp v45, v29, v29 quad_perm:[1,0,3,2] row_mask:0xf bank_mask:0xf
	v_cndmask_b32_e64 v27, v44, v45, s[42:43]
	s_nop 1
	v_mul_f32_e32 v26, v26, v56
	v_mul_f32_e32 v27, v27, v56
	global_store_dwordx2 v6, v[26:27], s[6:7]

; #define P5_LOAD(A, TAB, j0)                                                                \
;   _Pragma("unroll") for (int q = 0; q < 16; q++) {                                         \
;     A[q] = ((const uint4*)((TAB) + (size_t)widx[(j0) + q] * 1024))[lane];                  \
;   }
; __device__ __forceinline__ void phase5(const Params& p, char* smem, const bool store_x = true) {
;     ...
; #pragma unroll 1
;     for (int j0 = 0; j0 < 128; j0 += 32) {
;       P5_LOAD(A1, EV, j0 + 16)
;       P5_COMPUTE_V(A0, j0)
;       if (j0 + 32 < 128) { P5_LOAD(A0, EV, j0 + 32) }
;       P5_COMPUTE_V(A1, j0 + 16)
;     }
.Lp5v_loop:
	s_add_u32 s11, s16, 2
	s_and_b32 s11, s11, 7
	s_lshl_b32 s11, s11, 10
	v_add_u32_e32 v8, s11, v2
	ds_read_b128 v[10:13], v8 offset:0
	ds_read_b128 v[14:17], v8 offset:16
	ds_read_b128 v[18:21], v8 offset:32
	ds_read_b128 v[22:25], v8 offset:48
	s_add_u32 s10, s8, s25
	s_min_u32 s10, s10, s13
	s_lshl_b32 s18, s10, 10
	s_add_u32 s11, s16, 6
	s_and_b32 s11, s11, 7
	s_lshl_b32 s11, s11, 10
	s_add_u32 s11, s11, s17
	s_mov_b32 m0, s11
	v_lshl_add_u64 v[4:5], v[58:59], 0, s[18:19]
	global_load_lds_dwordx4 v[4:5], off
	s_add_u32 s10, s8, s21
	s_min_u32 s10, s10, s13
	s_lshl_b32 s11, s10, 12
	v_add_u32_e32 v6, s11, v3
	global_load_dwordx2 v[54:55], v6, s[6:7]
	s_waitcnt lgkmcnt(0)
	v_add_u32_e32 v10, v10, v1
	global_load_dwordx4 v[188:191], v10, s[2:3]
	v_add_u32_e32 v11, v11, v1
	global_load_dwordx4 v[192:195], v11, s[2:3]
	v_add_u32_e32 v12, v12, v1
	global_load_dwordx4 v[196:199], v12, s[2:3]
	v_add_u32_e32 v13, v13, v1
	global_load_dwordx4 v[200:203], v13, s[2:3]
	v_add_u32_e32 v14, v14, v1
	global_load_dwordx4 v[204:207], v14, s[2:3]
	v_add_u32_e32 v15, v15, v1
	global_load_dwordx4 v[208:211], v15, s[2:3]
	v_add_u32_e32 v16, v16, v1
	global_load_dwordx4 v[212:215], v16, s[2:3]
	v_add_u32_e32 v17, v17, v1
	global_load_dwordx4 v[216:219], v17, s[2:3]
	v_add_u32_e32 v18, v18, v1
	global_load_dwordx4 v[220:223], v18, s[2:3]
	v_add_u32_e32 v19, v19, v1
	global_load_dwordx4 v[224:227], v19, s[2:3]
	v_add_u32_e32 v20, v20, v1
	global_load_dwordx4 v[228:231], v20, s[2:3]
	v_add_u32_e32 v21, v21, v1
	global_load_dwordx4 v[232:235], v21, s[2:3]
	v_add_u32_e32 v22, v22, v1
	global_load_dwordx4 v[236:239], v22, s[2:3]
	v_add_u32_e32 v23, v23, v1
	global_load_dwordx4 v[240:243], v23, s[2:3]
	v_add_u32_e32 v24, v24, v1
	global_load_dwordx4 v[244:247], v24, s[2:3]
	v_add_u32_e32 v25, v25, v1
	global_load_dwordx4 v[248:251], v25, s[2:3]
	s_add_u32 s11, s16, 0
	s_and_b32 s11, s11, 7
	s_lshl_b32 s11, s11, 10
	v_add_u32_e32 v8, s11, v2
	ds_read_b128 v[10:13], v8 offset:512
	ds_read_b128 v[14:17], v8 offset:528
	ds_read_b128 v[18:21], v8 offset:544
	ds_read_b128 v[22:25], v8 offset:560
	s_mov_b32 s12, s8
	s_waitcnt vmcnt(42) lgkmcnt(0)
	s_cmp_lt_u32 s12, 0x4200
	s_cbranch_scc0 .Lp5v_skip0
	v_cvt_pk_f32_fp8_e32 v[42:43], v60
	v_cvt_pk_f32_fp8_sdwa v[44:45], v60 src0_sel:WORD_1
	v_pk_mul_f32 v[26:27], v[42:43], v[10:11] op_sel_hi:[1,0]
	v_pk_mul_f32 v[28:29], v[44:45], v[10:11] op_sel_hi:[1,0]
	v_cvt_pk_f32_fp8_e32 v[46:47], v61
	v_cvt_pk_f32_fp8_sdwa v[48:49], v61 src0_sel:WORD_1
	v_pk_mul_f32 v[30:31], v[46:47], v[10:11] op_sel_hi:[1,0]
	v_pk_mul_f32 v[32:33], v[48:49], v[10:11] op_sel_hi:[1,0]
	v_cvt_pk_f32_fp8_e32 v[42:43], v62
	v_cvt_pk_f32_fp8_sdwa v[44:45], v62 src0_sel:WORD_1
	v_pk_mul_f32 v[34:35], v[42:43], v[10:11] op_sel_hi:[1,0]
	v_pk_mul_f32 v[36:37], v[44:45], v[10:11] op_sel_hi:[1,0]
	v_cvt_pk_f32_fp8_e32 v[46:47], v63
	v_cvt_pk_f32_fp8_sdwa v[48:49], v63 src0_sel:WORD_1
	v_pk_mul_f32 v[38:39], v[46:47], v[10:11] op_sel_hi:[1,0]
	v_pk_mul_f32 v[40:41], v[48:49], v[10:11] op_sel_hi:[1,0]
	v_cvt_pk_f32_fp8_e32 v[42:43], v64
	v_cvt_pk_f32_fp8_sdwa v[44:45], v64 src0_sel:WORD_1
	v_pk_fma_f32 v[26:27], v[42:43], v[10:11], v[26:27] op_sel:[0,1,0] op_sel_hi:[1,1,1]
	v_pk_fma_f32 v[28:29], v[44:45], v[10:11], v[28:29] op_sel:[0,1,0] op_sel_hi:[1,1,1]
	v_cvt_pk_f32_fp8_e32 v[46:47], v65
	v_cvt_pk_f32_fp8_sdwa v[48:49], v65 src0_sel:WORD_1
	v_pk_fma_f32 v[30:31], v[46:47], v[10:11], v[30:31] op_sel:[0,1,0] op_sel_hi:[1,1,1]
	v_pk_fma_f32 v[32:33], v[48:49], v[10:11], v[32:33] op_sel:[0,1,0] op_sel_hi:[1,1,1]
	v_cvt_pk_f32_fp8_e32 v[42:43], v66
	v_cvt_pk_f32_fp8_sdwa v[44:45], v66 src0_sel:WORD_1
	v_pk_fma_f32 v[34:35], v[42:43], v[10:11], v[34:35] op_sel:[0,1,0] op_sel_hi:[1,1,1]
	v_pk_fma_f32 v[36:37], v[44:45], v[10:11], v[36:37] op_sel:[0,1,0] op_sel_hi:[1,1,1]
	v_cvt_pk_f32_fp8_e32 v[46:47], v67
	v_cvt_pk_f32_fp8_sdwa v[48:49], v67 src0_sel:WORD_1
	v_pk_fma_f32 v[38:39], v[46:47], v[10:11], v[38:39] op_sel:[0,1,0] op_sel_hi:[1,1,1]
	v_pk_fma_f32 v[40:41], v[48:49], v[10:11], v[40:41] op_sel:[0,1,0] op_sel_hi:[1,1,1]
	v_cvt_pk_f32_fp8_e32 v[42:43], v68
	v_cvt_pk_f32_fp8_sdwa v[44:45], v68 src0_sel:WORD_1
	v_pk_fma_f32 v[26:27], v[42:43], v[12:13], v[26:27] op_sel_hi:[1,0,1]
	v_pk_fma_f32 v[28:29], v[44:45], v[12:13], v[28:29] op_sel_hi:[1,0,1]
	v_cvt_pk_f32_fp8_e32 v[46:47], v69
	v_cvt_pk_f32_fp8_sdwa v[48:49], v69 src0_sel:WORD_1
	v_pk_fma_f32 v[30:31], v[46:47], v[12:13], v[30:31] op_sel_hi:[1,0,1]
	v_pk_fma_f32 v[32:33], v[48:49], v[12:13], v[32:33] op_sel_hi:[1,0,1]
	v_cvt_pk_f32_fp8_e32 v[42:43], v70
	v_cvt_pk_f32_fp8_sdwa v[44:45], v70 src0_sel:WORD_1
	v_pk_fma_f32 v[34:35], v[42:43], v[12:13], v[34:35] op_sel_hi:[1,0,1]
	v_pk_fma_f32 v[36:37], v[44:45], v[12:13], v[36:37] op_sel_hi:[1,0,1]
	v_cvt_pk_f32_fp8_e32 v[46:47], v71
	v_cvt_pk_f32_fp8_sdwa v[48:49], v71 src0_sel:WORD_1
	v_pk_fma_f32 v[38:39], v[46:47], v[12:13], v[38:39] op_sel_hi:[1,0,1]
	v_pk_fma_f32 v[40:41], v[48:49], v[12:13], v[40:41] op_sel_hi:[1,0,1]
	v_cvt_pk_f32_fp8_e32 v[42:43], v72
	v_cvt_pk_f32_fp8_sdwa v[44:45], v72 src0_sel:WORD_1
	v_pk_fma_f32 v[26:27], v[42:43], v[12:13], v[26:27] op_sel:[0,1,0] op_sel_hi:[1,1,1]
	v_pk_fma_f32 v[28:29], v[44:45], v[12:13], v[28:29] op_sel:[0,1,0] op_sel_hi:[1,1,1]
	v_cvt_pk_f32_fp8_e32 v[46:47], v73
	v_cvt_pk_f32_fp8_sdwa v[48:49], v73 src0_sel:WORD_1
	v_pk_fma_f32 v[30:31], v[46:47], v[12:13], v[30:31] op_sel:[0,1,0] op_sel_hi:[1,1,1]
	v_pk_fma_f32 v[32:33], v[48:49], v[12:13], v[32:33] op_sel:[0,1,0] op_sel_hi:[1,1,1]
	v_cvt_pk_f32_fp8_e32 v[42:43], v74
	v_cvt_pk_f32_fp8_sdwa v[44:45], v74 src0_sel:WORD_1
; #define P5_LOAD(A, TAB, j0)                                                                \
;   _Pragma("unroll") for (int q = 0; q < 16; q++) {                                         \
;     A[q] = ((const uint4*)((TAB) + (size_t)widx[(j0) + q] * 1024))[lane];                  \
;   }
; __device__ __forceinline__ void phase5(const Params& p, char* smem, const bool store_x = true) {
;     ...
; #pragma unroll 1
;     for (int j0 = 0; j0 < 128; j0 += 32) {
;       P5_LOAD(A1, EV, j0 + 16)
;       P5_COMPUTE_V(A0, j0)
;       if (j0 + 32 < 128) { P5_LOAD(A0, EV, j0 + 32) }
;       P5_COMPUTE_V(A1, j0 + 16)
;     }
	v_pk_fma_f32 v[34:35], v[42:43], v[12:13], v[34:35] op_sel:[0,1,0] op_sel_hi:[1,1,1]
	v_pk_fma_f32 v[36:37], v[44:45], v[12:13], v[36:37] op_sel:[0,1,0] op_sel_hi:[1,1,1]
	v_cvt_pk_f32_fp8_e32 v[46:47], v75
	v_cvt_pk_f32_fp8_sdwa v[48:49], v75 src0_sel:WORD_1
	v_pk_fma_f32 v[38:39], v[46:47], v[12:13], v[38:39] op_sel:[0,1,0] op_sel_hi:[1,1,1]
	v_pk_fma_f32 v[40:41], v[48:49], v[12:13], v[40:41] op_sel:[0,1,0] op_sel_hi:[1,1,1]
	v_cvt_pk_f32_fp8_e32 v[42:43], v76
	v_cvt_pk_f32_fp8_sdwa v[44:45], v76 src0_sel:WORD_1
	v_pk_fma_f32 v[26:27], v[42:43], v[14:15], v[26:27] op_sel_hi:[1,0,1]
	v_pk_fma_f32 v[28:29], v[44:45], v[14:15], v[28:29] op_sel_hi:[1,0,1]
	v_cvt_pk_f32_fp8_e32 v[46:47], v77
	v_cvt_pk_f32_fp8_sdwa v[48:49], v77 src0_sel:WORD_1
	v_pk_fma_f32 v[30:31], v[46:47], v[14:15], v[30:31] op_sel_hi:[1,0,1]
	v_pk_fma_f32 v[32:33], v[48:49], v[14:15], v[32:33] op_sel_hi:[1,0,1]
	v_cvt_pk_f32_fp8_e32 v[42:43], v78
	v_cvt_pk_f32_fp8_sdwa v[44:45], v78 src0_sel:WORD_1
	v_pk_fma_f32 v[34:35], v[42:43], v[14:15], v[34:35] op_sel_hi:[1,0,1]
	v_pk_fma_f32 v[36:37], v[44:45], v[14:15], v[36:37] op_sel_hi:[1,0,1]
	v_cvt_pk_f32_fp8_e32 v[46:47], v79
	v_cvt_pk_f32_fp8_sdwa v[48:49], v79 src0_sel:WORD_1
	v_pk_fma_f32 v[38:39], v[46:47], v[14:15], v[38:39] op_sel_hi:[1,0,1]
	v_pk_fma_f32 v[40:41], v[48:49], v[14:15], v[40:41] op_sel_hi:[1,0,1]
	v_cvt_pk_f32_fp8_e32 v[42:43], v80
	v_cvt_pk_f32_fp8_sdwa v[44:45], v80 src0_sel:WORD_1
	v_pk_fma_f32 v[26:27], v[42:43], v[14:15], v[26:27] op_sel:[0,1,0] op_sel_hi:[1,1,1]
	v_pk_fma_f32 v[28:29], v[44:45], v[14:15], v[28:29] op_sel:[0,1,0] op_sel_hi:[1,1,1]
	v_cvt_pk_f32_fp8_e32 v[46:47], v81
	v_cvt_pk_f32_fp8_sdwa v[48:49], v81 src0_sel:WORD_1
	v_pk_fma_f32 v[30:31], v[46:47], v[14:15], v[30:31] op_sel:[0,1,0] op_sel_hi:[1,1,1]
	v_pk_fma_f32 v[32:33], v[48:49], v[14:15], v[32:33] op_sel:[0,1,0] op_sel_hi:[1,1,1]
	v_cvt_pk_f32_fp8_e32 v[42:43], v82
	v_cvt_pk_f32_fp8_sdwa v[44:45], v82 src0_sel:WORD_1
	v_pk_fma_f32 v[34:35], v[42:43], v[14:15], v[34:35] op_sel:[0,1,0] op_sel_hi:[1,1,1]
	v_pk_fma_f32 v[36:37], v[44:45], v[14:15], v[36:37] op_sel:[0,1,0] op_sel_hi:[1,1,1]
	v_cvt_pk_f32_fp8_e32 v[46:47], v83
	v_cvt_pk_f32_fp8_sdwa v[48:49], v83 src0_sel:WORD_1
	v_pk_fma_f32 v[38:39], v[46:47], v[14:15], v[38:39] op_sel:[0,1,0] op_sel_hi:[1,1,1]
	v_pk_fma_f32 v[40:41], v[48:49], v[14:15], v[40:41] op_sel:[0,1,0] op_sel_hi:[1,1,1]
	v_cvt_pk_f32_fp8_e32 v[42:43], v84
	v_cvt_pk_f32_fp8_sdwa v[44:45], v84 src0_sel:WORD_1
	v_pk_fma_f32 v[26:27], v[42:43], v[16:17], v[26:27] op_sel_hi:[1,0,1]
	v_pk_fma_f32 v[28:29], v[44:45], v[16:17], v[28:29] op_sel_hi:[1,0,1]
	v_cvt_pk_f32_fp8_e32 v[46:47], v85
	v_cvt_pk_f32_fp8_sdwa v[48:49], v85 src0_sel:WORD_1
	v_pk_fma_f32 v[30:31], v[46:47], v[16:17], v[30:31] op_sel_hi:[1,0,1]
	v_pk_fma_f32 v[32:33], v[48:49], v[16:17], v[32:33] op_sel_hi:[1,0,1]
	v_cvt_pk_f32_fp8_e32 v[42:43], v86
	v_cvt_pk_f32_fp8_sdwa v[44:45], v86 src0_sel:WORD_1
	v_pk_fma_f32 v[34:35], v[42:43], v[16:17], v[34:35] op_sel_hi:[1,0,1]
	v_pk_fma_f32 v[36:37], v[44:45], v[16:17], v[36:37] op_sel_hi:[1,0,1]
	v_cvt_pk_f32_fp8_e32 v[46:47], v87
	v_cvt_pk_f32_fp8_sdwa v[48:49], v87 src0_sel:WORD_1
	v_pk_fma_f32 v[38:39], v[46:47], v[16:17], v[38:39] op_sel_hi:[1,0,1]
	v_pk_fma_f32 v[40:41], v[48:49], v[16:17], v[40:41] op_sel_hi:[1,0,1]
	v_cvt_pk_f32_fp8_e32 v[42:43], v88
	v_cvt_pk_f32_fp8_sdwa v[44:45], v88 src0_sel:WORD_1
	v_pk_fma_f32 v[26:27], v[42:43], v[16:17], v[26:27] op_sel:[0,1,0] op_sel_hi:[1,1,1]
	v_pk_fma_f32 v[28:29], v[44:45], v[16:17], v[28:29] op_sel:[0,1,0] op_sel_hi:[1,1,1]
	v_cvt_pk_f32_fp8_e32 v[46:47], v89
	v_cvt_pk_f32_fp8_sdwa v[48:49], v89 src0_sel:WORD_1
	v_pk_fma_f32 v[30:31], v[46:47], v[16:17], v[30:31] op_sel:[0,1,0] op_sel_hi:[1,1,1]
	v_pk_fma_f32 v[32:33], v[48:49], v[16:17], v[32:33] op_sel:[0,1,0] op_sel_hi:[1,1,1]
	v_cvt_pk_f32_fp8_e32 v[42:43], v90
	v_cvt_pk_f32_fp8_sdwa v[44:45], v90 src0_sel:WORD_1
	v_pk_fma_f32 v[34:35], v[42:43], v[16:17], v[34:35] op_sel:[0,1,0] op_sel_hi:[1,1,1]
	v_pk_fma_f32 v[36:37], v[44:45], v[16:17], v[36:37] op_sel:[0,1,0] op_sel_hi:[1,1,1]
	v_cvt_pk_f32_fp8_e32 v[46:47], v91
	v_cvt_pk_f32_fp8_sdwa v[48:49], v91 src0_sel:WORD_1
	v_pk_fma_f32 v[38:39], v[46:47], v[16:17], v[38:39] op_sel:[0,1,0] op_sel_hi:[1,1,1]
	v_pk_fma_f32 v[40:41], v[48:49], v[16:17], v[40:41] op_sel:[0,1,0] op_sel_hi:[1,1,1]
	v_cvt_pk_f32_fp8_e32 v[42:43], v92
	v_cvt_pk_f32_fp8_sdwa v[44:45], v92 src0_sel:WORD_1
	v_pk_fma_f32 v[26:27], v[42:43], v[18:19], v[26:27] op_sel_hi:[1,0,1]
	v_pk_fma_f32 v[28:29], v[44:45], v[18:19], v[28:29] op_sel_hi:[1,0,1]
	v_cvt_pk_f32_fp8_e32 v[46:47], v93
	v_cvt_pk_f32_fp8_sdwa v[48:49], v93 src0_sel:WORD_1
	v_pk_fma_f32 v[30:31], v[46:47], v[18:19], v[30:31] op_sel_hi:[1,0,1]
	v_pk_fma_f32 v[32:33], v[48:49], v[18:19], v[32:33] op_sel_hi:[1,0,1]
	v_cvt_pk_f32_fp8_e32 v[42:43], v94
	v_cvt_pk_f32_fp8_sdwa v[44:45], v94 src0_sel:WORD_1
	v_pk_fma_f32 v[34:35], v[42:43], v[18:19], v[34:35] op_sel_hi:[1,0,1]
	v_pk_fma_f32 v[36:37], v[44:45], v[18:19], v[36:37] op_sel_hi:[1,0,1]
	v_cvt_pk_f32_fp8_e32 v[46:47], v95
	v_cvt_pk_f32_fp8_sdwa v[48:49], v95 src0_sel:WORD_1
	v_pk_fma_f32 v[38:39], v[46:47], v[18:19], v[38:39] op_sel_hi:[1,0,1]
	v_pk_fma_f32 v[40:41], v[48:49], v[18:19], v[40:41] op_sel_hi:[1,0,1]
	v_cvt_pk_f32_fp8_e32 v[42:43], v96
	v_cvt_pk_f32_fp8_sdwa v[44:45], v96 src0_sel:WORD_1
	v_pk_fma_f32 v[26:27], v[42:43], v[18:19], v[26:27] op_sel:[0,1,0] op_sel_hi:[1,1,1]
	v_pk_fma_f32 v[28:29], v[44:45], v[18:19], v[28:29] op_sel:[0,1,0] op_sel_hi:[1,1,1]
	v_cvt_pk_f32_fp8_e32 v[46:47], v97
	v_cvt_pk_f32_fp8_sdwa v[48:49], v97 src0_sel:WORD_1
; #define P5_LOAD(A, TAB, j0)                                                                \
;   _Pragma("unroll") for (int q = 0; q < 16; q++) {                                         \
;     A[q] = ((const uint4*)((TAB) + (size_t)widx[(j0) + q] * 1024))[lane];                  \
;   }
; __device__ __forceinline__ void phase5(const Params& p, char* smem, const bool store_x = true) {
;     ...
; #pragma unroll 1
;     for (int j0 = 0; j0 < 128; j0 += 32) {
;       P5_LOAD(A1, EV, j0 + 16)
;       P5_COMPUTE_V(A0, j0)
;       if (j0 + 32 < 128) { P5_LOAD(A0, EV, j0 + 32) }
;       P5_COMPUTE_V(A1, j0 + 16)
;     }
	v_pk_fma_f32 v[30:31], v[46:47], v[18:19], v[30:31] op_sel:[0,1,0] op_sel_hi:[1,1,1]
	v_pk_fma_f32 v[32:33], v[48:49], v[18:19], v[32:33] op_sel:[0,1,0] op_sel_hi:[1,1,1]
	v_cvt_pk_f32_fp8_e32 v[42:43], v98
	v_cvt_pk_f32_fp8_sdwa v[44:45], v98 src0_sel:WORD_1
	v_pk_fma_f32 v[34:35], v[42:43], v[18:19], v[34:35] op_sel:[0,1,0] op_sel_hi:[1,1,1]
	v_pk_fma_f32 v[36:37], v[44:45], v[18:19], v[36:37] op_sel:[0,1,0] op_sel_hi:[1,1,1]
	v_cvt_pk_f32_fp8_e32 v[46:47], v99
	v_cvt_pk_f32_fp8_sdwa v[48:49], v99 src0_sel:WORD_1
	v_pk_fma_f32 v[38:39], v[46:47], v[18:19], v[38:39] op_sel:[0,1,0] op_sel_hi:[1,1,1]
	v_pk_fma_f32 v[40:41], v[48:49], v[18:19], v[40:41] op_sel:[0,1,0] op_sel_hi:[1,1,1]
	v_cvt_pk_f32_fp8_e32 v[42:43], v100
	v_cvt_pk_f32_fp8_sdwa v[44:45], v100 src0_sel:WORD_1
	v_pk_fma_f32 v[26:27], v[42:43], v[20:21], v[26:27] op_sel_hi:[1,0,1]
	v_pk_fma_f32 v[28:29], v[44:45], v[20:21], v[28:29] op_sel_hi:[1,0,1]
	v_cvt_pk_f32_fp8_e32 v[46:47], v101
	v_cvt_pk_f32_fp8_sdwa v[48:49], v101 src0_sel:WORD_1
	v_pk_fma_f32 v[30:31], v[46:47], v[20:21], v[30:31] op_sel_hi:[1,0,1]
	v_pk_fma_f32 v[32:33], v[48:49], v[20:21], v[32:33] op_sel_hi:[1,0,1]
	v_cvt_pk_f32_fp8_e32 v[42:43], v102
	v_cvt_pk_f32_fp8_sdwa v[44:45], v102 src0_sel:WORD_1
	v_pk_fma_f32 v[34:35], v[42:43], v[20:21], v[34:35] op_sel_hi:[1,0,1]
	v_pk_fma_f32 v[36:37], v[44:45], v[20:21], v[36:37] op_sel_hi:[1,0,1]
	v_cvt_pk_f32_fp8_e32 v[46:47], v103
	v_cvt_pk_f32_fp8_sdwa v[48:49], v103 src0_sel:WORD_1
	v_pk_fma_f32 v[38:39], v[46:47], v[20:21], v[38:39] op_sel_hi:[1,0,1]
	v_pk_fma_f32 v[40:41], v[48:49], v[20:21], v[40:41] op_sel_hi:[1,0,1]
	v_cvt_pk_f32_fp8_e32 v[42:43], v104
	v_cvt_pk_f32_fp8_sdwa v[44:45], v104 src0_sel:WORD_1
	v_pk_fma_f32 v[26:27], v[42:43], v[20:21], v[26:27] op_sel:[0,1,0] op_sel_hi:[1,1,1]
	v_pk_fma_f32 v[28:29], v[44:45], v[20:21], v[28:29] op_sel:[0,1,0] op_sel_hi:[1,1,1]
	v_cvt_pk_f32_fp8_e32 v[46:47], v105
	v_cvt_pk_f32_fp8_sdwa v[48:49], v105 src0_sel:WORD_1
	v_pk_fma_f32 v[30:31], v[46:47], v[20:21], v[30:31] op_sel:[0,1,0] op_sel_hi:[1,1,1]
	v_pk_fma_f32 v[32:33], v[48:49], v[20:21], v[32:33] op_sel:[0,1,0] op_sel_hi:[1,1,1]
	v_cvt_pk_f32_fp8_e32 v[42:43], v106
	v_cvt_pk_f32_fp8_sdwa v[44:45], v106 src0_sel:WORD_1
	v_pk_fma_f32 v[34:35], v[42:43], v[20:21], v[34:35] op_sel:[0,1,0] op_sel_hi:[1,1,1]
	v_pk_fma_f32 v[36:37], v[44:45], v[20:21], v[36:37] op_sel:[0,1,0] op_sel_hi:[1,1,1]
	v_cvt_pk_f32_fp8_e32 v[46:47], v107
	v_cvt_pk_f32_fp8_sdwa v[48:49], v107 src0_sel:WORD_1
	v_pk_fma_f32 v[38:39], v[46:47], v[20:21], v[38:39] op_sel:[0,1,0] op_sel_hi:[1,1,1]
	v_pk_fma_f32 v[40:41], v[48:49], v[20:21], v[40:41] op_sel:[0,1,0] op_sel_hi:[1,1,1]
	v_cvt_pk_f32_fp8_e32 v[42:43], v108
	v_cvt_pk_f32_fp8_sdwa v[44:45], v108 src0_sel:WORD_1
	v_pk_fma_f32 v[26:27], v[42:43], v[22:23], v[26:27] op_sel_hi:[1,0,1]
	v_pk_fma_f32 v[28:29], v[44:45], v[22:23], v[28:29] op_sel_hi:[1,0,1]
	v_cvt_pk_f32_fp8_e32 v[46:47], v109
	v_cvt_pk_f32_fp8_sdwa v[48:49], v109 src0_sel:WORD_1
	v_pk_fma_f32 v[30:31], v[46:47], v[22:23], v[30:31] op_sel_hi:[1,0,1]
	v_pk_fma_f32 v[32:33], v[48:49], v[22:23], v[32:33] op_sel_hi:[1,0,1]
	v_cvt_pk_f32_fp8_e32 v[42:43], v110
	v_cvt_pk_f32_fp8_sdwa v[44:45], v110 src0_sel:WORD_1
	v_pk_fma_f32 v[34:35], v[42:43], v[22:23], v[34:35] op_sel_hi:[1,0,1]
	v_pk_fma_f32 v[36:37], v[44:45], v[22:23], v[36:37] op_sel_hi:[1,0,1]
	v_cvt_pk_f32_fp8_e32 v[46:47], v111
	v_cvt_pk_f32_fp8_sdwa v[48:49], v111 src0_sel:WORD_1
	v_pk_fma_f32 v[38:39], v[46:47], v[22:23], v[38:39] op_sel_hi:[1,0,1]
	v_pk_fma_f32 v[40:41], v[48:49], v[22:23], v[40:41] op_sel_hi:[1,0,1]
	v_cvt_pk_f32_fp8_e32 v[42:43], v112
	v_cvt_pk_f32_fp8_sdwa v[44:45], v112 src0_sel:WORD_1
	v_pk_fma_f32 v[26:27], v[42:43], v[22:23], v[26:27] op_sel:[0,1,0] op_sel_hi:[1,1,1]
	v_pk_fma_f32 v[28:29], v[44:45], v[22:23], v[28:29] op_sel:[0,1,0] op_sel_hi:[1,1,1]
	v_cvt_pk_f32_fp8_e32 v[46:47], v113
	v_cvt_pk_f32_fp8_sdwa v[48:49], v113 src0_sel:WORD_1
	v_pk_fma_f32 v[30:31], v[46:47], v[22:23], v[30:31] op_sel:[0,1,0] op_sel_hi:[1,1,1]
	v_pk_fma_f32 v[32:33], v[48:49], v[22:23], v[32:33] op_sel:[0,1,0] op_sel_hi:[1,1,1]
	v_cvt_pk_f32_fp8_e32 v[42:43], v114
	v_cvt_pk_f32_fp8_sdwa v[44:45], v114 src0_sel:WORD_1
	v_pk_fma_f32 v[34:35], v[42:43], v[22:23], v[34:35] op_sel:[0,1,0] op_sel_hi:[1,1,1]
	v_pk_fma_f32 v[36:37], v[44:45], v[22:23], v[36:37] op_sel:[0,1,0] op_sel_hi:[1,1,1]
	v_cvt_pk_f32_fp8_e32 v[46:47], v115
	v_cvt_pk_f32_fp8_sdwa v[48:49], v115 src0_sel:WORD_1
	v_pk_fma_f32 v[38:39], v[46:47], v[22:23], v[38:39] op_sel:[0,1,0] op_sel_hi:[1,1,1]
	v_pk_fma_f32 v[40:41], v[48:49], v[22:23], v[40:41] op_sel:[0,1,0] op_sel_hi:[1,1,1]
	v_cvt_pk_f32_fp8_e32 v[42:43], v116
	v_cvt_pk_f32_fp8_sdwa v[44:45], v116 src0_sel:WORD_1
	v_pk_fma_f32 v[26:27], v[42:43], v[24:25], v[26:27] op_sel_hi:[1,0,1]
	v_pk_fma_f32 v[28:29], v[44:45], v[24:25], v[28:29] op_sel_hi:[1,0,1]
	v_cvt_pk_f32_fp8_e32 v[46:47], v117
	v_cvt_pk_f32_fp8_sdwa v[48:49], v117 src0_sel:WORD_1
	v_pk_fma_f32 v[30:31], v[46:47], v[24:25], v[30:31] op_sel_hi:[1,0,1]
	v_pk_fma_f32 v[32:33], v[48:49], v[24:25], v[32:33] op_sel_hi:[1,0,1]
	v_cvt_pk_f32_fp8_e32 v[42:43], v118
	v_cvt_pk_f32_fp8_sdwa v[44:45], v118 src0_sel:WORD_1
	v_pk_fma_f32 v[34:35], v[42:43], v[24:25], v[34:35] op_sel_hi:[1,0,1]
	v_pk_fma_f32 v[36:37], v[44:45], v[24:25], v[36:37] op_sel_hi:[1,0,1]
	v_cvt_pk_f32_fp8_e32 v[46:47], v119
	v_cvt_pk_f32_fp8_sdwa v[48:49], v119 src0_sel:WORD_1
	v_pk_fma_f32 v[38:39], v[46:47], v[24:25], v[38:39] op_sel_hi:[1,0,1]
	v_pk_fma_f32 v[40:41], v[48:49], v[24:25], v[40:41] op_sel_hi:[1,0,1]
	v_cvt_pk_f32_fp8_e32 v[42:43], v120
; __device__ __forceinline__ float wsum(float v) { v = dpp_row_sum16(v); v += __shfl_xor(v, 16); v += __shfl_xor(v, 32); return v; }
; __device__ __forceinline__ void phase5(const Params& p, char* smem, const bool store_x = true) {
;     ...
;     float x2[16];
; #pragma unroll
;     for (int i = 0; i < 4; i++) {
;       const float4 xv = i == 0 ? xv0 : i == 1 ? xv1 : i == 2 ? xv2 : xv3;
;       x2[4 * i] = xv.x + o2[2 * i].x; x2[4 * i + 1] = xv.y + o2[2 * i].y; x2[4 * i + 2] = xv.z + o2[2 * i + 1].x; x2[4 * i + 3] = xv.w + o2[2 * i + 1].y;
;     }
;     float ss = 0.f;
; #pragma unroll
;     for (int i = 0; i < 16; i++) ss += x2[i] * x2[i];
;     ss = wsum(ss);
;     const float rs = rsqrtf(ss * (1.f / 1024.f) + EPSF);
;     if (store_x) {
; #pragma unroll
;       for (int i = 0; i < 4; i++) *(float4*)(xr + i * 4) = make_float4(x2[4 * i], x2[4 * i + 1], x2[4 * i + 2], x2[4 * i + 3]);
;     }
;     unsigned hp[8];
; #pragma unroll
;     for (int i = 0; i < 4; i++) {
;       const float4 g = *(const float4*)(p.g_ple + lane * 16 + i * 4);
;       hp[2 * i] = pack2(x2[4 * i] * rs * g.x, x2[4 * i + 1] * rs * g.y);
;       hp[2 * i + 1] = pack2(x2[4 * i + 2] * rs * g.z, x2[4 * i + 3] * rs * g.w);
;     }
;     *(uint4*)(H3 + (size_t)tok * 1024 + lane * 16) = make_uint4(hp[0], hp[1], hp[2], hp[3]);
;     *(uint4*)(H3 + (size_t)tok * 1024 + lane * 16 + 8) = make_uint4(hp[4], hp[5], hp[6], hp[7]);
	v_cvt_pk_f32_fp8_sdwa v[44:45], v120 src0_sel:WORD_1
	v_pk_fma_f32 v[26:27], v[42:43], v[24:25], v[26:27] op_sel:[0,1,0] op_sel_hi:[1,1,1]
	v_pk_fma_f32 v[28:29], v[44:45], v[24:25], v[28:29] op_sel:[0,1,0] op_sel_hi:[1,1,1]
	v_cvt_pk_f32_fp8_e32 v[46:47], v121
	v_cvt_pk_f32_fp8_sdwa v[48:49], v121 src0_sel:WORD_1
	v_pk_fma_f32 v[30:31], v[46:47], v[24:25], v[30:31] op_sel:[0,1,0] op_sel_hi:[1,1,1]
	v_pk_fma_f32 v[32:33], v[48:49], v[24:25], v[32:33] op_sel:[0,1,0] op_sel_hi:[1,1,1]
	v_cvt_pk_f32_fp8_e32 v[42:43], v122
	v_cvt_pk_f32_fp8_sdwa v[44:45], v122 src0_sel:WORD_1
	v_pk_fma_f32 v[34:35], v[42:43], v[24:25], v[34:35] op_sel:[0,1,0] op_sel_hi:[1,1,1]
	v_pk_fma_f32 v[36:37], v[44:45], v[24:25], v[36:37] op_sel:[0,1,0] op_sel_hi:[1,1,1]
	v_cvt_pk_f32_fp8_e32 v[46:47], v123
	v_cvt_pk_f32_fp8_sdwa v[48:49], v123 src0_sel:WORD_1
	v_pk_fma_f32 v[38:39], v[46:47], v[24:25], v[38:39] op_sel:[0,1,0] op_sel_hi:[1,1,1]
	v_pk_fma_f32 v[40:41], v[48:49], v[24:25], v[40:41] op_sel:[0,1,0] op_sel_hi:[1,1,1]
	s_nop 1
	v_permlane32_swap_b32_e32 v26, v34
	v_permlane32_swap_b32_e32 v27, v35
	v_permlane32_swap_b32_e32 v28, v36
	v_permlane32_swap_b32_e32 v29, v37
	v_permlane32_swap_b32_e32 v30, v38
	v_permlane32_swap_b32_e32 v31, v39
	v_permlane32_swap_b32_e32 v32, v40
	v_permlane32_swap_b32_e32 v33, v41
	v_add_f32_e32 v26, v26, v34
	v_add_f32_e32 v27, v27, v35
	v_add_f32_e32 v28, v28, v36
	v_add_f32_e32 v29, v29, v37
	v_add_f32_e32 v30, v30, v38
	v_add_f32_e32 v31, v31, v39
	v_add_f32_e32 v32, v32, v40
	v_add_f32_e32 v33, v33, v41
	s_nop 1
	v_permlane16_swap_b32_e32 v26, v30
	v_permlane16_swap_b32_e32 v27, v31
	v_permlane16_swap_b32_e32 v28, v32
	v_permlane16_swap_b32_e32 v29, v33
	v_add_f32_e32 v26, v26, v30
	v_add_f32_e32 v27, v27, v31
	v_add_f32_e32 v28, v28, v32
	v_add_f32_e32 v29, v29, v33
	s_lshl_b32 s11, s12, 12
	v_add_u32_e32 v6, s11, v3
	v_add_f32_dpp v42, v26, v26 row_ror:8 row_mask:0xf bank_mask:0xf
	v_add_f32_dpp v43, v28, v28 row_ror:8 row_mask:0xf bank_mask:0xf
	v_add_f32_dpp v44, v27, v27 row_ror:8 row_mask:0xf bank_mask:0xf
	v_add_f32_dpp v45, v29, v29 row_ror:8 row_mask:0xf bank_mask:0xf
	v_cndmask_b32_e64 v46, v42, v43, s[14:15]
	v_cndmask_b32_e64 v47, v44, v45, s[14:15]
	v_add_f32_e32 v46, v50, v46
	v_add_f32_e32 v47, v51, v47
	global_store_dwordx2 v6, v[46:47], s[6:7]
	v_pk_mul_f32 v[42:43], v[46:47], v[56:57]
	s_lshl_b32 s11, s12, 11
	v_add_u32_e32 v8, s11, v9
	v_cvt_pk_bf16_f32 v42, v42, v43
	global_store_dword v8, v42, s[36:37]
	v_mul_f32_e32 v48, v46, v46
	v_fmac_f32_e32 v48, v47, v47
	s_lshl_b32 s11, s12, 2
	s_add_u32 s11, s11, 0x1100000
	v_mov_b32_e32 v7, s11
	v_add_f32_dpp v48, v48, v48 quad_perm:[1,0,3,2] row_mask:0xf bank_mask:0xf
	s_nop 1
	v_add_f32_dpp v48, v48, v48 quad_perm:[2,3,0,1] row_mask:0xf bank_mask:0xf
	s_nop 1
	v_add_f32_dpp v48, v48, v48 row_half_mirror row_mask:0xf bank_mask:0xf
	s_nop 1
	v_add_f32_dpp v48, v48, v48 row_mirror row_mask:0xf bank_mask:0xf
	s_nop 1
	v_add_f32_dpp v48, v48, v48 row_bcast:15 row_mask:0xa bank_mask:0xf
	s_nop 1
	v_add_f32_dpp v48, v48, v48 row_bcast:31 row_mask:0xc bank_mask:0xf
	s_nop 1
	s_mov_b32 exec_lo, 0
	s_brev_b32 exec_hi, 1
	global_atomic_add_f32 v7, v48, s[4:5]
	s_mov_b64 exec, -1
.Lp5v_skip0:
	s_add_u32 s11, s16, 3
	s_and_b32 s11, s11, 7
	s_lshl_b32 s11, s11, 10
	v_add_u32_e32 v8, s11, v2
	ds_read_b128 v[10:13], v8 offset:0
	ds_read_b128 v[14:17], v8 offset:16
	ds_read_b128 v[18:21], v8 offset:32
	ds_read_b128 v[22:25], v8 offset:48
	s_add_u32 s10, s8, s26
	s_min_u32 s10, s10, s13
	s_lshl_b32 s18, s10, 10
	s_add_u32 s11, s16, 7
	s_and_b32 s11, s11, 7
	s_lshl_b32 s11, s11, 10
	s_add_u32 s11, s11, s17
	s_mov_b32 m0, s11
	v_lshl_add_u64 v[4:5], v[58:59], 0, s[18:19]
	global_load_lds_dwordx4 v[4:5], off
	s_add_u32 s10, s8, s22
	s_min_u32 s10, s10, s13
	s_lshl_b32 s11, s10, 12
	v_add_u32_e32 v6, s11, v3
	global_load_dwordx2 v[50:51], v6, s[6:7]
	s_waitcnt lgkmcnt(0)
	v_add_u32_e32 v10, v10, v1
	global_load_dwordx4 v[60:63], v10, s[2:3]
	v_add_u32_e32 v11, v11, v1
	global_load_dwordx4 v[64:67], v11, s[2:3]
	v_add_u32_e32 v12, v12, v1
	global_load_dwordx4 v[68:71], v12, s[2:3]
	v_add_u32_e32 v13, v13, v1
	global_load_dwordx4 v[72:75], v13, s[2:3]
	v_add_u32_e32 v14, v14, v1
	global_load_dwordx4 v[76:79], v14, s[2:3]
	v_add_u32_e32 v15, v15, v1
	global_load_dwordx4 v[80:83], v15, s[2:3]
	v_add_u32_e32 v16, v16, v1
	global_load_dwordx4 v[84:87], v16, s[2:3]
	v_add_u32_e32 v17, v17, v1
	global_load_dwordx4 v[88:91], v17, s[2:3]
	v_add_u32_e32 v18, v18, v1
	global_load_dwordx4 v[92:95], v18, s[2:3]
	v_add_u32_e32 v19, v19, v1
	global_load_dwordx4 v[96:99], v19, s[2:3]
	v_add_u32_e32 v20, v20, v1
	global_load_dwordx4 v[100:103], v20, s[2:3]
	v_add_u32_e32 v21, v21, v1
	global_load_dwordx4 v[104:107], v21, s[2:3]
	v_add_u32_e32 v22, v22, v1
	global_load_dwordx4 v[108:111], v22, s[2:3]
	v_add_u32_e32 v23, v23, v1
	global_load_dwordx4 v[112:115], v23, s[2:3]
	v_add_u32_e32 v24, v24, v1
	global_load_dwordx4 v[116:119], v24, s[2:3]
	v_add_u32_e32 v25, v25, v1
	global_load_dwordx4 v[120:123], v25, s[2:3]
	s_add_u32 s11, s16, 1
	s_and_b32 s11, s11, 7
	s_lshl_b32 s11, s11, 10
	v_add_u32_e32 v8, s11, v2
	ds_read_b128 v[10:13], v8 offset:512
	ds_read_b128 v[14:17], v8 offset:528
	ds_read_b128 v[18:21], v8 offset:544
	ds_read_b128 v[22:25], v8 offset:560
	s_add_u32 s12, s8, s20
	s_waitcnt vmcnt(42) lgkmcnt(0)
	s_cmp_lt_u32 s12, 0x4200
	s_cbranch_scc0 .Lp5v_skip1
; #define P5_LOAD(A, TAB, j0)                                                                \
;   _Pragma("unroll") for (int q = 0; q < 16; q++) {                                         \
;     A[q] = ((const uint4*)((TAB) + (size_t)widx[(j0) + q] * 1024))[lane];                  \
;   }
; __device__ __forceinline__ void phase5(const Params& p, char* smem, const bool store_x = true) {
;     ...
; #pragma unroll 1
;     for (int j0 = 0; j0 < 128; j0 += 32) {
;       P5_LOAD(A1, EV, j0 + 16)
;       P5_COMPUTE_V(A0, j0)
;       if (j0 + 32 < 128) { P5_LOAD(A0, EV, j0 + 32) }
;       P5_COMPUTE_V(A1, j0 + 16)
;     }
	v_cvt_pk_f32_fp8_e32 v[42:43], v124
	v_cvt_pk_f32_fp8_sdwa v[44:45], v124 src0_sel:WORD_1
	v_pk_mul_f32 v[26:27], v[42:43], v[10:11] op_sel_hi:[1,0]
	v_pk_mul_f32 v[28:29], v[44:45], v[10:11] op_sel_hi:[1,0]
	v_cvt_pk_f32_fp8_e32 v[46:47], v125
	v_cvt_pk_f32_fp8_sdwa v[48:49], v125 src0_sel:WORD_1
	v_pk_mul_f32 v[30:31], v[46:47], v[10:11] op_sel_hi:[1,0]
	v_pk_mul_f32 v[32:33], v[48:49], v[10:11] op_sel_hi:[1,0]
	v_cvt_pk_f32_fp8_e32 v[42:43], v126
	v_cvt_pk_f32_fp8_sdwa v[44:45], v126 src0_sel:WORD_1
	v_pk_mul_f32 v[34:35], v[42:43], v[10:11] op_sel_hi:[1,0]
	v_pk_mul_f32 v[36:37], v[44:45], v[10:11] op_sel_hi:[1,0]
	v_cvt_pk_f32_fp8_e32 v[46:47], v127
	v_cvt_pk_f32_fp8_sdwa v[48:49], v127 src0_sel:WORD_1
	v_pk_mul_f32 v[38:39], v[46:47], v[10:11] op_sel_hi:[1,0]
	v_pk_mul_f32 v[40:41], v[48:49], v[10:11] op_sel_hi:[1,0]
	v_cvt_pk_f32_fp8_e32 v[42:43], v128
	v_cvt_pk_f32_fp8_sdwa v[44:45], v128 src0_sel:WORD_1
	v_pk_fma_f32 v[26:27], v[42:43], v[10:11], v[26:27] op_sel:[0,1,0] op_sel_hi:[1,1,1]
	v_pk_fma_f32 v[28:29], v[44:45], v[10:11], v[28:29] op_sel:[0,1,0] op_sel_hi:[1,1,1]
	v_cvt_pk_f32_fp8_e32 v[46:47], v129
	v_cvt_pk_f32_fp8_sdwa v[48:49], v129 src0_sel:WORD_1
	v_pk_fma_f32 v[30:31], v[46:47], v[10:11], v[30:31] op_sel:[0,1,0] op_sel_hi:[1,1,1]
	v_pk_fma_f32 v[32:33], v[48:49], v[10:11], v[32:33] op_sel:[0,1,0] op_sel_hi:[1,1,1]
	v_cvt_pk_f32_fp8_e32 v[42:43], v130
	v_cvt_pk_f32_fp8_sdwa v[44:45], v130 src0_sel:WORD_1
	v_pk_fma_f32 v[34:35], v[42:43], v[10:11], v[34:35] op_sel:[0,1,0] op_sel_hi:[1,1,1]
	v_pk_fma_f32 v[36:37], v[44:45], v[10:11], v[36:37] op_sel:[0,1,0] op_sel_hi:[1,1,1]
	v_cvt_pk_f32_fp8_e32 v[46:47], v131
	v_cvt_pk_f32_fp8_sdwa v[48:49], v131 src0_sel:WORD_1
	v_pk_fma_f32 v[38:39], v[46:47], v[10:11], v[38:39] op_sel:[0,1,0] op_sel_hi:[1,1,1]
	v_pk_fma_f32 v[40:41], v[48:49], v[10:11], v[40:41] op_sel:[0,1,0] op_sel_hi:[1,1,1]
	v_cvt_pk_f32_fp8_e32 v[42:43], v132
	v_cvt_pk_f32_fp8_sdwa v[44:45], v132 src0_sel:WORD_1
	v_pk_fma_f32 v[26:27], v[42:43], v[12:13], v[26:27] op_sel_hi:[1,0,1]
	v_pk_fma_f32 v[28:29], v[44:45], v[12:13], v[28:29] op_sel_hi:[1,0,1]
	v_cvt_pk_f32_fp8_e32 v[46:47], v133
	v_cvt_pk_f32_fp8_sdwa v[48:49], v133 src0_sel:WORD_1
	v_pk_fma_f32 v[30:31], v[46:47], v[12:13], v[30:31] op_sel_hi:[1,0,1]
	v_pk_fma_f32 v[32:33], v[48:49], v[12:13], v[32:33] op_sel_hi:[1,0,1]
	v_cvt_pk_f32_fp8_e32 v[42:43], v134
	v_cvt_pk_f32_fp8_sdwa v[44:45], v134 src0_sel:WORD_1
	v_pk_fma_f32 v[34:35], v[42:43], v[12:13], v[34:35] op_sel_hi:[1,0,1]
	v_pk_fma_f32 v[36:37], v[44:45], v[12:13], v[36:37] op_sel_hi:[1,0,1]
	v_cvt_pk_f32_fp8_e32 v[46:47], v135
	v_cvt_pk_f32_fp8_sdwa v[48:49], v135 src0_sel:WORD_1
	v_pk_fma_f32 v[38:39], v[46:47], v[12:13], v[38:39] op_sel_hi:[1,0,1]
	v_pk_fma_f32 v[40:41], v[48:49], v[12:13], v[40:41] op_sel_hi:[1,0,1]
	v_cvt_pk_f32_fp8_e32 v[42:43], v136
	v_cvt_pk_f32_fp8_sdwa v[44:45], v136 src0_sel:WORD_1
	v_pk_fma_f32 v[26:27], v[42:43], v[12:13], v[26:27] op_sel:[0,1,0] op_sel_hi:[1,1,1]
	v_pk_fma_f32 v[28:29], v[44:45], v[12:13], v[28:29] op_sel:[0,1,0] op_sel_hi:[1,1,1]
	v_cvt_pk_f32_fp8_e32 v[46:47], v137
	v_cvt_pk_f32_fp8_sdwa v[48:49], v137 src0_sel:WORD_1
	v_pk_fma_f32 v[30:31], v[46:47], v[12:13], v[30:31] op_sel:[0,1,0] op_sel_hi:[1,1,1]
	v_pk_fma_f32 v[32:33], v[48:49], v[12:13], v[32:33] op_sel:[0,1,0] op_sel_hi:[1,1,1]
	v_cvt_pk_f32_fp8_e32 v[42:43], v138
	v_cvt_pk_f32_fp8_sdwa v[44:45], v138 src0_sel:WORD_1
	v_pk_fma_f32 v[34:35], v[42:43], v[12:13], v[34:35] op_sel:[0,1,0] op_sel_hi:[1,1,1]
	v_pk_fma_f32 v[36:37], v[44:45], v[12:13], v[36:37] op_sel:[0,1,0] op_sel_hi:[1,1,1]
	v_cvt_pk_f32_fp8_e32 v[46:47], v139
	v_cvt_pk_f32_fp8_sdwa v[48:49], v139 src0_sel:WORD_1
	v_pk_fma_f32 v[38:39], v[46:47], v[12:13], v[38:39] op_sel:[0,1,0] op_sel_hi:[1,1,1]
	v_pk_fma_f32 v[40:41], v[48:49], v[12:13], v[40:41] op_sel:[0,1,0] op_sel_hi:[1,1,1]
	v_cvt_pk_f32_fp8_e32 v[42:43], v140
	v_cvt_pk_f32_fp8_sdwa v[44:45], v140 src0_sel:WORD_1
	v_pk_fma_f32 v[26:27], v[42:43], v[14:15], v[26:27] op_sel_hi:[1,0,1]
	v_pk_fma_f32 v[28:29], v[44:45], v[14:15], v[28:29] op_sel_hi:[1,0,1]
	v_cvt_pk_f32_fp8_e32 v[46:47], v141
	v_cvt_pk_f32_fp8_sdwa v[48:49], v141 src0_sel:WORD_1
	v_pk_fma_f32 v[30:31], v[46:47], v[14:15], v[30:31] op_sel_hi:[1,0,1]
	v_pk_fma_f32 v[32:33], v[48:49], v[14:15], v[32:33] op_sel_hi:[1,0,1]
	v_cvt_pk_f32_fp8_e32 v[42:43], v142
	v_cvt_pk_f32_fp8_sdwa v[44:45], v142 src0_sel:WORD_1
	v_pk_fma_f32 v[34:35], v[42:43], v[14:15], v[34:35] op_sel_hi:[1,0,1]
	v_pk_fma_f32 v[36:37], v[44:45], v[14:15], v[36:37] op_sel_hi:[1,0,1]
	v_cvt_pk_f32_fp8_e32 v[46:47], v143
	v_cvt_pk_f32_fp8_sdwa v[48:49], v143 src0_sel:WORD_1
	v_pk_fma_f32 v[38:39], v[46:47], v[14:15], v[38:39] op_sel_hi:[1,0,1]
	v_pk_fma_f32 v[40:41], v[48:49], v[14:15], v[40:41] op_sel_hi:[1,0,1]
	v_cvt_pk_f32_fp8_e32 v[42:43], v144
	v_cvt_pk_f32_fp8_sdwa v[44:45], v144 src0_sel:WORD_1
	v_pk_fma_f32 v[26:27], v[42:43], v[14:15], v[26:27] op_sel:[0,1,0] op_sel_hi:[1,1,1]
	v_pk_fma_f32 v[28:29], v[44:45], v[14:15], v[28:29] op_sel:[0,1,0] op_sel_hi:[1,1,1]
	v_cvt_pk_f32_fp8_e32 v[46:47], v145
	v_cvt_pk_f32_fp8_sdwa v[48:49], v145 src0_sel:WORD_1
	v_pk_fma_f32 v[30:31], v[46:47], v[14:15], v[30:31] op_sel:[0,1,0] op_sel_hi:[1,1,1]
	v_pk_fma_f32 v[32:33], v[48:49], v[14:15], v[32:33] op_sel:[0,1,0] op_sel_hi:[1,1,1]
	v_cvt_pk_f32_fp8_e32 v[42:43], v146
	v_cvt_pk_f32_fp8_sdwa v[44:45], v146 src0_sel:WORD_1
	v_pk_fma_f32 v[34:35], v[42:43], v[14:15], v[34:35] op_sel:[0,1,0] op_sel_hi:[1,1,1]
	v_pk_fma_f32 v[36:37], v[44:45], v[14:15], v[36:37] op_sel:[0,1,0] op_sel_hi:[1,1,1]
	v_cvt_pk_f32_fp8_e32 v[46:47], v147
; #define P5_LOAD(A, TAB, j0)                                                                \
;   _Pragma("unroll") for (int q = 0; q < 16; q++) {                                         \
;     A[q] = ((const uint4*)((TAB) + (size_t)widx[(j0) + q] * 1024))[lane];                  \
;   }
; __device__ __forceinline__ void phase5(const Params& p, char* smem, const bool store_x = true) {
;     ...
; #pragma unroll 1
;     for (int j0 = 0; j0 < 128; j0 += 32) {
;       P5_LOAD(A1, EV, j0 + 16)
;       P5_COMPUTE_V(A0, j0)
;       if (j0 + 32 < 128) { P5_LOAD(A0, EV, j0 + 32) }
;       P5_COMPUTE_V(A1, j0 + 16)
;     }
	v_cvt_pk_f32_fp8_sdwa v[48:49], v147 src0_sel:WORD_1
	v_pk_fma_f32 v[38:39], v[46:47], v[14:15], v[38:39] op_sel:[0,1,0] op_sel_hi:[1,1,1]
	v_pk_fma_f32 v[40:41], v[48:49], v[14:15], v[40:41] op_sel:[0,1,0] op_sel_hi:[1,1,1]
	v_cvt_pk_f32_fp8_e32 v[42:43], v148
	v_cvt_pk_f32_fp8_sdwa v[44:45], v148 src0_sel:WORD_1
	v_pk_fma_f32 v[26:27], v[42:43], v[16:17], v[26:27] op_sel_hi:[1,0,1]
	v_pk_fma_f32 v[28:29], v[44:45], v[16:17], v[28:29] op_sel_hi:[1,0,1]
	v_cvt_pk_f32_fp8_e32 v[46:47], v149
	v_cvt_pk_f32_fp8_sdwa v[48:49], v149 src0_sel:WORD_1
	v_pk_fma_f32 v[30:31], v[46:47], v[16:17], v[30:31] op_sel_hi:[1,0,1]
	v_pk_fma_f32 v[32:33], v[48:49], v[16:17], v[32:33] op_sel_hi:[1,0,1]
	v_cvt_pk_f32_fp8_e32 v[42:43], v150
	v_cvt_pk_f32_fp8_sdwa v[44:45], v150 src0_sel:WORD_1
	v_pk_fma_f32 v[34:35], v[42:43], v[16:17], v[34:35] op_sel_hi:[1,0,1]
	v_pk_fma_f32 v[36:37], v[44:45], v[16:17], v[36:37] op_sel_hi:[1,0,1]
	v_cvt_pk_f32_fp8_e32 v[46:47], v151
	v_cvt_pk_f32_fp8_sdwa v[48:49], v151 src0_sel:WORD_1
	v_pk_fma_f32 v[38:39], v[46:47], v[16:17], v[38:39] op_sel_hi:[1,0,1]
	v_pk_fma_f32 v[40:41], v[48:49], v[16:17], v[40:41] op_sel_hi:[1,0,1]
	v_cvt_pk_f32_fp8_e32 v[42:43], v152
	v_cvt_pk_f32_fp8_sdwa v[44:45], v152 src0_sel:WORD_1
	v_pk_fma_f32 v[26:27], v[42:43], v[16:17], v[26:27] op_sel:[0,1,0] op_sel_hi:[1,1,1]
	v_pk_fma_f32 v[28:29], v[44:45], v[16:17], v[28:29] op_sel:[0,1,0] op_sel_hi:[1,1,1]
	v_cvt_pk_f32_fp8_e32 v[46:47], v153
	v_cvt_pk_f32_fp8_sdwa v[48:49], v153 src0_sel:WORD_1
	v_pk_fma_f32 v[30:31], v[46:47], v[16:17], v[30:31] op_sel:[0,1,0] op_sel_hi:[1,1,1]
	v_pk_fma_f32 v[32:33], v[48:49], v[16:17], v[32:33] op_sel:[0,1,0] op_sel_hi:[1,1,1]
	v_cvt_pk_f32_fp8_e32 v[42:43], v154
	v_cvt_pk_f32_fp8_sdwa v[44:45], v154 src0_sel:WORD_1
	v_pk_fma_f32 v[34:35], v[42:43], v[16:17], v[34:35] op_sel:[0,1,0] op_sel_hi:[1,1,1]
	v_pk_fma_f32 v[36:37], v[44:45], v[16:17], v[36:37] op_sel:[0,1,0] op_sel_hi:[1,1,1]
	v_cvt_pk_f32_fp8_e32 v[46:47], v155
	v_cvt_pk_f32_fp8_sdwa v[48:49], v155 src0_sel:WORD_1
	v_pk_fma_f32 v[38:39], v[46:47], v[16:17], v[38:39] op_sel:[0,1,0] op_sel_hi:[1,1,1]
	v_pk_fma_f32 v[40:41], v[48:49], v[16:17], v[40:41] op_sel:[0,1,0] op_sel_hi:[1,1,1]
	v_cvt_pk_f32_fp8_e32 v[42:43], v156
	v_cvt_pk_f32_fp8_sdwa v[44:45], v156 src0_sel:WORD_1
	v_pk_fma_f32 v[26:27], v[42:43], v[18:19], v[26:27] op_sel_hi:[1,0,1]
	v_pk_fma_f32 v[28:29], v[44:45], v[18:19], v[28:29] op_sel_hi:[1,0,1]
	v_cvt_pk_f32_fp8_e32 v[46:47], v157
	v_cvt_pk_f32_fp8_sdwa v[48:49], v157 src0_sel:WORD_1
	v_pk_fma_f32 v[30:31], v[46:47], v[18:19], v[30:31] op_sel_hi:[1,0,1]
	v_pk_fma_f32 v[32:33], v[48:49], v[18:19], v[32:33] op_sel_hi:[1,0,1]
	v_cvt_pk_f32_fp8_e32 v[42:43], v158
	v_cvt_pk_f32_fp8_sdwa v[44:45], v158 src0_sel:WORD_1
	v_pk_fma_f32 v[34:35], v[42:43], v[18:19], v[34:35] op_sel_hi:[1,0,1]
	v_pk_fma_f32 v[36:37], v[44:45], v[18:19], v[36:37] op_sel_hi:[1,0,1]
	v_cvt_pk_f32_fp8_e32 v[46:47], v159
	v_cvt_pk_f32_fp8_sdwa v[48:49], v159 src0_sel:WORD_1
	v_pk_fma_f32 v[38:39], v[46:47], v[18:19], v[38:39] op_sel_hi:[1,0,1]
	v_pk_fma_f32 v[40:41], v[48:49], v[18:19], v[40:41] op_sel_hi:[1,0,1]
	v_cvt_pk_f32_fp8_e32 v[42:43], v160
	v_cvt_pk_f32_fp8_sdwa v[44:45], v160 src0_sel:WORD_1
	v_pk_fma_f32 v[26:27], v[42:43], v[18:19], v[26:27] op_sel:[0,1,0] op_sel_hi:[1,1,1]
	v_pk_fma_f32 v[28:29], v[44:45], v[18:19], v[28:29] op_sel:[0,1,0] op_sel_hi:[1,1,1]
	v_cvt_pk_f32_fp8_e32 v[46:47], v161
	v_cvt_pk_f32_fp8_sdwa v[48:49], v161 src0_sel:WORD_1
	v_pk_fma_f32 v[30:31], v[46:47], v[18:19], v[30:31] op_sel:[0,1,0] op_sel_hi:[1,1,1]
	v_pk_fma_f32 v[32:33], v[48:49], v[18:19], v[32:33] op_sel:[0,1,0] op_sel_hi:[1,1,1]
	v_cvt_pk_f32_fp8_e32 v[42:43], v162
	v_cvt_pk_f32_fp8_sdwa v[44:45], v162 src0_sel:WORD_1
	v_pk_fma_f32 v[34:35], v[42:43], v[18:19], v[34:35] op_sel:[0,1,0] op_sel_hi:[1,1,1]
	v_pk_fma_f32 v[36:37], v[44:45], v[18:19], v[36:37] op_sel:[0,1,0] op_sel_hi:[1,1,1]
	v_cvt_pk_f32_fp8_e32 v[46:47], v163
	v_cvt_pk_f32_fp8_sdwa v[48:49], v163 src0_sel:WORD_1
	v_pk_fma_f32 v[38:39], v[46:47], v[18:19], v[38:39] op_sel:[0,1,0] op_sel_hi:[1,1,1]
	v_pk_fma_f32 v[40:41], v[48:49], v[18:19], v[40:41] op_sel:[0,1,0] op_sel_hi:[1,1,1]
	v_cvt_pk_f32_fp8_e32 v[42:43], v164
	v_cvt_pk_f32_fp8_sdwa v[44:45], v164 src0_sel:WORD_1
	v_pk_fma_f32 v[26:27], v[42:43], v[20:21], v[26:27] op_sel_hi:[1,0,1]
	v_pk_fma_f32 v[28:29], v[44:45], v[20:21], v[28:29] op_sel_hi:[1,0,1]
	v_cvt_pk_f32_fp8_e32 v[46:47], v165
	v_cvt_pk_f32_fp8_sdwa v[48:49], v165 src0_sel:WORD_1
	v_pk_fma_f32 v[30:31], v[46:47], v[20:21], v[30:31] op_sel_hi:[1,0,1]
	v_pk_fma_f32 v[32:33], v[48:49], v[20:21], v[32:33] op_sel_hi:[1,0,1]
	v_cvt_pk_f32_fp8_e32 v[42:43], v166
	v_cvt_pk_f32_fp8_sdwa v[44:45], v166 src0_sel:WORD_1
	v_pk_fma_f32 v[34:35], v[42:43], v[20:21], v[34:35] op_sel_hi:[1,0,1]
	v_pk_fma_f32 v[36:37], v[44:45], v[20:21], v[36:37] op_sel_hi:[1,0,1]
	v_cvt_pk_f32_fp8_e32 v[46:47], v167
	v_cvt_pk_f32_fp8_sdwa v[48:49], v167 src0_sel:WORD_1
	v_pk_fma_f32 v[38:39], v[46:47], v[20:21], v[38:39] op_sel_hi:[1,0,1]
	v_pk_fma_f32 v[40:41], v[48:49], v[20:21], v[40:41] op_sel_hi:[1,0,1]
	v_cvt_pk_f32_fp8_e32 v[42:43], v168
	v_cvt_pk_f32_fp8_sdwa v[44:45], v168 src0_sel:WORD_1
	v_pk_fma_f32 v[26:27], v[42:43], v[20:21], v[26:27] op_sel:[0,1,0] op_sel_hi:[1,1,1]
	v_pk_fma_f32 v[28:29], v[44:45], v[20:21], v[28:29] op_sel:[0,1,0] op_sel_hi:[1,1,1]
	v_cvt_pk_f32_fp8_e32 v[46:47], v169
	v_cvt_pk_f32_fp8_sdwa v[48:49], v169 src0_sel:WORD_1
	v_pk_fma_f32 v[30:31], v[46:47], v[20:21], v[30:31] op_sel:[0,1,0] op_sel_hi:[1,1,1]
	v_pk_fma_f32 v[32:33], v[48:49], v[20:21], v[32:33] op_sel:[0,1,0] op_sel_hi:[1,1,1]
; __device__ __forceinline__ float wsum(float v) { v = dpp_row_sum16(v); v += __shfl_xor(v, 16); v += __shfl_xor(v, 32); return v; }
; __device__ __forceinline__ void phase5(const Params& p, char* smem, const bool store_x = true) {
;     ...
;     float x2[16];
; #pragma unroll
;     for (int i = 0; i < 4; i++) {
;       const float4 xv = i == 0 ? xv0 : i == 1 ? xv1 : i == 2 ? xv2 : xv3;
;       x2[4 * i] = xv.x + o2[2 * i].x; x2[4 * i + 1] = xv.y + o2[2 * i].y; x2[4 * i + 2] = xv.z + o2[2 * i + 1].x; x2[4 * i + 3] = xv.w + o2[2 * i + 1].y;
;     }
;     float ss = 0.f;
; #pragma unroll
;     for (int i = 0; i < 16; i++) ss += x2[i] * x2[i];
;     ss = wsum(ss);
;     const float rs = rsqrtf(ss * (1.f / 1024.f) + EPSF);
;     if (store_x) {
; #pragma unroll
;       for (int i = 0; i < 4; i++) *(float4*)(xr + i * 4) = make_float4(x2[4 * i], x2[4 * i + 1], x2[4 * i + 2], x2[4 * i + 3]);
;     }
;     unsigned hp[8];
; #pragma unroll
;     for (int i = 0; i < 4; i++) {
;       const float4 g = *(const float4*)(p.g_ple + lane * 16 + i * 4);
;       hp[2 * i] = pack2(x2[4 * i] * rs * g.x, x2[4 * i + 1] * rs * g.y);
;       hp[2 * i + 1] = pack2(x2[4 * i + 2] * rs * g.z, x2[4 * i + 3] * rs * g.w);
;     }
;     *(uint4*)(H3 + (size_t)tok * 1024 + lane * 16) = make_uint4(hp[0], hp[1], hp[2], hp[3]);
;     *(uint4*)(H3 + (size_t)tok * 1024 + lane * 16 + 8) = make_uint4(hp[4], hp[5], hp[6], hp[7]);
	v_cvt_pk_f32_fp8_e32 v[42:43], v170
	v_cvt_pk_f32_fp8_sdwa v[44:45], v170 src0_sel:WORD_1
	v_pk_fma_f32 v[34:35], v[42:43], v[20:21], v[34:35] op_sel:[0,1,0] op_sel_hi:[1,1,1]
	v_pk_fma_f32 v[36:37], v[44:45], v[20:21], v[36:37] op_sel:[0,1,0] op_sel_hi:[1,1,1]
	v_cvt_pk_f32_fp8_e32 v[46:47], v171
	v_cvt_pk_f32_fp8_sdwa v[48:49], v171 src0_sel:WORD_1
	v_pk_fma_f32 v[38:39], v[46:47], v[20:21], v[38:39] op_sel:[0,1,0] op_sel_hi:[1,1,1]
	v_pk_fma_f32 v[40:41], v[48:49], v[20:21], v[40:41] op_sel:[0,1,0] op_sel_hi:[1,1,1]
	v_cvt_pk_f32_fp8_e32 v[42:43], v172
	v_cvt_pk_f32_fp8_sdwa v[44:45], v172 src0_sel:WORD_1
	v_pk_fma_f32 v[26:27], v[42:43], v[22:23], v[26:27] op_sel_hi:[1,0,1]
	v_pk_fma_f32 v[28:29], v[44:45], v[22:23], v[28:29] op_sel_hi:[1,0,1]
	v_cvt_pk_f32_fp8_e32 v[46:47], v173
	v_cvt_pk_f32_fp8_sdwa v[48:49], v173 src0_sel:WORD_1
	v_pk_fma_f32 v[30:31], v[46:47], v[22:23], v[30:31] op_sel_hi:[1,0,1]
	v_pk_fma_f32 v[32:33], v[48:49], v[22:23], v[32:33] op_sel_hi:[1,0,1]
	v_cvt_pk_f32_fp8_e32 v[42:43], v174
	v_cvt_pk_f32_fp8_sdwa v[44:45], v174 src0_sel:WORD_1
	v_pk_fma_f32 v[34:35], v[42:43], v[22:23], v[34:35] op_sel_hi:[1,0,1]
	v_pk_fma_f32 v[36:37], v[44:45], v[22:23], v[36:37] op_sel_hi:[1,0,1]
	v_cvt_pk_f32_fp8_e32 v[46:47], v175
	v_cvt_pk_f32_fp8_sdwa v[48:49], v175 src0_sel:WORD_1
	v_pk_fma_f32 v[38:39], v[46:47], v[22:23], v[38:39] op_sel_hi:[1,0,1]
	v_pk_fma_f32 v[40:41], v[48:49], v[22:23], v[40:41] op_sel_hi:[1,0,1]
	v_cvt_pk_f32_fp8_e32 v[42:43], v176
	v_cvt_pk_f32_fp8_sdwa v[44:45], v176 src0_sel:WORD_1
	v_pk_fma_f32 v[26:27], v[42:43], v[22:23], v[26:27] op_sel:[0,1,0] op_sel_hi:[1,1,1]
	v_pk_fma_f32 v[28:29], v[44:45], v[22:23], v[28:29] op_sel:[0,1,0] op_sel_hi:[1,1,1]
	v_cvt_pk_f32_fp8_e32 v[46:47], v177
	v_cvt_pk_f32_fp8_sdwa v[48:49], v177 src0_sel:WORD_1
	v_pk_fma_f32 v[30:31], v[46:47], v[22:23], v[30:31] op_sel:[0,1,0] op_sel_hi:[1,1,1]
	v_pk_fma_f32 v[32:33], v[48:49], v[22:23], v[32:33] op_sel:[0,1,0] op_sel_hi:[1,1,1]
	v_cvt_pk_f32_fp8_e32 v[42:43], v178
	v_cvt_pk_f32_fp8_sdwa v[44:45], v178 src0_sel:WORD_1
	v_pk_fma_f32 v[34:35], v[42:43], v[22:23], v[34:35] op_sel:[0,1,0] op_sel_hi:[1,1,1]
	v_pk_fma_f32 v[36:37], v[44:45], v[22:23], v[36:37] op_sel:[0,1,0] op_sel_hi:[1,1,1]
	v_cvt_pk_f32_fp8_e32 v[46:47], v179
	v_cvt_pk_f32_fp8_sdwa v[48:49], v179 src0_sel:WORD_1
	v_pk_fma_f32 v[38:39], v[46:47], v[22:23], v[38:39] op_sel:[0,1,0] op_sel_hi:[1,1,1]
	v_pk_fma_f32 v[40:41], v[48:49], v[22:23], v[40:41] op_sel:[0,1,0] op_sel_hi:[1,1,1]
	v_cvt_pk_f32_fp8_e32 v[42:43], v180
	v_cvt_pk_f32_fp8_sdwa v[44:45], v180 src0_sel:WORD_1
	v_pk_fma_f32 v[26:27], v[42:43], v[24:25], v[26:27] op_sel_hi:[1,0,1]
	v_pk_fma_f32 v[28:29], v[44:45], v[24:25], v[28:29] op_sel_hi:[1,0,1]
	v_cvt_pk_f32_fp8_e32 v[46:47], v181
	v_cvt_pk_f32_fp8_sdwa v[48:49], v181 src0_sel:WORD_1
	v_pk_fma_f32 v[30:31], v[46:47], v[24:25], v[30:31] op_sel_hi:[1,0,1]
	v_pk_fma_f32 v[32:33], v[48:49], v[24:25], v[32:33] op_sel_hi:[1,0,1]
	v_cvt_pk_f32_fp8_e32 v[42:43], v182
	v_cvt_pk_f32_fp8_sdwa v[44:45], v182 src0_sel:WORD_1
	v_pk_fma_f32 v[34:35], v[42:43], v[24:25], v[34:35] op_sel_hi:[1,0,1]
	v_pk_fma_f32 v[36:37], v[44:45], v[24:25], v[36:37] op_sel_hi:[1,0,1]
	v_cvt_pk_f32_fp8_e32 v[46:47], v183
	v_cvt_pk_f32_fp8_sdwa v[48:49], v183 src0_sel:WORD_1
	v_pk_fma_f32 v[38:39], v[46:47], v[24:25], v[38:39] op_sel_hi:[1,0,1]
	v_pk_fma_f32 v[40:41], v[48:49], v[24:25], v[40:41] op_sel_hi:[1,0,1]
	v_cvt_pk_f32_fp8_e32 v[42:43], v184
	v_cvt_pk_f32_fp8_sdwa v[44:45], v184 src0_sel:WORD_1
	v_pk_fma_f32 v[26:27], v[42:43], v[24:25], v[26:27] op_sel:[0,1,0] op_sel_hi:[1,1,1]
	v_pk_fma_f32 v[28:29], v[44:45], v[24:25], v[28:29] op_sel:[0,1,0] op_sel_hi:[1,1,1]
	v_cvt_pk_f32_fp8_e32 v[46:47], v185
	v_cvt_pk_f32_fp8_sdwa v[48:49], v185 src0_sel:WORD_1
	v_pk_fma_f32 v[30:31], v[46:47], v[24:25], v[30:31] op_sel:[0,1,0] op_sel_hi:[1,1,1]
	v_pk_fma_f32 v[32:33], v[48:49], v[24:25], v[32:33] op_sel:[0,1,0] op_sel_hi:[1,1,1]
	v_cvt_pk_f32_fp8_e32 v[42:43], v186
	v_cvt_pk_f32_fp8_sdwa v[44:45], v186 src0_sel:WORD_1
	v_pk_fma_f32 v[34:35], v[42:43], v[24:25], v[34:35] op_sel:[0,1,0] op_sel_hi:[1,1,1]
	v_pk_fma_f32 v[36:37], v[44:45], v[24:25], v[36:37] op_sel:[0,1,0] op_sel_hi:[1,1,1]
	v_cvt_pk_f32_fp8_e32 v[46:47], v187
	v_cvt_pk_f32_fp8_sdwa v[48:49], v187 src0_sel:WORD_1
	v_pk_fma_f32 v[38:39], v[46:47], v[24:25], v[38:39] op_sel:[0,1,0] op_sel_hi:[1,1,1]
	v_pk_fma_f32 v[40:41], v[48:49], v[24:25], v[40:41] op_sel:[0,1,0] op_sel_hi:[1,1,1]
	s_nop 1
	v_permlane32_swap_b32_e32 v26, v34
	v_permlane32_swap_b32_e32 v27, v35
	v_permlane32_swap_b32_e32 v28, v36
	v_permlane32_swap_b32_e32 v29, v37
	v_permlane32_swap_b32_e32 v30, v38
	v_permlane32_swap_b32_e32 v31, v39
	v_permlane32_swap_b32_e32 v32, v40
	v_permlane32_swap_b32_e32 v33, v41
	v_add_f32_e32 v26, v26, v34
	v_add_f32_e32 v27, v27, v35
	v_add_f32_e32 v28, v28, v36
	v_add_f32_e32 v29, v29, v37
	v_add_f32_e32 v30, v30, v38
	v_add_f32_e32 v31, v31, v39
	v_add_f32_e32 v32, v32, v40
	v_add_f32_e32 v33, v33, v41
	s_nop 1
	v_permlane16_swap_b32_e32 v26, v30
	v_permlane16_swap_b32_e32 v27, v31
	v_permlane16_swap_b32_e32 v28, v32
	v_permlane16_swap_b32_e32 v29, v33
	v_add_f32_e32 v26, v26, v30
	v_add_f32_e32 v27, v27, v31
	v_add_f32_e32 v28, v28, v32
	v_add_f32_e32 v29, v29, v33
	s_lshl_b32 s11, s12, 12
	v_add_u32_e32 v6, s11, v3
	v_add_f32_dpp v42, v26, v26 row_ror:8 row_mask:0xf bank_mask:0xf
	v_add_f32_dpp v43, v28, v28 row_ror:8 row_mask:0xf bank_mask:0xf
	v_add_f32_dpp v44, v27, v27 row_ror:8 row_mask:0xf bank_mask:0xf
	v_add_f32_dpp v45, v29, v29 row_ror:8 row_mask:0xf bank_mask:0xf
	v_cndmask_b32_e64 v46, v42, v43, s[14:15]
	v_cndmask_b32_e64 v47, v44, v45, s[14:15]
	v_add_f32_e32 v46, v52, v46
	v_add_f32_e32 v47, v53, v47
	global_store_dwordx2 v6, v[46:47], s[6:7]
	v_pk_mul_f32 v[42:43], v[46:47], v[56:57]
	s_lshl_b32 s11, s12, 11
	v_add_u32_e32 v8, s11, v9
	v_cvt_pk_bf16_f32 v42, v42, v43
	global_store_dword v8, v42, s[36:37]
	v_mul_f32_e32 v48, v46, v46
	v_fmac_f32_e32 v48, v47, v47
	s_lshl_b32 s11, s12, 2
	s_add_u32 s11, s11, 0x1100000
	v_mov_b32_e32 v7, s11
	v_add_f32_dpp v48, v48, v48 quad_perm:[1,0,3,2] row_mask:0xf bank_mask:0xf
	s_nop 1
	v_add_f32_dpp v48, v48, v48 quad_perm:[2,3,0,1] row_mask:0xf bank_mask:0xf
	s_nop 1
	v_add_f32_dpp v48, v48, v48 row_half_mirror row_mask:0xf bank_mask:0xf
	s_nop 1
	v_add_f32_dpp v48, v48, v48 row_mirror row_mask:0xf bank_mask:0xf
	s_nop 1
	v_add_f32_dpp v48, v48, v48 row_bcast:15 row_mask:0xa bank_mask:0xf
	s_nop 1
	v_add_f32_dpp v48, v48, v48 row_bcast:31 row_mask:0xc bank_mask:0xf
	s_nop 1
	s_mov_b32 exec_lo, 0
	s_brev_b32 exec_hi, 1
	global_atomic_add_f32 v7, v48, s[4:5]
	s_mov_b64 exec, -1
; #define P5_LOAD(A, TAB, j0)                                                                \
;   _Pragma("unroll") for (int q = 0; q < 16; q++) {                                         \
;     A[q] = ((const uint4*)((TAB) + (size_t)widx[(j0) + q] * 1024))[lane];                  \
;   }
; __device__ __forceinline__ void phase5(const Params& p, char* smem, const bool store_x = true) {
;     ...
; #pragma unroll 1
;     for (int j0 = 0; j0 < 128; j0 += 32) {
;       P5_LOAD(A1, EV, j0 + 16)
;       P5_COMPUTE_V(A0, j0)
;       if (j0 + 32 < 128) { P5_LOAD(A0, EV, j0 + 32) }
;       P5_COMPUTE_V(A1, j0 + 16)
;     }
.Lp5v_skip1:
	s_add_u32 s11, s16, 4
	s_and_b32 s11, s11, 7
	s_lshl_b32 s11, s11, 10
	v_add_u32_e32 v8, s11, v2
	ds_read_b128 v[10:13], v8 offset:0
	ds_read_b128 v[14:17], v8 offset:16
	ds_read_b128 v[18:21], v8 offset:32
	ds_read_b128 v[22:25], v8 offset:48
	s_add_u32 s10, s8, s27
	s_min_u32 s10, s10, s13
	s_lshl_b32 s18, s10, 10
	s_add_u32 s11, s16, 8
	s_and_b32 s11, s11, 7
	s_lshl_b32 s11, s11, 10
	s_add_u32 s11, s11, s17
	s_mov_b32 m0, s11
	v_lshl_add_u64 v[4:5], v[58:59], 0, s[18:19]
	global_load_lds_dwordx4 v[4:5], off
	s_add_u32 s10, s8, s23
	s_min_u32 s10, s10, s13
	s_lshl_b32 s11, s10, 12
	v_add_u32_e32 v6, s11, v3
	global_load_dwordx2 v[52:53], v6, s[6:7]
	s_waitcnt lgkmcnt(0)
	v_add_u32_e32 v10, v10, v1
	global_load_dwordx4 v[124:127], v10, s[2:3]
	v_add_u32_e32 v11, v11, v1
	global_load_dwordx4 v[128:131], v11, s[2:3]
	v_add_u32_e32 v12, v12, v1
	global_load_dwordx4 v[132:135], v12, s[2:3]
	v_add_u32_e32 v13, v13, v1
	global_load_dwordx4 v[136:139], v13, s[2:3]
	v_add_u32_e32 v14, v14, v1
	global_load_dwordx4 v[140:143], v14, s[2:3]
	v_add_u32_e32 v15, v15, v1
	global_load_dwordx4 v[144:147], v15, s[2:3]
	v_add_u32_e32 v16, v16, v1
	global_load_dwordx4 v[148:151], v16, s[2:3]
	v_add_u32_e32 v17, v17, v1
	global_load_dwordx4 v[152:155], v17, s[2:3]
	v_add_u32_e32 v18, v18, v1
	global_load_dwordx4 v[156:159], v18, s[2:3]
	v_add_u32_e32 v19, v19, v1
	global_load_dwordx4 v[160:163], v19, s[2:3]
	v_add_u32_e32 v20, v20, v1
	global_load_dwordx4 v[164:167], v20, s[2:3]
	v_add_u32_e32 v21, v21, v1
	global_load_dwordx4 v[168:171], v21, s[2:3]
	v_add_u32_e32 v22, v22, v1
	global_load_dwordx4 v[172:175], v22, s[2:3]
	v_add_u32_e32 v23, v23, v1
	global_load_dwordx4 v[176:179], v23, s[2:3]
	v_add_u32_e32 v24, v24, v1
	global_load_dwordx4 v[180:183], v24, s[2:3]
	v_add_u32_e32 v25, v25, v1
	global_load_dwordx4 v[184:187], v25, s[2:3]
	s_add_u32 s11, s16, 2
	s_and_b32 s11, s11, 7
	s_lshl_b32 s11, s11, 10
	v_add_u32_e32 v8, s11, v2
	ds_read_b128 v[10:13], v8 offset:512
	ds_read_b128 v[14:17], v8 offset:528
	ds_read_b128 v[18:21], v8 offset:544
	ds_read_b128 v[22:25], v8 offset:560
	s_add_u32 s12, s8, s21
	s_waitcnt vmcnt(42) lgkmcnt(0)
	s_cmp_lt_u32 s12, 0x4200
	s_cbranch_scc0 .Lp5v_skip2
	v_cvt_pk_f32_fp8_e32 v[42:43], v188
	v_cvt_pk_f32_fp8_sdwa v[44:45], v188 src0_sel:WORD_1
	v_pk_mul_f32 v[26:27], v[42:43], v[10:11] op_sel_hi:[1,0]
	v_pk_mul_f32 v[28:29], v[44:45], v[10:11] op_sel_hi:[1,0]
	v_cvt_pk_f32_fp8_e32 v[46:47], v189
	v_cvt_pk_f32_fp8_sdwa v[48:49], v189 src0_sel:WORD_1
	v_pk_mul_f32 v[30:31], v[46:47], v[10:11] op_sel_hi:[1,0]
	v_pk_mul_f32 v[32:33], v[48:49], v[10:11] op_sel_hi:[1,0]
	v_cvt_pk_f32_fp8_e32 v[42:43], v190
	v_cvt_pk_f32_fp8_sdwa v[44:45], v190 src0_sel:WORD_1
	v_pk_mul_f32 v[34:35], v[42:43], v[10:11] op_sel_hi:[1,0]
	v_pk_mul_f32 v[36:37], v[44:45], v[10:11] op_sel_hi:[1,0]
	v_cvt_pk_f32_fp8_e32 v[46:47], v191
	v_cvt_pk_f32_fp8_sdwa v[48:49], v191 src0_sel:WORD_1
	v_pk_mul_f32 v[38:39], v[46:47], v[10:11] op_sel_hi:[1,0]
	v_pk_mul_f32 v[40:41], v[48:49], v[10:11] op_sel_hi:[1,0]
	v_cvt_pk_f32_fp8_e32 v[42:43], v192
	v_cvt_pk_f32_fp8_sdwa v[44:45], v192 src0_sel:WORD_1
	v_pk_fma_f32 v[26:27], v[42:43], v[10:11], v[26:27] op_sel:[0,1,0] op_sel_hi:[1,1,1]
	v_pk_fma_f32 v[28:29], v[44:45], v[10:11], v[28:29] op_sel:[0,1,0] op_sel_hi:[1,1,1]
	v_cvt_pk_f32_fp8_e32 v[46:47], v193
	v_cvt_pk_f32_fp8_sdwa v[48:49], v193 src0_sel:WORD_1
	v_pk_fma_f32 v[30:31], v[46:47], v[10:11], v[30:31] op_sel:[0,1,0] op_sel_hi:[1,1,1]
	v_pk_fma_f32 v[32:33], v[48:49], v[10:11], v[32:33] op_sel:[0,1,0] op_sel_hi:[1,1,1]
	v_cvt_pk_f32_fp8_e32 v[42:43], v194
	v_cvt_pk_f32_fp8_sdwa v[44:45], v194 src0_sel:WORD_1
	v_pk_fma_f32 v[34:35], v[42:43], v[10:11], v[34:35] op_sel:[0,1,0] op_sel_hi:[1,1,1]
	v_pk_fma_f32 v[36:37], v[44:45], v[10:11], v[36:37] op_sel:[0,1,0] op_sel_hi:[1,1,1]
	v_cvt_pk_f32_fp8_e32 v[46:47], v195
	v_cvt_pk_f32_fp8_sdwa v[48:49], v195 src0_sel:WORD_1
	v_pk_fma_f32 v[38:39], v[46:47], v[10:11], v[38:39] op_sel:[0,1,0] op_sel_hi:[1,1,1]
	v_pk_fma_f32 v[40:41], v[48:49], v[10:11], v[40:41] op_sel:[0,1,0] op_sel_hi:[1,1,1]
	v_cvt_pk_f32_fp8_e32 v[42:43], v196
	v_cvt_pk_f32_fp8_sdwa v[44:45], v196 src0_sel:WORD_1
	v_pk_fma_f32 v[26:27], v[42:43], v[12:13], v[26:27] op_sel_hi:[1,0,1]
	v_pk_fma_f32 v[28:29], v[44:45], v[12:13], v[28:29] op_sel_hi:[1,0,1]
	v_cvt_pk_f32_fp8_e32 v[46:47], v197
	v_cvt_pk_f32_fp8_sdwa v[48:49], v197 src0_sel:WORD_1
	v_pk_fma_f32 v[30:31], v[46:47], v[12:13], v[30:31] op_sel_hi:[1,0,1]
	v_pk_fma_f32 v[32:33], v[48:49], v[12:13], v[32:33] op_sel_hi:[1,0,1]
	v_cvt_pk_f32_fp8_e32 v[42:43], v198
	v_cvt_pk_f32_fp8_sdwa v[44:45], v198 src0_sel:WORD_1
	v_pk_fma_f32 v[34:35], v[42:43], v[12:13], v[34:35] op_sel_hi:[1,0,1]
	v_pk_fma_f32 v[36:37], v[44:45], v[12:13], v[36:37] op_sel_hi:[1,0,1]
	v_cvt_pk_f32_fp8_e32 v[46:47], v199
	v_cvt_pk_f32_fp8_sdwa v[48:49], v199 src0_sel:WORD_1
	v_pk_fma_f32 v[38:39], v[46:47], v[12:13], v[38:39] op_sel_hi:[1,0,1]
	v_pk_fma_f32 v[40:41], v[48:49], v[12:13], v[40:41] op_sel_hi:[1,0,1]
	v_cvt_pk_f32_fp8_e32 v[42:43], v200
	v_cvt_pk_f32_fp8_sdwa v[44:45], v200 src0_sel:WORD_1
	v_pk_fma_f32 v[26:27], v[42:43], v[12:13], v[26:27] op_sel:[0,1,0] op_sel_hi:[1,1,1]
	v_pk_fma_f32 v[28:29], v[44:45], v[12:13], v[28:29] op_sel:[0,1,0] op_sel_hi:[1,1,1]
	v_cvt_pk_f32_fp8_e32 v[46:47], v201
	v_cvt_pk_f32_fp8_sdwa v[48:49], v201 src0_sel:WORD_1
	v_pk_fma_f32 v[30:31], v[46:47], v[12:13], v[30:31] op_sel:[0,1,0] op_sel_hi:[1,1,1]
	v_pk_fma_f32 v[32:33], v[48:49], v[12:13], v[32:33] op_sel:[0,1,0] op_sel_hi:[1,1,1]
	v_cvt_pk_f32_fp8_e32 v[42:43], v202
	v_cvt_pk_f32_fp8_sdwa v[44:45], v202 src0_sel:WORD_1
; #define P5_LOAD(A, TAB, j0)                                                                \
;   _Pragma("unroll") for (int q = 0; q < 16; q++) {                                         \
;     A[q] = ((const uint4*)((TAB) + (size_t)widx[(j0) + q] * 1024))[lane];                  \
;   }
; __device__ __forceinline__ void phase5(const Params& p, char* smem, const bool store_x = true) {
;     ...
; #pragma unroll 1
;     for (int j0 = 0; j0 < 128; j0 += 32) {
;       P5_LOAD(A1, EV, j0 + 16)
;       P5_COMPUTE_V(A0, j0)
;       if (j0 + 32 < 128) { P5_LOAD(A0, EV, j0 + 32) }
;       P5_COMPUTE_V(A1, j0 + 16)
;     }
	v_pk_fma_f32 v[34:35], v[42:43], v[12:13], v[34:35] op_sel:[0,1,0] op_sel_hi:[1,1,1]
	v_pk_fma_f32 v[36:37], v[44:45], v[12:13], v[36:37] op_sel:[0,1,0] op_sel_hi:[1,1,1]
	v_cvt_pk_f32_fp8_e32 v[46:47], v203
	v_cvt_pk_f32_fp8_sdwa v[48:49], v203 src0_sel:WORD_1
	v_pk_fma_f32 v[38:39], v[46:47], v[12:13], v[38:39] op_sel:[0,1,0] op_sel_hi:[1,1,1]
	v_pk_fma_f32 v[40:41], v[48:49], v[12:13], v[40:41] op_sel:[0,1,0] op_sel_hi:[1,1,1]
	v_cvt_pk_f32_fp8_e32 v[42:43], v204
	v_cvt_pk_f32_fp8_sdwa v[44:45], v204 src0_sel:WORD_1
	v_pk_fma_f32 v[26:27], v[42:43], v[14:15], v[26:27] op_sel_hi:[1,0,1]
	v_pk_fma_f32 v[28:29], v[44:45], v[14:15], v[28:29] op_sel_hi:[1,0,1]
	v_cvt_pk_f32_fp8_e32 v[46:47], v205
	v_cvt_pk_f32_fp8_sdwa v[48:49], v205 src0_sel:WORD_1
	v_pk_fma_f32 v[30:31], v[46:47], v[14:15], v[30:31] op_sel_hi:[1,0,1]
	v_pk_fma_f32 v[32:33], v[48:49], v[14:15], v[32:33] op_sel_hi:[1,0,1]
	v_cvt_pk_f32_fp8_e32 v[42:43], v206
	v_cvt_pk_f32_fp8_sdwa v[44:45], v206 src0_sel:WORD_1
	v_pk_fma_f32 v[34:35], v[42:43], v[14:15], v[34:35] op_sel_hi:[1,0,1]
	v_pk_fma_f32 v[36:37], v[44:45], v[14:15], v[36:37] op_sel_hi:[1,0,1]
	v_cvt_pk_f32_fp8_e32 v[46:47], v207
	v_cvt_pk_f32_fp8_sdwa v[48:49], v207 src0_sel:WORD_1
	v_pk_fma_f32 v[38:39], v[46:47], v[14:15], v[38:39] op_sel_hi:[1,0,1]
	v_pk_fma_f32 v[40:41], v[48:49], v[14:15], v[40:41] op_sel_hi:[1,0,1]
	v_cvt_pk_f32_fp8_e32 v[42:43], v208
	v_cvt_pk_f32_fp8_sdwa v[44:45], v208 src0_sel:WORD_1
	v_pk_fma_f32 v[26:27], v[42:43], v[14:15], v[26:27] op_sel:[0,1,0] op_sel_hi:[1,1,1]
	v_pk_fma_f32 v[28:29], v[44:45], v[14:15], v[28:29] op_sel:[0,1,0] op_sel_hi:[1,1,1]
	v_cvt_pk_f32_fp8_e32 v[46:47], v209
	v_cvt_pk_f32_fp8_sdwa v[48:49], v209 src0_sel:WORD_1
	v_pk_fma_f32 v[30:31], v[46:47], v[14:15], v[30:31] op_sel:[0,1,0] op_sel_hi:[1,1,1]
	v_pk_fma_f32 v[32:33], v[48:49], v[14:15], v[32:33] op_sel:[0,1,0] op_sel_hi:[1,1,1]
	v_cvt_pk_f32_fp8_e32 v[42:43], v210
	v_cvt_pk_f32_fp8_sdwa v[44:45], v210 src0_sel:WORD_1
	v_pk_fma_f32 v[34:35], v[42:43], v[14:15], v[34:35] op_sel:[0,1,0] op_sel_hi:[1,1,1]
	v_pk_fma_f32 v[36:37], v[44:45], v[14:15], v[36:37] op_sel:[0,1,0] op_sel_hi:[1,1,1]
	v_cvt_pk_f32_fp8_e32 v[46:47], v211
	v_cvt_pk_f32_fp8_sdwa v[48:49], v211 src0_sel:WORD_1
	v_pk_fma_f32 v[38:39], v[46:47], v[14:15], v[38:39] op_sel:[0,1,0] op_sel_hi:[1,1,1]
	v_pk_fma_f32 v[40:41], v[48:49], v[14:15], v[40:41] op_sel:[0,1,0] op_sel_hi:[1,1,1]
	v_cvt_pk_f32_fp8_e32 v[42:43], v212
	v_cvt_pk_f32_fp8_sdwa v[44:45], v212 src0_sel:WORD_1
	v_pk_fma_f32 v[26:27], v[42:43], v[16:17], v[26:27] op_sel_hi:[1,0,1]
	v_pk_fma_f32 v[28:29], v[44:45], v[16:17], v[28:29] op_sel_hi:[1,0,1]
	v_cvt_pk_f32_fp8_e32 v[46:47], v213
	v_cvt_pk_f32_fp8_sdwa v[48:49], v213 src0_sel:WORD_1
	v_pk_fma_f32 v[30:31], v[46:47], v[16:17], v[30:31] op_sel_hi:[1,0,1]
	v_pk_fma_f32 v[32:33], v[48:49], v[16:17], v[32:33] op_sel_hi:[1,0,1]
	v_cvt_pk_f32_fp8_e32 v[42:43], v214
	v_cvt_pk_f32_fp8_sdwa v[44:45], v214 src0_sel:WORD_1
	v_pk_fma_f32 v[34:35], v[42:43], v[16:17], v[34:35] op_sel_hi:[1,0,1]
	v_pk_fma_f32 v[36:37], v[44:45], v[16:17], v[36:37] op_sel_hi:[1,0,1]
	v_cvt_pk_f32_fp8_e32 v[46:47], v215
	v_cvt_pk_f32_fp8_sdwa v[48:49], v215 src0_sel:WORD_1
	v_pk_fma_f32 v[38:39], v[46:47], v[16:17], v[38:39] op_sel_hi:[1,0,1]
	v_pk_fma_f32 v[40:41], v[48:49], v[16:17], v[40:41] op_sel_hi:[1,0,1]
	v_cvt_pk_f32_fp8_e32 v[42:43], v216
	v_cvt_pk_f32_fp8_sdwa v[44:45], v216 src0_sel:WORD_1
	v_pk_fma_f32 v[26:27], v[42:43], v[16:17], v[26:27] op_sel:[0,1,0] op_sel_hi:[1,1,1]
	v_pk_fma_f32 v[28:29], v[44:45], v[16:17], v[28:29] op_sel:[0,1,0] op_sel_hi:[1,1,1]
	v_cvt_pk_f32_fp8_e32 v[46:47], v217
	v_cvt_pk_f32_fp8_sdwa v[48:49], v217 src0_sel:WORD_1
	v_pk_fma_f32 v[30:31], v[46:47], v[16:17], v[30:31] op_sel:[0,1,0] op_sel_hi:[1,1,1]
	v_pk_fma_f32 v[32:33], v[48:49], v[16:17], v[32:33] op_sel:[0,1,0] op_sel_hi:[1,1,1]
	v_cvt_pk_f32_fp8_e32 v[42:43], v218
	v_cvt_pk_f32_fp8_sdwa v[44:45], v218 src0_sel:WORD_1
	v_pk_fma_f32 v[34:35], v[42:43], v[16:17], v[34:35] op_sel:[0,1,0] op_sel_hi:[1,1,1]
	v_pk_fma_f32 v[36:37], v[44:45], v[16:17], v[36:37] op_sel:[0,1,0] op_sel_hi:[1,1,1]
	v_cvt_pk_f32_fp8_e32 v[46:47], v219
	v_cvt_pk_f32_fp8_sdwa v[48:49], v219 src0_sel:WORD_1
	v_pk_fma_f32 v[38:39], v[46:47], v[16:17], v[38:39] op_sel:[0,1,0] op_sel_hi:[1,1,1]
	v_pk_fma_f32 v[40:41], v[48:49], v[16:17], v[40:41] op_sel:[0,1,0] op_sel_hi:[1,1,1]
	v_cvt_pk_f32_fp8_e32 v[42:43], v220
	v_cvt_pk_f32_fp8_sdwa v[44:45], v220 src0_sel:WORD_1
	v_pk_fma_f32 v[26:27], v[42:43], v[18:19], v[26:27] op_sel_hi:[1,0,1]
	v_pk_fma_f32 v[28:29], v[44:45], v[18:19], v[28:29] op_sel_hi:[1,0,1]
	v_cvt_pk_f32_fp8_e32 v[46:47], v221
	v_cvt_pk_f32_fp8_sdwa v[48:49], v221 src0_sel:WORD_1
	v_pk_fma_f32 v[30:31], v[46:47], v[18:19], v[30:31] op_sel_hi:[1,0,1]
	v_pk_fma_f32 v[32:33], v[48:49], v[18:19], v[32:33] op_sel_hi:[1,0,1]
	v_cvt_pk_f32_fp8_e32 v[42:43], v222
	v_cvt_pk_f32_fp8_sdwa v[44:45], v222 src0_sel:WORD_1
	v_pk_fma_f32 v[34:35], v[42:43], v[18:19], v[34:35] op_sel_hi:[1,0,1]
	v_pk_fma_f32 v[36:37], v[44:45], v[18:19], v[36:37] op_sel_hi:[1,0,1]
	v_cvt_pk_f32_fp8_e32 v[46:47], v223
	v_cvt_pk_f32_fp8_sdwa v[48:49], v223 src0_sel:WORD_1
	v_pk_fma_f32 v[38:39], v[46:47], v[18:19], v[38:39] op_sel_hi:[1,0,1]
	v_pk_fma_f32 v[40:41], v[48:49], v[18:19], v[40:41] op_sel_hi:[1,0,1]
	v_cvt_pk_f32_fp8_e32 v[42:43], v224
	v_cvt_pk_f32_fp8_sdwa v[44:45], v224 src0_sel:WORD_1
	v_pk_fma_f32 v[26:27], v[42:43], v[18:19], v[26:27] op_sel:[0,1,0] op_sel_hi:[1,1,1]
	v_pk_fma_f32 v[28:29], v[44:45], v[18:19], v[28:29] op_sel:[0,1,0] op_sel_hi:[1,1,1]
	v_cvt_pk_f32_fp8_e32 v[46:47], v225
; #define P5_LOAD(A, TAB, j0)                                                                \
;   _Pragma("unroll") for (int q = 0; q < 16; q++) {                                         \
;     A[q] = ((const uint4*)((TAB) + (size_t)widx[(j0) + q] * 1024))[lane];                  \
;   }
; __device__ __forceinline__ void phase5(const Params& p, char* smem, const bool store_x = true) {
;     ...
; #pragma unroll 1
;     for (int j0 = 0; j0 < 128; j0 += 32) {
;       P5_LOAD(A1, EV, j0 + 16)
;       P5_COMPUTE_V(A0, j0)
;       if (j0 + 32 < 128) { P5_LOAD(A0, EV, j0 + 32) }
;       P5_COMPUTE_V(A1, j0 + 16)
;     }
	v_cvt_pk_f32_fp8_sdwa v[48:49], v225 src0_sel:WORD_1
	v_pk_fma_f32 v[30:31], v[46:47], v[18:19], v[30:31] op_sel:[0,1,0] op_sel_hi:[1,1,1]
	v_pk_fma_f32 v[32:33], v[48:49], v[18:19], v[32:33] op_sel:[0,1,0] op_sel_hi:[1,1,1]
	v_cvt_pk_f32_fp8_e32 v[42:43], v226
	v_cvt_pk_f32_fp8_sdwa v[44:45], v226 src0_sel:WORD_1
	v_pk_fma_f32 v[34:35], v[42:43], v[18:19], v[34:35] op_sel:[0,1,0] op_sel_hi:[1,1,1]
	v_pk_fma_f32 v[36:37], v[44:45], v[18:19], v[36:37] op_sel:[0,1,0] op_sel_hi:[1,1,1]
	v_cvt_pk_f32_fp8_e32 v[46:47], v227
	v_cvt_pk_f32_fp8_sdwa v[48:49], v227 src0_sel:WORD_1
	v_pk_fma_f32 v[38:39], v[46:47], v[18:19], v[38:39] op_sel:[0,1,0] op_sel_hi:[1,1,1]
	v_pk_fma_f32 v[40:41], v[48:49], v[18:19], v[40:41] op_sel:[0,1,0] op_sel_hi:[1,1,1]
	v_cvt_pk_f32_fp8_e32 v[42:43], v228
	v_cvt_pk_f32_fp8_sdwa v[44:45], v228 src0_sel:WORD_1
	v_pk_fma_f32 v[26:27], v[42:43], v[20:21], v[26:27] op_sel_hi:[1,0,1]
	v_pk_fma_f32 v[28:29], v[44:45], v[20:21], v[28:29] op_sel_hi:[1,0,1]
	v_cvt_pk_f32_fp8_e32 v[46:47], v229
	v_cvt_pk_f32_fp8_sdwa v[48:49], v229 src0_sel:WORD_1
	v_pk_fma_f32 v[30:31], v[46:47], v[20:21], v[30:31] op_sel_hi:[1,0,1]
	v_pk_fma_f32 v[32:33], v[48:49], v[20:21], v[32:33] op_sel_hi:[1,0,1]
	v_cvt_pk_f32_fp8_e32 v[42:43], v230
	v_cvt_pk_f32_fp8_sdwa v[44:45], v230 src0_sel:WORD_1
	v_pk_fma_f32 v[34:35], v[42:43], v[20:21], v[34:35] op_sel_hi:[1,0,1]
	v_pk_fma_f32 v[36:37], v[44:45], v[20:21], v[36:37] op_sel_hi:[1,0,1]
	v_cvt_pk_f32_fp8_e32 v[46:47], v231
	v_cvt_pk_f32_fp8_sdwa v[48:49], v231 src0_sel:WORD_1
	v_pk_fma_f32 v[38:39], v[46:47], v[20:21], v[38:39] op_sel_hi:[1,0,1]
	v_pk_fma_f32 v[40:41], v[48:49], v[20:21], v[40:41] op_sel_hi:[1,0,1]
	v_cvt_pk_f32_fp8_e32 v[42:43], v232
	v_cvt_pk_f32_fp8_sdwa v[44:45], v232 src0_sel:WORD_1
	v_pk_fma_f32 v[26:27], v[42:43], v[20:21], v[26:27] op_sel:[0,1,0] op_sel_hi:[1,1,1]
	v_pk_fma_f32 v[28:29], v[44:45], v[20:21], v[28:29] op_sel:[0,1,0] op_sel_hi:[1,1,1]
	v_cvt_pk_f32_fp8_e32 v[46:47], v233
	v_cvt_pk_f32_fp8_sdwa v[48:49], v233 src0_sel:WORD_1
	v_pk_fma_f32 v[30:31], v[46:47], v[20:21], v[30:31] op_sel:[0,1,0] op_sel_hi:[1,1,1]
	v_pk_fma_f32 v[32:33], v[48:49], v[20:21], v[32:33] op_sel:[0,1,0] op_sel_hi:[1,1,1]
	v_cvt_pk_f32_fp8_e32 v[42:43], v234
	v_cvt_pk_f32_fp8_sdwa v[44:45], v234 src0_sel:WORD_1
	v_pk_fma_f32 v[34:35], v[42:43], v[20:21], v[34:35] op_sel:[0,1,0] op_sel_hi:[1,1,1]
	v_pk_fma_f32 v[36:37], v[44:45], v[20:21], v[36:37] op_sel:[0,1,0] op_sel_hi:[1,1,1]
	v_cvt_pk_f32_fp8_e32 v[46:47], v235
	v_cvt_pk_f32_fp8_sdwa v[48:49], v235 src0_sel:WORD_1
	v_pk_fma_f32 v[38:39], v[46:47], v[20:21], v[38:39] op_sel:[0,1,0] op_sel_hi:[1,1,1]
	v_pk_fma_f32 v[40:41], v[48:49], v[20:21], v[40:41] op_sel:[0,1,0] op_sel_hi:[1,1,1]
	v_cvt_pk_f32_fp8_e32 v[42:43], v236
	v_cvt_pk_f32_fp8_sdwa v[44:45], v236 src0_sel:WORD_1
	v_pk_fma_f32 v[26:27], v[42:43], v[22:23], v[26:27] op_sel_hi:[1,0,1]
	v_pk_fma_f32 v[28:29], v[44:45], v[22:23], v[28:29] op_sel_hi:[1,0,1]
	v_cvt_pk_f32_fp8_e32 v[46:47], v237
	v_cvt_pk_f32_fp8_sdwa v[48:49], v237 src0_sel:WORD_1
	v_pk_fma_f32 v[30:31], v[46:47], v[22:23], v[30:31] op_sel_hi:[1,0,1]
	v_pk_fma_f32 v[32:33], v[48:49], v[22:23], v[32:33] op_sel_hi:[1,0,1]
	v_cvt_pk_f32_fp8_e32 v[42:43], v238
	v_cvt_pk_f32_fp8_sdwa v[44:45], v238 src0_sel:WORD_1
	v_pk_fma_f32 v[34:35], v[42:43], v[22:23], v[34:35] op_sel_hi:[1,0,1]
	v_pk_fma_f32 v[36:37], v[44:45], v[22:23], v[36:37] op_sel_hi:[1,0,1]
	v_cvt_pk_f32_fp8_e32 v[46:47], v239
	v_cvt_pk_f32_fp8_sdwa v[48:49], v239 src0_sel:WORD_1
	v_pk_fma_f32 v[38:39], v[46:47], v[22:23], v[38:39] op_sel_hi:[1,0,1]
	v_pk_fma_f32 v[40:41], v[48:49], v[22:23], v[40:41] op_sel_hi:[1,0,1]
	v_cvt_pk_f32_fp8_e32 v[42:43], v240
	v_cvt_pk_f32_fp8_sdwa v[44:45], v240 src0_sel:WORD_1
	v_pk_fma_f32 v[26:27], v[42:43], v[22:23], v[26:27] op_sel:[0,1,0] op_sel_hi:[1,1,1]
	v_pk_fma_f32 v[28:29], v[44:45], v[22:23], v[28:29] op_sel:[0,1,0] op_sel_hi:[1,1,1]
	v_cvt_pk_f32_fp8_e32 v[46:47], v241
	v_cvt_pk_f32_fp8_sdwa v[48:49], v241 src0_sel:WORD_1
	v_pk_fma_f32 v[30:31], v[46:47], v[22:23], v[30:31] op_sel:[0,1,0] op_sel_hi:[1,1,1]
	v_pk_fma_f32 v[32:33], v[48:49], v[22:23], v[32:33] op_sel:[0,1,0] op_sel_hi:[1,1,1]
	v_cvt_pk_f32_fp8_e32 v[42:43], v242
	v_cvt_pk_f32_fp8_sdwa v[44:45], v242 src0_sel:WORD_1
	v_pk_fma_f32 v[34:35], v[42:43], v[22:23], v[34:35] op_sel:[0,1,0] op_sel_hi:[1,1,1]
	v_pk_fma_f32 v[36:37], v[44:45], v[22:23], v[36:37] op_sel:[0,1,0] op_sel_hi:[1,1,1]
; __device__ __forceinline__ float wsum(float v) { v = dpp_row_sum16(v); v += __shfl_xor(v, 16); v += __shfl_xor(v, 32); return v; }
; __device__ __forceinline__ void phase5(const Params& p, char* smem, const bool store_x = true) {
;     ...
;     float x2[16];
; #pragma unroll
;     for (int i = 0; i < 4; i++) {
;       const float4 xv = i == 0 ? xv0 : i == 1 ? xv1 : i == 2 ? xv2 : xv3;
;       x2[4 * i] = xv.x + o2[2 * i].x; x2[4 * i + 1] = xv.y + o2[2 * i].y; x2[4 * i + 2] = xv.z + o2[2 * i + 1].x; x2[4 * i + 3] = xv.w + o2[2 * i + 1].y;
;     }
;     float ss = 0.f;
; #pragma unroll
;     for (int i = 0; i < 16; i++) ss += x2[i] * x2[i];
;     ss = wsum(ss);
;     const float rs = rsqrtf(ss * (1.f / 1024.f) + EPSF);
;     if (store_x) {
; #pragma unroll
;       for (int i = 0; i < 4; i++) *(float4*)(xr + i * 4) = make_float4(x2[4 * i], x2[4 * i + 1], x2[4 * i + 2], x2[4 * i + 3]);
;     }
;     unsigned hp[8];
; #pragma unroll
;     for (int i = 0; i < 4; i++) {
;       const float4 g = *(const float4*)(p.g_ple + lane * 16 + i * 4);
;       hp[2 * i] = pack2(x2[4 * i] * rs * g.x, x2[4 * i + 1] * rs * g.y);
;       hp[2 * i + 1] = pack2(x2[4 * i + 2] * rs * g.z, x2[4 * i + 3] * rs * g.w);
;     }
;     *(uint4*)(H3 + (size_t)tok * 1024 + lane * 16) = make_uint4(hp[0], hp[1], hp[2], hp[3]);
;     *(uint4*)(H3 + (size_t)tok * 1024 + lane * 16 + 8) = make_uint4(hp[4], hp[5], hp[6], hp[7]);
	v_cvt_pk_f32_fp8_e32 v[46:47], v243
	v_cvt_pk_f32_fp8_sdwa v[48:49], v243 src0_sel:WORD_1
	v_pk_fma_f32 v[38:39], v[46:47], v[22:23], v[38:39] op_sel:[0,1,0] op_sel_hi:[1,1,1]
	v_pk_fma_f32 v[40:41], v[48:49], v[22:23], v[40:41] op_sel:[0,1,0] op_sel_hi:[1,1,1]
	v_cvt_pk_f32_fp8_e32 v[42:43], v244
	v_cvt_pk_f32_fp8_sdwa v[44:45], v244 src0_sel:WORD_1
	v_pk_fma_f32 v[26:27], v[42:43], v[24:25], v[26:27] op_sel_hi:[1,0,1]
	v_pk_fma_f32 v[28:29], v[44:45], v[24:25], v[28:29] op_sel_hi:[1,0,1]
	v_cvt_pk_f32_fp8_e32 v[46:47], v245
	v_cvt_pk_f32_fp8_sdwa v[48:49], v245 src0_sel:WORD_1
	v_pk_fma_f32 v[30:31], v[46:47], v[24:25], v[30:31] op_sel_hi:[1,0,1]
	v_pk_fma_f32 v[32:33], v[48:49], v[24:25], v[32:33] op_sel_hi:[1,0,1]
	v_cvt_pk_f32_fp8_e32 v[42:43], v246
	v_cvt_pk_f32_fp8_sdwa v[44:45], v246 src0_sel:WORD_1
	v_pk_fma_f32 v[34:35], v[42:43], v[24:25], v[34:35] op_sel_hi:[1,0,1]
	v_pk_fma_f32 v[36:37], v[44:45], v[24:25], v[36:37] op_sel_hi:[1,0,1]
	v_cvt_pk_f32_fp8_e32 v[46:47], v247
	v_cvt_pk_f32_fp8_sdwa v[48:49], v247 src0_sel:WORD_1
	v_pk_fma_f32 v[38:39], v[46:47], v[24:25], v[38:39] op_sel_hi:[1,0,1]
	v_pk_fma_f32 v[40:41], v[48:49], v[24:25], v[40:41] op_sel_hi:[1,0,1]
	v_cvt_pk_f32_fp8_e32 v[42:43], v248
	v_cvt_pk_f32_fp8_sdwa v[44:45], v248 src0_sel:WORD_1
	v_pk_fma_f32 v[26:27], v[42:43], v[24:25], v[26:27] op_sel:[0,1,0] op_sel_hi:[1,1,1]
	v_pk_fma_f32 v[28:29], v[44:45], v[24:25], v[28:29] op_sel:[0,1,0] op_sel_hi:[1,1,1]
	v_cvt_pk_f32_fp8_e32 v[46:47], v249
	v_cvt_pk_f32_fp8_sdwa v[48:49], v249 src0_sel:WORD_1
	v_pk_fma_f32 v[30:31], v[46:47], v[24:25], v[30:31] op_sel:[0,1,0] op_sel_hi:[1,1,1]
	v_pk_fma_f32 v[32:33], v[48:49], v[24:25], v[32:33] op_sel:[0,1,0] op_sel_hi:[1,1,1]
	v_cvt_pk_f32_fp8_e32 v[42:43], v250
	v_cvt_pk_f32_fp8_sdwa v[44:45], v250 src0_sel:WORD_1
	v_pk_fma_f32 v[34:35], v[42:43], v[24:25], v[34:35] op_sel:[0,1,0] op_sel_hi:[1,1,1]
	v_pk_fma_f32 v[36:37], v[44:45], v[24:25], v[36:37] op_sel:[0,1,0] op_sel_hi:[1,1,1]
	v_cvt_pk_f32_fp8_e32 v[46:47], v251
	v_cvt_pk_f32_fp8_sdwa v[48:49], v251 src0_sel:WORD_1
	v_pk_fma_f32 v[38:39], v[46:47], v[24:25], v[38:39] op_sel:[0,1,0] op_sel_hi:[1,1,1]
	v_pk_fma_f32 v[40:41], v[48:49], v[24:25], v[40:41] op_sel:[0,1,0] op_sel_hi:[1,1,1]
	s_nop 1
	v_permlane32_swap_b32_e32 v26, v34
	v_permlane32_swap_b32_e32 v27, v35
	v_permlane32_swap_b32_e32 v28, v36
	v_permlane32_swap_b32_e32 v29, v37
	v_permlane32_swap_b32_e32 v30, v38
	v_permlane32_swap_b32_e32 v31, v39
	v_permlane32_swap_b32_e32 v32, v40
	v_permlane32_swap_b32_e32 v33, v41
	v_add_f32_e32 v26, v26, v34
	v_add_f32_e32 v27, v27, v35
	v_add_f32_e32 v28, v28, v36
	v_add_f32_e32 v29, v29, v37
	v_add_f32_e32 v30, v30, v38
	v_add_f32_e32 v31, v31, v39
	v_add_f32_e32 v32, v32, v40
	v_add_f32_e32 v33, v33, v41
	s_nop 1
	v_permlane16_swap_b32_e32 v26, v30
	v_permlane16_swap_b32_e32 v27, v31
	v_permlane16_swap_b32_e32 v28, v32
	v_permlane16_swap_b32_e32 v29, v33
	v_add_f32_e32 v26, v26, v30
	v_add_f32_e32 v27, v27, v31
	v_add_f32_e32 v28, v28, v32
	v_add_f32_e32 v29, v29, v33
	s_lshl_b32 s11, s12, 12
	v_add_u32_e32 v6, s11, v3
	v_add_f32_dpp v42, v26, v26 row_ror:8 row_mask:0xf bank_mask:0xf
	v_add_f32_dpp v43, v28, v28 row_ror:8 row_mask:0xf bank_mask:0xf
	v_add_f32_dpp v44, v27, v27 row_ror:8 row_mask:0xf bank_mask:0xf
	v_add_f32_dpp v45, v29, v29 row_ror:8 row_mask:0xf bank_mask:0xf
	v_cndmask_b32_e64 v46, v42, v43, s[14:15]
	v_cndmask_b32_e64 v47, v44, v45, s[14:15]
	v_add_f32_e32 v46, v54, v46
	v_add_f32_e32 v47, v55, v47
	global_store_dwordx2 v6, v[46:47], s[6:7]
	v_pk_mul_f32 v[42:43], v[46:47], v[56:57]
	s_lshl_b32 s11, s12, 11
	v_add_u32_e32 v8, s11, v9
	v_cvt_pk_bf16_f32 v42, v42, v43
	global_store_dword v8, v42, s[36:37]
	v_mul_f32_e32 v48, v46, v46
	v_fmac_f32_e32 v48, v47, v47
	s_lshl_b32 s11, s12, 2
	s_add_u32 s11, s11, 0x1100000
	v_mov_b32_e32 v7, s11
	v_add_f32_dpp v48, v48, v48 quad_perm:[1,0,3,2] row_mask:0xf bank_mask:0xf
	s_nop 1
	v_add_f32_dpp v48, v48, v48 quad_perm:[2,3,0,1] row_mask:0xf bank_mask:0xf
	s_nop 1
	v_add_f32_dpp v48, v48, v48 row_half_mirror row_mask:0xf bank_mask:0xf
	s_nop 1
	v_add_f32_dpp v48, v48, v48 row_mirror row_mask:0xf bank_mask:0xf
	s_nop 1
	v_add_f32_dpp v48, v48, v48 row_bcast:15 row_mask:0xa bank_mask:0xf
	s_nop 1
	v_add_f32_dpp v48, v48, v48 row_bcast:31 row_mask:0xc bank_mask:0xf
	s_nop 1
	s_mov_b32 exec_lo, 0
	s_brev_b32 exec_hi, 1
	global_atomic_add_f32 v7, v48, s[4:5]
	s_mov_b64 exec, -1
